# GEMM K-loops: removed the back-to-back s_setprio 0/1 pair in the middle of each 32-MFMA block (two issue slots per block)
# speedup vs baseline: 1.0116x; 1.0043x over previous
; #define PG8_STAGE(bufoff, gbase, voff) do { _Pragma("unroll") for (int _i = 0; _i < 2; ++_i) \
;         __builtin_amdgcn_global_load_lds((const unsigned*)((const char*)(gbase) + (voff)[_i]), (LAS unsigned*)(lds + (bufoff) + ldsw + _i * 8192), 16, 0, 0); } while (0)
; #define PG8_LDA(dst, b, h) do { _Pragma("unroll") for (int m = 0; m < 4; ++m) _Pragma("unroll") for (int k = 0; k < 2; ++k) dst[m][k] = *(const LAS bf16x8*)(lds + PG8_SA(b, h) + aoff + m * 2048 + k * 1024); } while (0)
; #define PG8_LDB(dst, b, h) do { _Pragma("unroll") for (int n = 0; n < 2; ++n) _Pragma("unroll") for (int k = 0; k < 2; ++k) dst[n][k] = *(const LAS bf16x8*)(lds + PG8_SB(b, h) + boff + n * 2048 + k * 1024); } while (0)
; #define PG8_MMA(ai, bj, At, Bt) do { __builtin_amdgcn_s_setprio(1); _Pragma("unroll") for (int m = 0; m < 4; ++m) _Pragma("unroll") for (int n = 0; n < 2; ++n) _Pragma("unroll") for (int k = 0; k < 2; ++k) \
;         acc[ai][bj][m][n] = __builtin_amdgcn_mfma_f32_16x16x32_bf16(Bt[n][k], At[m][k], acc[ai][bj][m][n], 0, 0, 0); __builtin_amdgcn_s_setprio(0); } while (0)
; #define PG8_WAIT_V(n) asm volatile("s_waitcnt vmcnt(" #n ")" ::: "memory")
; #define PG8_WAIT_L(n) asm volatile("s_waitcnt lgkmcnt(" #n ")" ::: "memory")
; #define PG8_BAR __builtin_amdgcn_s_barrier()
; #define PG8_SCHED __builtin_amdgcn_sched_barrier(0)
; template <class Epi, bool ALIGN_EPI = true, bool SP2 = true>
; __device__ __forceinline__ void gemm_phase(LAS unsigned char* lds, const Gemm g, const StaticOrder& S, const Epi& E, const int wave_s) {
;     ...
;             PG8_LDB(B0, 0, 0); PG8_LDB(B1, 0, 1); PG8_SCHED; PG8_LDA(At, 0, 0); PG8_STAGE(PG8_SA(1, 1), a1 + hstep, voffA);
;             PG8_WAIT_V(8); PG8_WAIT_L(0); PG8_BAR; PG8_MMA(0, 0, At, B0); PG8_MMA(0, 1, At, B1); PG8_BAR; PG8_SCHED;
;             PG8_LDA(At, 0, 1); PG8_STAGE(PG8_SB(0, 0), b2, voffB); PG8_STAGE(PG8_SB(0, 1), b2 + hstep, voffB); PG8_STAGE(PG8_SA(0, 0), a2, voffA);
;             PG8_WAIT_V(8); PG8_WAIT_L(0); PG8_BAR; PG8_MMA(1, 0, At, B0); PG8_MMA(1, 1, At, B1); PG8_BAR; PG8_SCHED;
.LBB0_116:
	ds_read_b128 v[144:147], v151
	ds_read_b128 v[154:157], v151 offset:1024
	ds_read_b128 v[158:161], v151 offset:2048
	ds_read_b128 v[162:165], v151 offset:3072
	ds_read_b128 v[166:169], v152
	ds_read_b128 v[170:173], v152 offset:1024
	ds_read_b128 v[174:177], v152 offset:2048
	ds_read_b128 v[178:181], v152 offset:3072
	s_add_u32 s30, s28, 0xfffc0080
	s_addc_u32 s31, s29, -1
	s_cmp_eq_u32 s52, 12
	s_cselect_b32 s35, s21, s31
	s_cselect_b32 s34, s48, s30
	s_cselect_b32 s31, s19, s51
	s_cselect_b32 s30, s49, s50
	v_lshl_add_u64 v[214:215], s[28:29], 0, v[138:139]
	s_add_i32 m0, s27, 0xc000
	ds_read_b128 v[182:185], v153
	ds_read_b128 v[186:189], v153 offset:1024
	ds_read_b128 v[190:193], v153 offset:2048
	ds_read_b128 v[194:197], v153 offset:3072
	ds_read_b128 v[198:201], v153 offset:4096
	ds_read_b128 v[202:205], v153 offset:5120
	ds_read_b128 v[206:209], v153 offset:6144
	ds_read_b128 v[210:213], v153 offset:7168
	global_load_lds_dwordx4 v[214:215], off
	v_lshl_add_u64 v[214:215], s[28:29], 0, v[136:137]
	s_add_i32 m0, s27, 0xe000
	s_nop 0
	global_load_lds_dwordx4 v[214:215], off
	s_waitcnt vmcnt(8)
	s_waitcnt lgkmcnt(0)
	s_barrier
	s_setprio 1
	s_waitcnt lgkmcnt(0)
	v_mfma_f32_16x16x32_bf16 v[124:127], v[144:147], v[182:185], v[124:127]
	v_mfma_f32_16x16x32_bf16 v[120:123], v[158:161], v[182:185], v[120:123]
	v_mfma_f32_16x16x32_bf16 v[116:119], v[144:147], v[190:193], v[116:119]
	v_mfma_f32_16x16x32_bf16 v[108:111], v[158:161], v[190:193], v[108:111]
	v_mfma_f32_16x16x32_bf16 v[100:103], v[144:147], v[198:201], v[100:103]
	v_mfma_f32_16x16x32_bf16 v[92:95], v[158:161], v[198:201], v[92:95]
	v_mfma_f32_16x16x32_bf16 v[84:87], v[144:147], v[206:209], v[84:87]
	v_mfma_f32_16x16x32_bf16 v[76:79], v[158:161], v[206:209], v[76:79]
	v_mfma_f32_16x16x32_bf16 v[124:127], v[154:157], v[186:189], v[124:127]
	v_mfma_f32_16x16x32_bf16 v[120:123], v[162:165], v[186:189], v[120:123]
	v_mfma_f32_16x16x32_bf16 v[116:119], v[154:157], v[194:197], v[116:119]
	v_mfma_f32_16x16x32_bf16 v[108:111], v[162:165], v[194:197], v[108:111]
	v_mfma_f32_16x16x32_bf16 v[100:103], v[154:157], v[202:205], v[100:103]
	v_mfma_f32_16x16x32_bf16 v[92:95], v[162:165], v[202:205], v[92:95]
	v_mfma_f32_16x16x32_bf16 v[84:87], v[154:157], v[210:213], v[84:87]
	v_mfma_f32_16x16x32_bf16 v[76:79], v[162:165], v[210:213], v[76:79]
	v_mfma_f32_16x16x32_bf16 v[112:115], v[166:169], v[182:185], v[112:115]
	v_mfma_f32_16x16x32_bf16 v[104:107], v[174:177], v[182:185], v[104:107]
	v_mfma_f32_16x16x32_bf16 v[96:99], v[166:169], v[190:193], v[96:99]
	v_mfma_f32_16x16x32_bf16 v[88:91], v[174:177], v[190:193], v[88:91]
	v_mfma_f32_16x16x32_bf16 v[80:83], v[166:169], v[198:201], v[80:83]
	v_mfma_f32_16x16x32_bf16 v[72:75], v[174:177], v[198:201], v[72:75]
	v_mfma_f32_16x16x32_bf16 v[68:71], v[166:169], v[206:209], v[68:71]
	v_mfma_f32_16x16x32_bf16 v[64:67], v[174:177], v[206:209], v[64:67]
	v_mfma_f32_16x16x32_bf16 v[112:115], v[170:173], v[186:189], v[112:115]
	v_mfma_f32_16x16x32_bf16 v[104:107], v[178:181], v[186:189], v[104:107]
	v_mfma_f32_16x16x32_bf16 v[96:99], v[170:173], v[194:197], v[96:99]
	v_mfma_f32_16x16x32_bf16 v[88:91], v[178:181], v[194:197], v[88:91]
	v_mfma_f32_16x16x32_bf16 v[80:83], v[170:173], v[202:205], v[80:83]
	v_mfma_f32_16x16x32_bf16 v[72:75], v[178:181], v[202:205], v[72:75]
	v_mfma_f32_16x16x32_bf16 v[68:71], v[170:173], v[210:213], v[68:71]
	v_mfma_f32_16x16x32_bf16 v[64:67], v[178:181], v[210:213], v[64:67]
	s_setprio 0
	s_barrier
	s_add_i32 s53, s44, s61
	v_lshl_add_u64 v[214:215], s[30:31], 0, v[132:133]
	s_mov_b32 m0, s53
	ds_read_b128 v[182:185], v153 offset:16384
	ds_read_b128 v[186:189], v153 offset:17408
	ds_read_b128 v[190:193], v153 offset:18432
	ds_read_b128 v[194:197], v153 offset:19456
	ds_read_b128 v[198:201], v153 offset:20480
	ds_read_b128 v[202:205], v153 offset:21504
	ds_read_b128 v[206:209], v153 offset:22528
	ds_read_b128 v[210:213], v153 offset:23552
	global_load_lds_dwordx4 v[214:215], off
	s_add_i32 m0, s53, 0x2000
	s_add_u32 s54, s30, 0x40000
	v_lshl_add_u64 v[216:217], s[30:31], 0, v[128:129]
	s_addc_u32 s55, s31, 0
	s_add_i32 s53, s45, s61
	global_load_lds_dwordx4 v[216:217], off
	v_lshl_add_u64 v[218:219], s[54:55], 0, v[132:133]
	s_mov_b32 m0, s53
	v_lshl_add_u64 v[220:221], s[34:35], 0, v[130:131]
	global_load_lds_dwordx4 v[218:219], off
	v_lshl_add_u64 v[218:219], s[54:55], 0, v[128:129]
	s_add_i32 m0, s53, 0x2000
	s_nop 0
	global_load_lds_dwordx4 v[218:219], off
	v_lshl_add_u64 v[218:219], s[34:35], 0, v[134:135]
	s_mov_b32 m0, s27
	s_nop 0
	global_load_lds_dwordx4 v[218:219], off
	s_mov_b32 m0, s37
	s_nop 0
	global_load_lds_dwordx4 v[220:221], off
	s_waitcnt vmcnt(8)
	s_waitcnt lgkmcnt(0)
	s_barrier
; #define PG8_STAGE(bufoff, gbase, voff) do { _Pragma("unroll") for (int _i = 0; _i < 2; ++_i) \
;         __builtin_amdgcn_global_load_lds((const unsigned*)((const char*)(gbase) + (voff)[_i]), (LAS unsigned*)(lds + (bufoff) + ldsw + _i * 8192), 16, 0, 0); } while (0)
; #define PG8_LDA(dst, b, h) do { _Pragma("unroll") for (int m = 0; m < 4; ++m) _Pragma("unroll") for (int k = 0; k < 2; ++k) dst[m][k] = *(const LAS bf16x8*)(lds + PG8_SA(b, h) + aoff + m * 2048 + k * 1024); } while (0)
; #define PG8_LDB(dst, b, h) do { _Pragma("unroll") for (int n = 0; n < 2; ++n) _Pragma("unroll") for (int k = 0; k < 2; ++k) dst[n][k] = *(const LAS bf16x8*)(lds + PG8_SB(b, h) + boff + n * 2048 + k * 1024); } while (0)
; #define PG8_MMA(ai, bj, At, Bt) do { __builtin_amdgcn_s_setprio(1); _Pragma("unroll") for (int m = 0; m < 4; ++m) _Pragma("unroll") for (int n = 0; n < 2; ++n) _Pragma("unroll") for (int k = 0; k < 2; ++k) \
;         acc[ai][bj][m][n] = __builtin_amdgcn_mfma_f32_16x16x32_bf16(Bt[n][k], At[m][k], acc[ai][bj][m][n], 0, 0, 0); __builtin_amdgcn_s_setprio(0); } while (0)
; #define PG8_WAIT_V(n) asm volatile("s_waitcnt vmcnt(" #n ")" ::: "memory")
; #define PG8_WAIT_L(n) asm volatile("s_waitcnt lgkmcnt(" #n ")" ::: "memory")
; #define PG8_BAR __builtin_amdgcn_s_barrier()
; #define PG8_SCHED __builtin_amdgcn_sched_barrier(0)
; template <class Epi, bool ALIGN_EPI = true, bool SP2 = true>
; __device__ __forceinline__ void gemm_phase(LAS unsigned char* lds, const Gemm g, const StaticOrder& S, const Epi& E, const int wave_s) {
;     ...
;             PG8_WAIT_V(8); PG8_WAIT_L(0); PG8_BAR; PG8_MMA(1, 0, At, B0); PG8_MMA(1, 1, At, B1); PG8_BAR; PG8_SCHED;
;             PG8_LDB(B0, 1, 0); PG8_LDB(B1, 1, 1); PG8_SCHED; PG8_LDA(At, 1, 0); PG8_STAGE(PG8_SA(0, 1), a2 + hstep, voffA);
;             PG8_WAIT_V(8); PG8_WAIT_L(0); PG8_BAR; PG8_MMA(0, 0, At, B0); PG8_MMA(0, 1, At, B1); PG8_BAR; PG8_SCHED;
	s_setprio 1
	s_waitcnt lgkmcnt(0)
	v_mfma_f32_16x16x32_bf16 v[60:63], v[144:147], v[182:185], v[60:63]
	v_mfma_f32_16x16x32_bf16 v[56:59], v[158:161], v[182:185], v[56:59]
	v_mfma_f32_16x16x32_bf16 v[52:55], v[144:147], v[190:193], v[52:55]
	v_mfma_f32_16x16x32_bf16 v[44:47], v[158:161], v[190:193], v[44:47]
	v_mfma_f32_16x16x32_bf16 v[36:39], v[144:147], v[198:201], v[36:39]
	v_mfma_f32_16x16x32_bf16 v[28:31], v[158:161], v[198:201], v[28:31]
	v_mfma_f32_16x16x32_bf16 v[20:23], v[144:147], v[206:209], v[20:23]
	v_mfma_f32_16x16x32_bf16 v[12:15], v[158:161], v[206:209], v[12:15]
	v_mfma_f32_16x16x32_bf16 v[60:63], v[154:157], v[186:189], v[60:63]
	v_mfma_f32_16x16x32_bf16 v[56:59], v[162:165], v[186:189], v[56:59]
	v_mfma_f32_16x16x32_bf16 v[52:55], v[154:157], v[194:197], v[52:55]
	v_mfma_f32_16x16x32_bf16 v[44:47], v[162:165], v[194:197], v[44:47]
	v_mfma_f32_16x16x32_bf16 v[36:39], v[154:157], v[202:205], v[36:39]
	v_mfma_f32_16x16x32_bf16 v[28:31], v[162:165], v[202:205], v[28:31]
	v_mfma_f32_16x16x32_bf16 v[20:23], v[154:157], v[210:213], v[20:23]
	v_mfma_f32_16x16x32_bf16 v[12:15], v[162:165], v[210:213], v[12:15]
	v_mfma_f32_16x16x32_bf16 v[48:51], v[166:169], v[182:185], v[48:51]
	v_mfma_f32_16x16x32_bf16 v[40:43], v[174:177], v[182:185], v[40:43]
	v_mfma_f32_16x16x32_bf16 v[32:35], v[166:169], v[190:193], v[32:35]
	v_mfma_f32_16x16x32_bf16 v[24:27], v[174:177], v[190:193], v[24:27]
	v_mfma_f32_16x16x32_bf16 v[16:19], v[166:169], v[198:201], v[16:19]
	v_mfma_f32_16x16x32_bf16 v[8:11], v[174:177], v[198:201], v[8:11]
	v_mfma_f32_16x16x32_bf16 v[4:7], v[166:169], v[206:209], v[4:7]
	v_mfma_f32_16x16x32_bf16 v[0:3], v[174:177], v[206:209], v[0:3]
	v_mfma_f32_16x16x32_bf16 v[48:51], v[170:173], v[186:189], v[48:51]
	v_mfma_f32_16x16x32_bf16 v[40:43], v[178:181], v[186:189], v[40:43]
	v_mfma_f32_16x16x32_bf16 v[32:35], v[170:173], v[194:197], v[32:35]
	v_mfma_f32_16x16x32_bf16 v[24:27], v[178:181], v[194:197], v[24:27]
	v_mfma_f32_16x16x32_bf16 v[16:19], v[170:173], v[202:205], v[16:19]
	v_mfma_f32_16x16x32_bf16 v[8:11], v[178:181], v[202:205], v[8:11]
	v_mfma_f32_16x16x32_bf16 v[4:7], v[170:173], v[210:213], v[4:7]
	v_mfma_f32_16x16x32_bf16 v[0:3], v[178:181], v[210:213], v[0:3]
	s_setprio 0
	s_barrier
	s_add_i32 s53, 0, 0x18000
	s_add_i32 s54, 0, 0x1c000
	v_add_u32_e32 v162, s53, v149
	v_add_u32_e32 v178, s54, v149
	ds_read_b128 v[144:147], v162
	ds_read_b128 v[154:157], v162 offset:1024
	ds_read_b128 v[158:161], v162 offset:2048
	ds_read_b128 v[162:165], v162 offset:3072
	ds_read_b128 v[166:169], v178
	ds_read_b128 v[170:173], v178 offset:1024
	ds_read_b128 v[174:177], v178 offset:2048
	ds_read_b128 v[178:181], v178 offset:3072
	s_add_u32 s34, s34, 0x40000
	s_addc_u32 s35, s35, 0
	s_mov_b32 m0, s38
	v_lshl_add_u64 v[222:223], s[34:35], 0, v[134:135]
	ds_read_b128 v[182:185], v153 offset:32768
	ds_read_b128 v[186:189], v153 offset:33792
	ds_read_b128 v[190:193], v153 offset:34816
	ds_read_b128 v[194:197], v153 offset:35840
	ds_read_b128 v[198:201], v153 offset:36864
	ds_read_b128 v[202:205], v153 offset:37888
	ds_read_b128 v[206:209], v153 offset:38912
	ds_read_b128 v[210:213], v153 offset:39936
	global_load_lds_dwordx4 v[222:223], off
	v_lshl_add_u64 v[222:223], s[34:35], 0, v[130:131]
	s_mov_b32 m0, s39
	s_nop 0
	global_load_lds_dwordx4 v[222:223], off
	s_waitcnt vmcnt(8)
	s_waitcnt lgkmcnt(0)
	s_barrier
	s_setprio 1
	s_waitcnt lgkmcnt(0)
	v_mfma_f32_16x16x32_bf16 v[124:127], v[144:147], v[182:185], v[124:127]
	v_mfma_f32_16x16x32_bf16 v[120:123], v[158:161], v[182:185], v[120:123]
	v_mfma_f32_16x16x32_bf16 v[116:119], v[144:147], v[190:193], v[116:119]
	v_mfma_f32_16x16x32_bf16 v[108:111], v[158:161], v[190:193], v[108:111]
	v_mfma_f32_16x16x32_bf16 v[100:103], v[144:147], v[198:201], v[100:103]
	v_mfma_f32_16x16x32_bf16 v[92:95], v[158:161], v[198:201], v[92:95]
	v_mfma_f32_16x16x32_bf16 v[84:87], v[144:147], v[206:209], v[84:87]
	v_mfma_f32_16x16x32_bf16 v[76:79], v[158:161], v[206:209], v[76:79]
	v_mfma_f32_16x16x32_bf16 v[124:127], v[154:157], v[186:189], v[124:127]
	v_mfma_f32_16x16x32_bf16 v[120:123], v[162:165], v[186:189], v[120:123]
	v_mfma_f32_16x16x32_bf16 v[116:119], v[154:157], v[194:197], v[116:119]
	v_mfma_f32_16x16x32_bf16 v[108:111], v[162:165], v[194:197], v[108:111]
	v_mfma_f32_16x16x32_bf16 v[100:103], v[154:157], v[202:205], v[100:103]
	v_mfma_f32_16x16x32_bf16 v[92:95], v[162:165], v[202:205], v[92:95]
	v_mfma_f32_16x16x32_bf16 v[84:87], v[154:157], v[210:213], v[84:87]
	v_mfma_f32_16x16x32_bf16 v[76:79], v[162:165], v[210:213], v[76:79]
	v_mfma_f32_16x16x32_bf16 v[112:115], v[166:169], v[182:185], v[112:115]
	v_mfma_f32_16x16x32_bf16 v[104:107], v[174:177], v[182:185], v[104:107]
	v_mfma_f32_16x16x32_bf16 v[96:99], v[166:169], v[190:193], v[96:99]
	v_mfma_f32_16x16x32_bf16 v[88:91], v[174:177], v[190:193], v[88:91]
	v_mfma_f32_16x16x32_bf16 v[80:83], v[166:169], v[198:201], v[80:83]
	v_mfma_f32_16x16x32_bf16 v[72:75], v[174:177], v[198:201], v[72:75]
	v_mfma_f32_16x16x32_bf16 v[68:71], v[166:169], v[206:209], v[68:71]
	v_mfma_f32_16x16x32_bf16 v[64:67], v[174:177], v[206:209], v[64:67]
	v_mfma_f32_16x16x32_bf16 v[112:115], v[170:173], v[186:189], v[112:115]
	v_mfma_f32_16x16x32_bf16 v[104:107], v[178:181], v[186:189], v[104:107]
	v_mfma_f32_16x16x32_bf16 v[96:99], v[170:173], v[194:197], v[96:99]
	v_mfma_f32_16x16x32_bf16 v[88:91], v[178:181], v[194:197], v[88:91]
	v_mfma_f32_16x16x32_bf16 v[80:83], v[170:173], v[202:205], v[80:83]
	v_mfma_f32_16x16x32_bf16 v[72:75], v[178:181], v[202:205], v[72:75]
	v_mfma_f32_16x16x32_bf16 v[68:71], v[170:173], v[210:213], v[68:71]
	v_mfma_f32_16x16x32_bf16 v[64:67], v[178:181], v[210:213], v[64:67]
	s_setprio 0
	s_barrier
; #define PG8_STAGE(bufoff, gbase, voff) do { _Pragma("unroll") for (int _i = 0; _i < 2; ++_i) \
;         __builtin_amdgcn_global_load_lds((const unsigned*)((const char*)(gbase) + (voff)[_i]), (LAS unsigned*)(lds + (bufoff) + ldsw + _i * 8192), 16, 0, 0); } while (0)
; #define PG8_LDA(dst, b, h) do { _Pragma("unroll") for (int m = 0; m < 4; ++m) _Pragma("unroll") for (int k = 0; k < 2; ++k) dst[m][k] = *(const LAS bf16x8*)(lds + PG8_SA(b, h) + aoff + m * 2048 + k * 1024); } while (0)
; #define PG8_MMA(ai, bj, At, Bt) do { __builtin_amdgcn_s_setprio(1); _Pragma("unroll") for (int m = 0; m < 4; ++m) _Pragma("unroll") for (int n = 0; n < 2; ++n) _Pragma("unroll") for (int k = 0; k < 2; ++k) \
;         acc[ai][bj][m][n] = __builtin_amdgcn_mfma_f32_16x16x32_bf16(Bt[n][k], At[m][k], acc[ai][bj][m][n], 0, 0, 0); __builtin_amdgcn_s_setprio(0); } while (0)
; #define PG8_WAIT_V(n) asm volatile("s_waitcnt vmcnt(" #n ")" ::: "memory")
; #define PG8_WAIT_L(n) asm volatile("s_waitcnt lgkmcnt(" #n ")" ::: "memory")
; #define PG8_BAR __builtin_amdgcn_s_barrier()
; #define PG8_SCHED __builtin_amdgcn_sched_barrier(0)
; template <class Epi, bool ALIGN_EPI = true, bool SP2 = true>
; __device__ __forceinline__ void gemm_phase(LAS unsigned char* lds, const Gemm g, const StaticOrder& S, const Epi& E, const int wave_s) {
;     ...
;         for (int t = 0; t < nt; t += 2) {
;             const bool last = (t == nt - 2);
;             const char* a1 = cA + (size_t)(t + 1) * kstep;
;             const char* a2 = last ? nA : cA + (size_t)(t + 2) * kstep; const char* b2 = last ? nB : cB + (size_t)(t + 2) * kstep;
;     ...
;             PG8_LDA(At, 1, 1); PG8_STAGE(PG8_SB(1, 0), b3, voffB); PG8_STAGE(PG8_SB(1, 1), b3 + hstep, voffB); PG8_STAGE(PG8_SA(1, 0), a3, voffA);
;             PG8_WAIT_V(8); PG8_WAIT_L(0); PG8_BAR; PG8_MMA(1, 0, At, B0); PG8_MMA(1, 1, At, B1); PG8_BAR; PG8_SCHED;
	s_add_i32 s34, s53, s61
	v_lshl_add_u64 v[214:215], v[214:215], 0, s[14:15]
	s_mov_b32 m0, s34
	ds_read_b128 v[182:185], v153 offset:49152
	ds_read_b128 v[186:189], v153 offset:50176
	ds_read_b128 v[190:193], v153 offset:51200
	ds_read_b128 v[194:197], v153 offset:52224
	ds_read_b128 v[198:201], v153 offset:53248
	ds_read_b128 v[202:205], v153 offset:54272
	ds_read_b128 v[206:209], v153 offset:55296
	ds_read_b128 v[210:213], v153 offset:56320
	global_load_lds_dwordx4 v[214:215], off
	s_add_i32 m0, s34, 0x2000
	s_add_u32 s30, s30, 0x40080
	v_lshl_add_u64 v[214:215], v[216:217], 0, s[14:15]
	s_addc_u32 s31, s31, 0
	s_add_i32 s34, s54, s61
	global_load_lds_dwordx4 v[214:215], off
	v_lshl_add_u64 v[214:215], s[30:31], 0, v[132:133]
	s_mov_b32 m0, s34
	s_nop 0
	global_load_lds_dwordx4 v[214:215], off
	v_lshl_add_u64 v[214:215], s[30:31], 0, v[128:129]
	s_add_i32 m0, s34, 0x2000
	s_nop 0
	global_load_lds_dwordx4 v[214:215], off
	v_lshl_add_u64 v[214:215], v[218:219], 0, s[14:15]
	s_mov_b32 m0, s40
	s_nop 0
	global_load_lds_dwordx4 v[214:215], off
	v_lshl_add_u64 v[214:215], v[220:221], 0, s[14:15]
	s_mov_b32 m0, s41
	s_nop 0
	global_load_lds_dwordx4 v[214:215], off
	s_waitcnt vmcnt(8)
	s_waitcnt lgkmcnt(0)
	s_barrier
	s_setprio 1
	s_waitcnt lgkmcnt(0)
	v_mfma_f32_16x16x32_bf16 v[60:63], v[144:147], v[182:185], v[60:63]
	v_mfma_f32_16x16x32_bf16 v[56:59], v[158:161], v[182:185], v[56:59]
	v_mfma_f32_16x16x32_bf16 v[52:55], v[144:147], v[190:193], v[52:55]
	v_mfma_f32_16x16x32_bf16 v[44:47], v[158:161], v[190:193], v[44:47]
	v_mfma_f32_16x16x32_bf16 v[36:39], v[144:147], v[198:201], v[36:39]
	v_mfma_f32_16x16x32_bf16 v[28:31], v[158:161], v[198:201], v[28:31]
	v_mfma_f32_16x16x32_bf16 v[20:23], v[144:147], v[206:209], v[20:23]
	v_mfma_f32_16x16x32_bf16 v[12:15], v[158:161], v[206:209], v[12:15]
	v_mfma_f32_16x16x32_bf16 v[60:63], v[154:157], v[186:189], v[60:63]
	v_mfma_f32_16x16x32_bf16 v[56:59], v[162:165], v[186:189], v[56:59]
	v_mfma_f32_16x16x32_bf16 v[52:55], v[154:157], v[194:197], v[52:55]
	v_mfma_f32_16x16x32_bf16 v[44:47], v[162:165], v[194:197], v[44:47]
	v_mfma_f32_16x16x32_bf16 v[36:39], v[154:157], v[202:205], v[36:39]
	v_mfma_f32_16x16x32_bf16 v[28:31], v[162:165], v[202:205], v[28:31]
	v_mfma_f32_16x16x32_bf16 v[20:23], v[154:157], v[210:213], v[20:23]
	v_mfma_f32_16x16x32_bf16 v[12:15], v[162:165], v[210:213], v[12:15]
	v_mfma_f32_16x16x32_bf16 v[48:51], v[166:169], v[182:185], v[48:51]
	v_mfma_f32_16x16x32_bf16 v[40:43], v[174:177], v[182:185], v[40:43]
	v_mfma_f32_16x16x32_bf16 v[32:35], v[166:169], v[190:193], v[32:35]
	v_mfma_f32_16x16x32_bf16 v[24:27], v[174:177], v[190:193], v[24:27]
	v_mfma_f32_16x16x32_bf16 v[16:19], v[166:169], v[198:201], v[16:19]
	v_mfma_f32_16x16x32_bf16 v[8:11], v[174:177], v[198:201], v[8:11]
	v_mfma_f32_16x16x32_bf16 v[4:7], v[166:169], v[206:209], v[4:7]
	v_mfma_f32_16x16x32_bf16 v[0:3], v[174:177], v[206:209], v[0:3]
	v_mfma_f32_16x16x32_bf16 v[48:51], v[170:173], v[186:189], v[48:51]
	v_mfma_f32_16x16x32_bf16 v[40:43], v[178:181], v[186:189], v[40:43]
	v_mfma_f32_16x16x32_bf16 v[32:35], v[170:173], v[194:197], v[32:35]
	v_mfma_f32_16x16x32_bf16 v[24:27], v[178:181], v[194:197], v[24:27]
	v_mfma_f32_16x16x32_bf16 v[16:19], v[170:173], v[202:205], v[16:19]
	v_mfma_f32_16x16x32_bf16 v[8:11], v[178:181], v[202:205], v[8:11]
	v_mfma_f32_16x16x32_bf16 v[4:7], v[170:173], v[210:213], v[4:7]
	v_mfma_f32_16x16x32_bf16 v[0:3], v[178:181], v[210:213], v[0:3]
	s_setprio 0
	s_barrier
	s_add_i32 s52, s52, 2
	s_add_u32 s50, s50, 0x100
	s_addc_u32 s51, s51, 0
	s_add_u32 s28, s28, 0x100
	s_addc_u32 s29, s29, 0
	s_cmp_gt_u32 s52, 13
	s_cbranch_scc0 .LBB0_116
	s_and_b64 vcc, exec, s[16:17]
	s_cbranch_vccz .LBB0_119
	s_barrier

; #define PG8_STAGE(bufoff, gbase, voff) do { _Pragma("unroll") for (int _i = 0; _i < 2; ++_i) \
;         __builtin_amdgcn_global_load_lds((const unsigned*)((const char*)(gbase) + (voff)[_i]), (LAS unsigned*)(lds + (bufoff) + ldsw + _i * 8192), 16, 0, 0); } while (0)
; #define PG8_LDA(dst, b, h) do { _Pragma("unroll") for (int m = 0; m < 4; ++m) _Pragma("unroll") for (int k = 0; k < 2; ++k) dst[m][k] = *(const LAS bf16x8*)(lds + PG8_SA(b, h) + aoff + m * 2048 + k * 1024); } while (0)
; #define PG8_LDB(dst, b, h) do { _Pragma("unroll") for (int n = 0; n < 2; ++n) _Pragma("unroll") for (int k = 0; k < 2; ++k) dst[n][k] = *(const LAS bf16x8*)(lds + PG8_SB(b, h) + boff + n * 2048 + k * 1024); } while (0)
; #define PG8_MMA(ai, bj, At, Bt) do { __builtin_amdgcn_s_setprio(1); _Pragma("unroll") for (int m = 0; m < 4; ++m) _Pragma("unroll") for (int n = 0; n < 2; ++n) _Pragma("unroll") for (int k = 0; k < 2; ++k) \
;         acc[ai][bj][m][n] = __builtin_amdgcn_mfma_f32_16x16x32_bf16(Bt[n][k], At[m][k], acc[ai][bj][m][n], 0, 0, 0); __builtin_amdgcn_s_setprio(0); } while (0)
; #define PG8_WAIT_V(n) asm volatile("s_waitcnt vmcnt(" #n ")" ::: "memory")
; #define PG8_WAIT_L(n) asm volatile("s_waitcnt lgkmcnt(" #n ")" ::: "memory")
; #define PG8_BAR __builtin_amdgcn_s_barrier()
; #define PG8_SCHED __builtin_amdgcn_sched_barrier(0)
; template <class Epi, bool ALIGN_EPI = true, bool SP2 = true>
; __device__ __forceinline__ void gemm_phase(LAS unsigned char* lds, const Gemm g, const StaticOrder& S, const Epi& E, const int wave_s) {
;     ...
;             PG8_LDB(B0, 0, 0); PG8_LDB(B1, 0, 1); PG8_SCHED; PG8_LDA(At, 0, 0); PG8_STAGE(PG8_SA(1, 1), a1 + hstep, voffA);
;             PG8_WAIT_V(8); PG8_WAIT_L(0); PG8_BAR; PG8_MMA(0, 0, At, B0); PG8_MMA(0, 1, At, B1); PG8_BAR; PG8_SCHED;
;             PG8_LDA(At, 0, 1); PG8_STAGE(PG8_SB(0, 0), b2, voffB); PG8_STAGE(PG8_SB(0, 1), b2 + hstep, voffB); PG8_STAGE(PG8_SA(0, 0), a2, voffA);
;             PG8_WAIT_V(8); PG8_WAIT_L(0); PG8_BAR; PG8_MMA(1, 0, At, B0); PG8_MMA(1, 1, At, B1); PG8_BAR; PG8_SCHED;
.LBB0_477:
	ds_read_b128 v[128:131], v252
	ds_read_b128 v[132:135], v252 offset:1024
	ds_read_b128 v[136:139], v252 offset:2048
	ds_read_b128 v[140:143], v252 offset:3072
	ds_read_b128 v[144:147], v253
	ds_read_b128 v[148:151], v253 offset:1024
	ds_read_b128 v[152:155], v253 offset:2048
	ds_read_b128 v[156:159], v253 offset:3072
	s_add_u32 s46, s44, 0xfffc0080
	s_addc_u32 s47, s45, -1
	s_cmp_eq_u32 s64, 12
	s_cselect_b32 s49, s31, s47
	s_cselect_b32 s48, s59, s46
	s_cselect_b32 s47, s29, s63
	s_cselect_b32 s46, s60, s62
	v_lshl_add_u64 v[192:193], s[44:45], 0, v[210:211]
	s_add_i32 m0, s39, 0xc000
	ds_read_b128 v[160:163], v254
	ds_read_b128 v[164:167], v254 offset:1024
	ds_read_b128 v[168:171], v254 offset:2048
	ds_read_b128 v[172:175], v254 offset:3072
	ds_read_b128 v[176:179], v254 offset:4096
	ds_read_b128 v[180:183], v254 offset:5120
	ds_read_b128 v[184:187], v254 offset:6144
	ds_read_b128 v[188:191], v254 offset:7168
	global_load_lds_dwordx4 v[192:193], off
	v_lshl_add_u64 v[192:193], s[44:45], 0, v[208:209]
	s_add_i32 m0, s39, 0xe000
	s_nop 0
	global_load_lds_dwordx4 v[192:193], off
	s_waitcnt vmcnt(8)
	s_waitcnt lgkmcnt(0)
	s_barrier
	s_setprio 1
	s_waitcnt lgkmcnt(0)
	v_mfma_f32_16x16x32_bf16 v[124:127], v[128:131], v[160:163], v[124:127]
	v_mfma_f32_16x16x32_bf16 v[120:123], v[136:139], v[160:163], v[120:123]
	v_mfma_f32_16x16x32_bf16 v[116:119], v[128:131], v[168:171], v[116:119]
	v_mfma_f32_16x16x32_bf16 v[112:115], v[136:139], v[168:171], v[112:115]
	v_mfma_f32_16x16x32_bf16 v[108:111], v[128:131], v[176:179], v[108:111]
	v_mfma_f32_16x16x32_bf16 v[104:107], v[136:139], v[176:179], v[104:107]
	v_mfma_f32_16x16x32_bf16 v[100:103], v[128:131], v[184:187], v[100:103]
	v_mfma_f32_16x16x32_bf16 v[96:99], v[136:139], v[184:187], v[96:99]
	v_mfma_f32_16x16x32_bf16 v[124:127], v[132:135], v[164:167], v[124:127]
	v_mfma_f32_16x16x32_bf16 v[120:123], v[140:143], v[164:167], v[120:123]
	v_mfma_f32_16x16x32_bf16 v[116:119], v[132:135], v[172:175], v[116:119]
	v_mfma_f32_16x16x32_bf16 v[112:115], v[140:143], v[172:175], v[112:115]
	v_mfma_f32_16x16x32_bf16 v[108:111], v[132:135], v[180:183], v[108:111]
	v_mfma_f32_16x16x32_bf16 v[104:107], v[140:143], v[180:183], v[104:107]
	v_mfma_f32_16x16x32_bf16 v[100:103], v[132:135], v[188:191], v[100:103]
	v_mfma_f32_16x16x32_bf16 v[96:99], v[140:143], v[188:191], v[96:99]
	v_mfma_f32_16x16x32_bf16 v[60:63], v[144:147], v[160:163], v[60:63]
	v_mfma_f32_16x16x32_bf16 v[56:59], v[152:155], v[160:163], v[56:59]
	v_mfma_f32_16x16x32_bf16 v[52:55], v[144:147], v[168:171], v[52:55]
	v_mfma_f32_16x16x32_bf16 v[48:51], v[152:155], v[168:171], v[48:51]
	v_mfma_f32_16x16x32_bf16 v[44:47], v[144:147], v[176:179], v[44:47]
	v_mfma_f32_16x16x32_bf16 v[40:43], v[152:155], v[176:179], v[40:43]
	v_mfma_f32_16x16x32_bf16 v[36:39], v[144:147], v[184:187], v[36:39]
	v_mfma_f32_16x16x32_bf16 v[32:35], v[152:155], v[184:187], v[32:35]
	v_mfma_f32_16x16x32_bf16 v[60:63], v[148:151], v[164:167], v[60:63]
	v_mfma_f32_16x16x32_bf16 v[56:59], v[156:159], v[164:167], v[56:59]
	v_mfma_f32_16x16x32_bf16 v[52:55], v[148:151], v[172:175], v[52:55]
	v_mfma_f32_16x16x32_bf16 v[48:51], v[156:159], v[172:175], v[48:51]
	v_mfma_f32_16x16x32_bf16 v[44:47], v[148:151], v[180:183], v[44:47]
	v_mfma_f32_16x16x32_bf16 v[40:43], v[156:159], v[180:183], v[40:43]
	v_mfma_f32_16x16x32_bf16 v[36:39], v[148:151], v[188:191], v[36:39]
	v_mfma_f32_16x16x32_bf16 v[32:35], v[156:159], v[188:191], v[32:35]
	s_setprio 0
	s_barrier
	s_add_i32 s65, s57, s61
	v_lshl_add_u64 v[192:193], s[46:47], 0, v[202:203]
	s_mov_b32 m0, s65
	ds_read_b128 v[160:163], v254 offset:16384
	ds_read_b128 v[164:167], v254 offset:17408
	ds_read_b128 v[168:171], v254 offset:18432
	ds_read_b128 v[172:175], v254 offset:19456
	ds_read_b128 v[176:179], v254 offset:20480
	ds_read_b128 v[180:183], v254 offset:21504
	ds_read_b128 v[184:187], v254 offset:22528
	ds_read_b128 v[188:191], v254 offset:23552
	global_load_lds_dwordx4 v[192:193], off
	s_add_i32 m0, s65, 0x2000
	s_add_u32 s68, s46, 0x40000
	v_lshl_add_u64 v[194:195], s[46:47], 0, v[206:207]
	s_addc_u32 s69, s47, 0
	s_add_i32 s65, s58, s61
	global_load_lds_dwordx4 v[194:195], off
	v_lshl_add_u64 v[196:197], s[68:69], 0, v[202:203]
	s_mov_b32 m0, s65
	v_lshl_add_u64 v[198:199], s[48:49], 0, v[204:205]
	global_load_lds_dwordx4 v[196:197], off
	v_lshl_add_u64 v[196:197], s[68:69], 0, v[206:207]
	s_add_i32 m0, s65, 0x2000
	s_nop 0
	global_load_lds_dwordx4 v[196:197], off
	v_lshl_add_u64 v[196:197], s[48:49], 0, v[200:201]
	s_mov_b32 m0, s39
	s_nop 0
	global_load_lds_dwordx4 v[196:197], off
	s_mov_b32 m0, s40
	s_nop 0
	global_load_lds_dwordx4 v[198:199], off
	s_waitcnt vmcnt(8)
	s_waitcnt lgkmcnt(0)
	s_barrier
; #define PG8_STAGE(bufoff, gbase, voff) do { _Pragma("unroll") for (int _i = 0; _i < 2; ++_i) \
;         __builtin_amdgcn_global_load_lds((const unsigned*)((const char*)(gbase) + (voff)[_i]), (LAS unsigned*)(lds + (bufoff) + ldsw + _i * 8192), 16, 0, 0); } while (0)
; #define PG8_LDA(dst, b, h) do { _Pragma("unroll") for (int m = 0; m < 4; ++m) _Pragma("unroll") for (int k = 0; k < 2; ++k) dst[m][k] = *(const LAS bf16x8*)(lds + PG8_SA(b, h) + aoff + m * 2048 + k * 1024); } while (0)
; #define PG8_LDB(dst, b, h) do { _Pragma("unroll") for (int n = 0; n < 2; ++n) _Pragma("unroll") for (int k = 0; k < 2; ++k) dst[n][k] = *(const LAS bf16x8*)(lds + PG8_SB(b, h) + boff + n * 2048 + k * 1024); } while (0)
; #define PG8_MMA(ai, bj, At, Bt) do { __builtin_amdgcn_s_setprio(1); _Pragma("unroll") for (int m = 0; m < 4; ++m) _Pragma("unroll") for (int n = 0; n < 2; ++n) _Pragma("unroll") for (int k = 0; k < 2; ++k) \
;         acc[ai][bj][m][n] = __builtin_amdgcn_mfma_f32_16x16x32_bf16(Bt[n][k], At[m][k], acc[ai][bj][m][n], 0, 0, 0); __builtin_amdgcn_s_setprio(0); } while (0)
; #define PG8_WAIT_V(n) asm volatile("s_waitcnt vmcnt(" #n ")" ::: "memory")
; #define PG8_WAIT_L(n) asm volatile("s_waitcnt lgkmcnt(" #n ")" ::: "memory")
; #define PG8_BAR __builtin_amdgcn_s_barrier()
; #define PG8_SCHED __builtin_amdgcn_sched_barrier(0)
; template <class Epi, bool ALIGN_EPI = true, bool SP2 = true>
; __device__ __forceinline__ void gemm_phase(LAS unsigned char* lds, const Gemm g, const StaticOrder& S, const Epi& E, const int wave_s) {
;     ...
;             PG8_WAIT_V(8); PG8_WAIT_L(0); PG8_BAR; PG8_MMA(1, 0, At, B0); PG8_MMA(1, 1, At, B1); PG8_BAR; PG8_SCHED;
;             PG8_LDB(B0, 1, 0); PG8_LDB(B1, 1, 1); PG8_SCHED; PG8_LDA(At, 1, 0); PG8_STAGE(PG8_SA(0, 1), a2 + hstep, voffA);
;             PG8_WAIT_V(8); PG8_WAIT_L(0); PG8_BAR; PG8_MMA(0, 0, At, B0); PG8_MMA(0, 1, At, B1); PG8_BAR; PG8_SCHED;
	s_setprio 1
	s_waitcnt lgkmcnt(0)
	v_mfma_f32_16x16x32_bf16 v[92:95], v[128:131], v[160:163], v[92:95]
	v_mfma_f32_16x16x32_bf16 v[88:91], v[136:139], v[160:163], v[88:91]
	v_mfma_f32_16x16x32_bf16 v[84:87], v[128:131], v[168:171], v[84:87]
	v_mfma_f32_16x16x32_bf16 v[80:83], v[136:139], v[168:171], v[80:83]
	v_mfma_f32_16x16x32_bf16 v[76:79], v[128:131], v[176:179], v[76:79]
	v_mfma_f32_16x16x32_bf16 v[72:75], v[136:139], v[176:179], v[72:75]
	v_mfma_f32_16x16x32_bf16 v[68:71], v[128:131], v[184:187], v[68:71]
	v_mfma_f32_16x16x32_bf16 v[64:67], v[136:139], v[184:187], v[64:67]
	v_mfma_f32_16x16x32_bf16 v[92:95], v[132:135], v[164:167], v[92:95]
	v_mfma_f32_16x16x32_bf16 v[88:91], v[140:143], v[164:167], v[88:91]
	v_mfma_f32_16x16x32_bf16 v[84:87], v[132:135], v[172:175], v[84:87]
	v_mfma_f32_16x16x32_bf16 v[80:83], v[140:143], v[172:175], v[80:83]
	v_mfma_f32_16x16x32_bf16 v[76:79], v[132:135], v[180:183], v[76:79]
	v_mfma_f32_16x16x32_bf16 v[72:75], v[140:143], v[180:183], v[72:75]
	v_mfma_f32_16x16x32_bf16 v[68:71], v[132:135], v[188:191], v[68:71]
	v_mfma_f32_16x16x32_bf16 v[64:67], v[140:143], v[188:191], v[64:67]
	v_mfma_f32_16x16x32_bf16 v[28:31], v[144:147], v[160:163], v[28:31]
	v_mfma_f32_16x16x32_bf16 v[24:27], v[152:155], v[160:163], v[24:27]
	v_mfma_f32_16x16x32_bf16 v[20:23], v[144:147], v[168:171], v[20:23]
	v_mfma_f32_16x16x32_bf16 v[16:19], v[152:155], v[168:171], v[16:19]
	v_mfma_f32_16x16x32_bf16 v[12:15], v[144:147], v[176:179], v[12:15]
	v_mfma_f32_16x16x32_bf16 v[8:11], v[152:155], v[176:179], v[8:11]
	v_mfma_f32_16x16x32_bf16 v[4:7], v[144:147], v[184:187], v[4:7]
	v_mfma_f32_16x16x32_bf16 v[0:3], v[152:155], v[184:187], v[0:3]
	v_mfma_f32_16x16x32_bf16 v[28:31], v[148:151], v[164:167], v[28:31]
	v_mfma_f32_16x16x32_bf16 v[24:27], v[156:159], v[164:167], v[24:27]
	v_mfma_f32_16x16x32_bf16 v[20:23], v[148:151], v[172:175], v[20:23]
	v_mfma_f32_16x16x32_bf16 v[16:19], v[156:159], v[172:175], v[16:19]
	v_mfma_f32_16x16x32_bf16 v[12:15], v[148:151], v[180:183], v[12:15]
	v_mfma_f32_16x16x32_bf16 v[8:11], v[156:159], v[180:183], v[8:11]
	v_mfma_f32_16x16x32_bf16 v[4:7], v[148:151], v[188:191], v[4:7]
	v_mfma_f32_16x16x32_bf16 v[0:3], v[156:159], v[188:191], v[0:3]
	s_setprio 0
	s_barrier
	s_add_i32 s65, 0, 0x18000
	s_add_i32 s66, 0, 0x1c000
	v_add_u32_e32 v140, s65, v250
	v_add_u32_e32 v156, s66, v250
	ds_read_b128 v[128:131], v140
	ds_read_b128 v[132:135], v140 offset:1024
	ds_read_b128 v[136:139], v140 offset:2048
	ds_read_b128 v[140:143], v140 offset:3072
	ds_read_b128 v[144:147], v156
	ds_read_b128 v[148:151], v156 offset:1024
	ds_read_b128 v[152:155], v156 offset:2048
	ds_read_b128 v[156:159], v156 offset:3072
	s_add_u32 s48, s48, 0x40000
	s_addc_u32 s49, s49, 0
	s_mov_b32 m0, s41
	v_lshl_add_u64 v[212:213], s[48:49], 0, v[200:201]
	ds_read_b128 v[160:163], v254 offset:32768
	ds_read_b128 v[164:167], v254 offset:33792
	ds_read_b128 v[168:171], v254 offset:34816
	ds_read_b128 v[172:175], v254 offset:35840
	ds_read_b128 v[176:179], v254 offset:36864
	ds_read_b128 v[180:183], v254 offset:37888
	ds_read_b128 v[184:187], v254 offset:38912
	ds_read_b128 v[188:191], v254 offset:39936
	global_load_lds_dwordx4 v[212:213], off
	v_lshl_add_u64 v[212:213], s[48:49], 0, v[204:205]
	s_mov_b32 m0, s50
	s_nop 0
	global_load_lds_dwordx4 v[212:213], off
	s_waitcnt vmcnt(8)
	s_waitcnt lgkmcnt(0)
	s_barrier
	s_setprio 1
	s_waitcnt lgkmcnt(0)
	v_mfma_f32_16x16x32_bf16 v[124:127], v[128:131], v[160:163], v[124:127]
	v_mfma_f32_16x16x32_bf16 v[120:123], v[136:139], v[160:163], v[120:123]
	v_mfma_f32_16x16x32_bf16 v[116:119], v[128:131], v[168:171], v[116:119]
	v_mfma_f32_16x16x32_bf16 v[112:115], v[136:139], v[168:171], v[112:115]
	v_mfma_f32_16x16x32_bf16 v[108:111], v[128:131], v[176:179], v[108:111]
	v_mfma_f32_16x16x32_bf16 v[104:107], v[136:139], v[176:179], v[104:107]
	v_mfma_f32_16x16x32_bf16 v[100:103], v[128:131], v[184:187], v[100:103]
	v_mfma_f32_16x16x32_bf16 v[96:99], v[136:139], v[184:187], v[96:99]
	v_mfma_f32_16x16x32_bf16 v[124:127], v[132:135], v[164:167], v[124:127]
	v_mfma_f32_16x16x32_bf16 v[120:123], v[140:143], v[164:167], v[120:123]
	v_mfma_f32_16x16x32_bf16 v[116:119], v[132:135], v[172:175], v[116:119]
	v_mfma_f32_16x16x32_bf16 v[112:115], v[140:143], v[172:175], v[112:115]
	v_mfma_f32_16x16x32_bf16 v[108:111], v[132:135], v[180:183], v[108:111]
	v_mfma_f32_16x16x32_bf16 v[104:107], v[140:143], v[180:183], v[104:107]
	v_mfma_f32_16x16x32_bf16 v[100:103], v[132:135], v[188:191], v[100:103]
	v_mfma_f32_16x16x32_bf16 v[96:99], v[140:143], v[188:191], v[96:99]
	v_mfma_f32_16x16x32_bf16 v[60:63], v[144:147], v[160:163], v[60:63]
	v_mfma_f32_16x16x32_bf16 v[56:59], v[152:155], v[160:163], v[56:59]
	v_mfma_f32_16x16x32_bf16 v[52:55], v[144:147], v[168:171], v[52:55]
	v_mfma_f32_16x16x32_bf16 v[48:51], v[152:155], v[168:171], v[48:51]
	v_mfma_f32_16x16x32_bf16 v[44:47], v[144:147], v[176:179], v[44:47]
	v_mfma_f32_16x16x32_bf16 v[40:43], v[152:155], v[176:179], v[40:43]
	v_mfma_f32_16x16x32_bf16 v[36:39], v[144:147], v[184:187], v[36:39]
	v_mfma_f32_16x16x32_bf16 v[32:35], v[152:155], v[184:187], v[32:35]
	v_mfma_f32_16x16x32_bf16 v[60:63], v[148:151], v[164:167], v[60:63]
	v_mfma_f32_16x16x32_bf16 v[56:59], v[156:159], v[164:167], v[56:59]
	v_mfma_f32_16x16x32_bf16 v[52:55], v[148:151], v[172:175], v[52:55]
	v_mfma_f32_16x16x32_bf16 v[48:51], v[156:159], v[172:175], v[48:51]
	v_mfma_f32_16x16x32_bf16 v[44:47], v[148:151], v[180:183], v[44:47]
	v_mfma_f32_16x16x32_bf16 v[40:43], v[156:159], v[180:183], v[40:43]
	v_mfma_f32_16x16x32_bf16 v[36:39], v[148:151], v[188:191], v[36:39]
	v_mfma_f32_16x16x32_bf16 v[32:35], v[156:159], v[188:191], v[32:35]
	s_setprio 0
	s_barrier
; #define PG8_STAGE(bufoff, gbase, voff) do { _Pragma("unroll") for (int _i = 0; _i < 2; ++_i) \
;         __builtin_amdgcn_global_load_lds((const unsigned*)((const char*)(gbase) + (voff)[_i]), (LAS unsigned*)(lds + (bufoff) + ldsw + _i * 8192), 16, 0, 0); } while (0)
; #define PG8_LDA(dst, b, h) do { _Pragma("unroll") for (int m = 0; m < 4; ++m) _Pragma("unroll") for (int k = 0; k < 2; ++k) dst[m][k] = *(const LAS bf16x8*)(lds + PG8_SA(b, h) + aoff + m * 2048 + k * 1024); } while (0)
; #define PG8_MMA(ai, bj, At, Bt) do { __builtin_amdgcn_s_setprio(1); _Pragma("unroll") for (int m = 0; m < 4; ++m) _Pragma("unroll") for (int n = 0; n < 2; ++n) _Pragma("unroll") for (int k = 0; k < 2; ++k) \
;         acc[ai][bj][m][n] = __builtin_amdgcn_mfma_f32_16x16x32_bf16(Bt[n][k], At[m][k], acc[ai][bj][m][n], 0, 0, 0); __builtin_amdgcn_s_setprio(0); } while (0)
; #define PG8_WAIT_V(n) asm volatile("s_waitcnt vmcnt(" #n ")" ::: "memory")
; #define PG8_WAIT_L(n) asm volatile("s_waitcnt lgkmcnt(" #n ")" ::: "memory")
; #define PG8_BAR __builtin_amdgcn_s_barrier()
; #define PG8_SCHED __builtin_amdgcn_sched_barrier(0)
; template <class Epi, bool ALIGN_EPI = true, bool SP2 = true>
; __device__ __forceinline__ void gemm_phase(LAS unsigned char* lds, const Gemm g, const StaticOrder& S, const Epi& E, const int wave_s) {
;     ...
;         for (int t = 0; t < nt; t += 2) {
;             const bool last = (t == nt - 2);
;             const char* a1 = cA + (size_t)(t + 1) * kstep;
;             const char* a2 = last ? nA : cA + (size_t)(t + 2) * kstep; const char* b2 = last ? nB : cB + (size_t)(t + 2) * kstep;
;     ...
;             PG8_LDA(At, 1, 1); PG8_STAGE(PG8_SB(1, 0), b3, voffB); PG8_STAGE(PG8_SB(1, 1), b3 + hstep, voffB); PG8_STAGE(PG8_SA(1, 0), a3, voffA);
;             PG8_WAIT_V(8); PG8_WAIT_L(0); PG8_BAR; PG8_MMA(1, 0, At, B0); PG8_MMA(1, 1, At, B1); PG8_BAR; PG8_SCHED;
	s_add_i32 s48, s65, s61
	v_lshl_add_u64 v[192:193], v[192:193], 0, s[14:15]
	s_mov_b32 m0, s48
	ds_read_b128 v[160:163], v254 offset:49152
	ds_read_b128 v[164:167], v254 offset:50176
	ds_read_b128 v[168:171], v254 offset:51200
	ds_read_b128 v[172:175], v254 offset:52224
	ds_read_b128 v[176:179], v254 offset:53248
	ds_read_b128 v[180:183], v254 offset:54272
	ds_read_b128 v[184:187], v254 offset:55296
	ds_read_b128 v[188:191], v254 offset:56320
	global_load_lds_dwordx4 v[192:193], off
	s_add_i32 m0, s48, 0x2000
	s_add_u32 s46, s46, 0x40080
	v_lshl_add_u64 v[192:193], v[194:195], 0, s[14:15]
	s_addc_u32 s47, s47, 0
	s_add_i32 s48, s66, s61
	global_load_lds_dwordx4 v[192:193], off
	v_lshl_add_u64 v[192:193], s[46:47], 0, v[202:203]
	s_mov_b32 m0, s48
	s_nop 0
	global_load_lds_dwordx4 v[192:193], off
	v_lshl_add_u64 v[192:193], s[46:47], 0, v[206:207]
	s_add_i32 m0, s48, 0x2000
	s_nop 0
	global_load_lds_dwordx4 v[192:193], off
	v_lshl_add_u64 v[192:193], v[196:197], 0, s[14:15]
	s_mov_b32 m0, s54
	s_nop 0
	global_load_lds_dwordx4 v[192:193], off
	v_lshl_add_u64 v[192:193], v[198:199], 0, s[14:15]
	s_mov_b32 m0, s55
	s_nop 0
	global_load_lds_dwordx4 v[192:193], off
	s_waitcnt vmcnt(8)
	s_waitcnt lgkmcnt(0)
	s_barrier
	s_setprio 1
	s_waitcnt lgkmcnt(0)
	v_mfma_f32_16x16x32_bf16 v[92:95], v[128:131], v[160:163], v[92:95]
	v_mfma_f32_16x16x32_bf16 v[88:91], v[136:139], v[160:163], v[88:91]
	v_mfma_f32_16x16x32_bf16 v[84:87], v[128:131], v[168:171], v[84:87]
	v_mfma_f32_16x16x32_bf16 v[80:83], v[136:139], v[168:171], v[80:83]
	v_mfma_f32_16x16x32_bf16 v[76:79], v[128:131], v[176:179], v[76:79]
	v_mfma_f32_16x16x32_bf16 v[72:75], v[136:139], v[176:179], v[72:75]
	v_mfma_f32_16x16x32_bf16 v[68:71], v[128:131], v[184:187], v[68:71]
	v_mfma_f32_16x16x32_bf16 v[64:67], v[136:139], v[184:187], v[64:67]
	v_mfma_f32_16x16x32_bf16 v[92:95], v[132:135], v[164:167], v[92:95]
	v_mfma_f32_16x16x32_bf16 v[88:91], v[140:143], v[164:167], v[88:91]
	v_mfma_f32_16x16x32_bf16 v[84:87], v[132:135], v[172:175], v[84:87]
	v_mfma_f32_16x16x32_bf16 v[80:83], v[140:143], v[172:175], v[80:83]
	v_mfma_f32_16x16x32_bf16 v[76:79], v[132:135], v[180:183], v[76:79]
	v_mfma_f32_16x16x32_bf16 v[72:75], v[140:143], v[180:183], v[72:75]
	v_mfma_f32_16x16x32_bf16 v[68:71], v[132:135], v[188:191], v[68:71]
	v_mfma_f32_16x16x32_bf16 v[64:67], v[140:143], v[188:191], v[64:67]
	v_mfma_f32_16x16x32_bf16 v[28:31], v[144:147], v[160:163], v[28:31]
	v_mfma_f32_16x16x32_bf16 v[24:27], v[152:155], v[160:163], v[24:27]
	v_mfma_f32_16x16x32_bf16 v[20:23], v[144:147], v[168:171], v[20:23]
	v_mfma_f32_16x16x32_bf16 v[16:19], v[152:155], v[168:171], v[16:19]
	v_mfma_f32_16x16x32_bf16 v[12:15], v[144:147], v[176:179], v[12:15]
	v_mfma_f32_16x16x32_bf16 v[8:11], v[152:155], v[176:179], v[8:11]
	v_mfma_f32_16x16x32_bf16 v[4:7], v[144:147], v[184:187], v[4:7]
	v_mfma_f32_16x16x32_bf16 v[0:3], v[152:155], v[184:187], v[0:3]
	v_mfma_f32_16x16x32_bf16 v[28:31], v[148:151], v[164:167], v[28:31]
	v_mfma_f32_16x16x32_bf16 v[24:27], v[156:159], v[164:167], v[24:27]
	v_mfma_f32_16x16x32_bf16 v[20:23], v[148:151], v[172:175], v[20:23]
	v_mfma_f32_16x16x32_bf16 v[16:19], v[156:159], v[172:175], v[16:19]
	v_mfma_f32_16x16x32_bf16 v[12:15], v[148:151], v[180:183], v[12:15]
	v_mfma_f32_16x16x32_bf16 v[8:11], v[156:159], v[180:183], v[8:11]
	v_mfma_f32_16x16x32_bf16 v[4:7], v[148:151], v[188:191], v[4:7]
	v_mfma_f32_16x16x32_bf16 v[0:3], v[156:159], v[188:191], v[0:3]
	s_setprio 0
	s_barrier
	s_add_i32 s64, s64, 2
	s_add_u32 s62, s62, 0x100
	s_addc_u32 s63, s63, 0
	s_add_u32 s44, s44, 0x100
	s_addc_u32 s45, s45, 0
	s_cmp_gt_u32 s64, 13
	s_cbranch_scc0 .LBB0_477
	s_and_b64 vcc, exec, s[16:17]
	s_cbranch_vccz .LBB0_480
	s_barrier

; #define PG8_STAGE(bufoff, gbase, voff) do { _Pragma("unroll") for (int _i = 0; _i < 2; ++_i) \
;         __builtin_amdgcn_global_load_lds((const unsigned*)((const char*)(gbase) + (voff)[_i]), (LAS unsigned*)(lds + (bufoff) + ldsw + _i * 8192), 16, 0, 0); } while (0)
; #define PG8_LDA(dst, b, h) do { _Pragma("unroll") for (int m = 0; m < 4; ++m) _Pragma("unroll") for (int k = 0; k < 2; ++k) dst[m][k] = *(const LAS bf16x8*)(lds + PG8_SA(b, h) + aoff + m * 2048 + k * 1024); } while (0)
; #define PG8_LDB(dst, b, h) do { _Pragma("unroll") for (int n = 0; n < 2; ++n) _Pragma("unroll") for (int k = 0; k < 2; ++k) dst[n][k] = *(const LAS bf16x8*)(lds + PG8_SB(b, h) + boff + n * 2048 + k * 1024); } while (0)
; #define PG8_MMA(ai, bj, At, Bt) do { __builtin_amdgcn_s_setprio(1); _Pragma("unroll") for (int m = 0; m < 4; ++m) _Pragma("unroll") for (int n = 0; n < 2; ++n) _Pragma("unroll") for (int k = 0; k < 2; ++k) \
;         acc[ai][bj][m][n] = __builtin_amdgcn_mfma_f32_16x16x32_bf16(Bt[n][k], At[m][k], acc[ai][bj][m][n], 0, 0, 0); __builtin_amdgcn_s_setprio(0); } while (0)
; #define PG8_WAIT_V(n) asm volatile("s_waitcnt vmcnt(" #n ")" ::: "memory")
; #define PG8_WAIT_L(n) asm volatile("s_waitcnt lgkmcnt(" #n ")" ::: "memory")
; #define PG8_BAR __builtin_amdgcn_s_barrier()
; #define PG8_SCHED __builtin_amdgcn_sched_barrier(0)
; template <class Epi, bool ALIGN_EPI = true, bool SP2 = true>
; __device__ __forceinline__ void gemm_phase(LAS unsigned char* lds, const Gemm g, const StaticOrder& S, const Epi& E, const int wave_s) {
;     ...
;             PG8_LDB(B0, 0, 0); PG8_LDB(B1, 0, 1); PG8_SCHED; PG8_LDA(At, 0, 0); PG8_STAGE(PG8_SA(1, 1), a1 + hstep, voffA);
;             PG8_WAIT_V(8); PG8_WAIT_L(0); PG8_BAR; PG8_MMA(0, 0, At, B0); PG8_MMA(0, 1, At, B1); PG8_BAR; PG8_SCHED;
;             PG8_LDA(At, 0, 1); PG8_STAGE(PG8_SB(0, 0), b2, voffB); PG8_STAGE(PG8_SB(0, 1), b2 + hstep, voffB); PG8_STAGE(PG8_SA(0, 0), a2, voffA);
;             PG8_WAIT_V(8); PG8_WAIT_L(0); PG8_BAR; PG8_MMA(1, 0, At, B0); PG8_MMA(1, 1, At, B1); PG8_BAR; PG8_SCHED;
.LBB0_616:
	ds_read_b128 v[152:155], v149
	ds_read_b128 v[156:159], v149 offset:1024
	ds_read_b128 v[160:163], v149 offset:2048
	ds_read_b128 v[164:167], v149 offset:3072
	ds_read_b128 v[168:171], v150
	ds_read_b128 v[172:175], v150 offset:1024
	ds_read_b128 v[176:179], v150 offset:2048
	ds_read_b128 v[180:183], v150 offset:3072
	s_add_u32 s28, s26, 0xfffc0080
	s_addc_u32 s29, s27, -1
	s_cmp_eq_u32 s52, 12
	s_cselect_b32 s31, s19, s29
	s_cselect_b32 s30, s48, s28
	s_cselect_b32 s29, s17, s51
	s_cselect_b32 s28, s49, s50
	v_lshl_add_u64 v[144:145], s[26:27], 0, v[138:139]
	s_add_i32 m0, s25, 0xc000
	ds_read_b128 v[184:187], v151
	ds_read_b128 v[188:191], v151 offset:1024
	ds_read_b128 v[192:195], v151 offset:2048
	ds_read_b128 v[196:199], v151 offset:3072
	ds_read_b128 v[200:203], v151 offset:4096
	ds_read_b128 v[204:207], v151 offset:5120
	ds_read_b128 v[208:211], v151 offset:6144
	ds_read_b128 v[212:215], v151 offset:7168
	global_load_lds_dwordx4 v[144:145], off
	v_lshl_add_u64 v[144:145], s[26:27], 0, v[136:137]
	s_add_i32 m0, s25, 0xe000
	s_nop 0
	global_load_lds_dwordx4 v[144:145], off
	s_waitcnt vmcnt(8)
	s_waitcnt lgkmcnt(0)
	s_barrier
	s_setprio 1
	s_waitcnt lgkmcnt(0)
	v_mfma_f32_16x16x32_bf16 v[124:127], v[152:155], v[184:187], v[124:127]
	v_mfma_f32_16x16x32_bf16 v[120:123], v[160:163], v[184:187], v[120:123]
	v_mfma_f32_16x16x32_bf16 v[108:111], v[152:155], v[192:195], v[108:111]
	v_mfma_f32_16x16x32_bf16 v[104:107], v[160:163], v[192:195], v[104:107]
	v_mfma_f32_16x16x32_bf16 v[92:95], v[152:155], v[200:203], v[92:95]
	v_mfma_f32_16x16x32_bf16 v[88:91], v[160:163], v[200:203], v[88:91]
	v_mfma_f32_16x16x32_bf16 v[76:79], v[152:155], v[208:211], v[76:79]
	v_mfma_f32_16x16x32_bf16 v[72:75], v[160:163], v[208:211], v[72:75]
	v_mfma_f32_16x16x32_bf16 v[124:127], v[156:159], v[188:191], v[124:127]
	v_mfma_f32_16x16x32_bf16 v[120:123], v[164:167], v[188:191], v[120:123]
	v_mfma_f32_16x16x32_bf16 v[108:111], v[156:159], v[196:199], v[108:111]
	v_mfma_f32_16x16x32_bf16 v[104:107], v[164:167], v[196:199], v[104:107]
	v_mfma_f32_16x16x32_bf16 v[92:95], v[156:159], v[204:207], v[92:95]
	v_mfma_f32_16x16x32_bf16 v[88:91], v[164:167], v[204:207], v[88:91]
	v_mfma_f32_16x16x32_bf16 v[76:79], v[156:159], v[212:215], v[76:79]
	v_mfma_f32_16x16x32_bf16 v[72:75], v[164:167], v[212:215], v[72:75]
	v_mfma_f32_16x16x32_bf16 v[116:119], v[168:171], v[184:187], v[116:119]
	v_mfma_f32_16x16x32_bf16 v[112:115], v[176:179], v[184:187], v[112:115]
	v_mfma_f32_16x16x32_bf16 v[100:103], v[168:171], v[192:195], v[100:103]
	v_mfma_f32_16x16x32_bf16 v[96:99], v[176:179], v[192:195], v[96:99]
	v_mfma_f32_16x16x32_bf16 v[84:87], v[168:171], v[200:203], v[84:87]
	v_mfma_f32_16x16x32_bf16 v[80:83], v[176:179], v[200:203], v[80:83]
	v_mfma_f32_16x16x32_bf16 v[68:71], v[168:171], v[208:211], v[68:71]
	v_mfma_f32_16x16x32_bf16 v[64:67], v[176:179], v[208:211], v[64:67]
	v_mfma_f32_16x16x32_bf16 v[116:119], v[172:175], v[188:191], v[116:119]
	v_mfma_f32_16x16x32_bf16 v[112:115], v[180:183], v[188:191], v[112:115]
	v_mfma_f32_16x16x32_bf16 v[100:103], v[172:175], v[196:199], v[100:103]
	v_mfma_f32_16x16x32_bf16 v[96:99], v[180:183], v[196:199], v[96:99]
	v_mfma_f32_16x16x32_bf16 v[84:87], v[172:175], v[204:207], v[84:87]
	v_mfma_f32_16x16x32_bf16 v[80:83], v[180:183], v[204:207], v[80:83]
	v_mfma_f32_16x16x32_bf16 v[68:71], v[172:175], v[212:215], v[68:71]
	v_mfma_f32_16x16x32_bf16 v[64:67], v[180:183], v[212:215], v[64:67]
	s_setprio 0
	s_barrier
	s_add_i32 s53, s44, s61
	v_lshl_add_u64 v[144:145], s[28:29], 0, v[132:133]
	s_mov_b32 m0, s53
	ds_read_b128 v[184:187], v151 offset:16384
	ds_read_b128 v[188:191], v151 offset:17408
	ds_read_b128 v[192:195], v151 offset:18432
	ds_read_b128 v[196:199], v151 offset:19456
	ds_read_b128 v[200:203], v151 offset:20480
	ds_read_b128 v[204:207], v151 offset:21504
	ds_read_b128 v[208:211], v151 offset:22528
	ds_read_b128 v[212:215], v151 offset:23552
	global_load_lds_dwordx4 v[144:145], off
	s_add_i32 m0, s53, 0x2000
	s_add_u32 s54, s28, 0x40000
	v_lshl_add_u64 v[216:217], s[28:29], 0, v[128:129]
	s_addc_u32 s55, s29, 0
	s_add_i32 s53, s45, s61
	global_load_lds_dwordx4 v[216:217], off
	v_lshl_add_u64 v[218:219], s[54:55], 0, v[132:133]
	s_mov_b32 m0, s53
	v_lshl_add_u64 v[220:221], s[30:31], 0, v[130:131]
	global_load_lds_dwordx4 v[218:219], off
	v_lshl_add_u64 v[218:219], s[54:55], 0, v[128:129]
	s_add_i32 m0, s53, 0x2000
	s_nop 0
	global_load_lds_dwordx4 v[218:219], off
	v_lshl_add_u64 v[218:219], s[30:31], 0, v[134:135]
	s_mov_b32 m0, s25
	s_nop 0
	global_load_lds_dwordx4 v[218:219], off
	s_mov_b32 m0, s37
	s_nop 0
	global_load_lds_dwordx4 v[220:221], off
	s_waitcnt vmcnt(8)
	s_waitcnt lgkmcnt(0)
	s_barrier
; #define PG8_STAGE(bufoff, gbase, voff) do { _Pragma("unroll") for (int _i = 0; _i < 2; ++_i) \
;         __builtin_amdgcn_global_load_lds((const unsigned*)((const char*)(gbase) + (voff)[_i]), (LAS unsigned*)(lds + (bufoff) + ldsw + _i * 8192), 16, 0, 0); } while (0)
; #define PG8_LDA(dst, b, h) do { _Pragma("unroll") for (int m = 0; m < 4; ++m) _Pragma("unroll") for (int k = 0; k < 2; ++k) dst[m][k] = *(const LAS bf16x8*)(lds + PG8_SA(b, h) + aoff + m * 2048 + k * 1024); } while (0)
; #define PG8_LDB(dst, b, h) do { _Pragma("unroll") for (int n = 0; n < 2; ++n) _Pragma("unroll") for (int k = 0; k < 2; ++k) dst[n][k] = *(const LAS bf16x8*)(lds + PG8_SB(b, h) + boff + n * 2048 + k * 1024); } while (0)
; #define PG8_MMA(ai, bj, At, Bt) do { __builtin_amdgcn_s_setprio(1); _Pragma("unroll") for (int m = 0; m < 4; ++m) _Pragma("unroll") for (int n = 0; n < 2; ++n) _Pragma("unroll") for (int k = 0; k < 2; ++k) \
;         acc[ai][bj][m][n] = __builtin_amdgcn_mfma_f32_16x16x32_bf16(Bt[n][k], At[m][k], acc[ai][bj][m][n], 0, 0, 0); __builtin_amdgcn_s_setprio(0); } while (0)
; #define PG8_WAIT_V(n) asm volatile("s_waitcnt vmcnt(" #n ")" ::: "memory")
; #define PG8_WAIT_L(n) asm volatile("s_waitcnt lgkmcnt(" #n ")" ::: "memory")
; #define PG8_BAR __builtin_amdgcn_s_barrier()
; #define PG8_SCHED __builtin_amdgcn_sched_barrier(0)
; template <class Epi, bool ALIGN_EPI = true, bool SP2 = true>
; __device__ __forceinline__ void gemm_phase(LAS unsigned char* lds, const Gemm g, const StaticOrder& S, const Epi& E, const int wave_s) {
;     ...
;             PG8_WAIT_V(8); PG8_WAIT_L(0); PG8_BAR; PG8_MMA(1, 0, At, B0); PG8_MMA(1, 1, At, B1); PG8_BAR; PG8_SCHED;
;             PG8_LDB(B0, 1, 0); PG8_LDB(B1, 1, 1); PG8_SCHED; PG8_LDA(At, 1, 0); PG8_STAGE(PG8_SA(0, 1), a2 + hstep, voffA);
;             PG8_WAIT_V(8); PG8_WAIT_L(0); PG8_BAR; PG8_MMA(0, 0, At, B0); PG8_MMA(0, 1, At, B1); PG8_BAR; PG8_SCHED;
	s_setprio 1
	s_waitcnt lgkmcnt(0)
	v_mfma_f32_16x16x32_bf16 v[60:63], v[152:155], v[184:187], v[60:63]
	v_mfma_f32_16x16x32_bf16 v[56:59], v[160:163], v[184:187], v[56:59]
	v_mfma_f32_16x16x32_bf16 v[44:47], v[152:155], v[192:195], v[44:47]
	v_mfma_f32_16x16x32_bf16 v[40:43], v[160:163], v[192:195], v[40:43]
	v_mfma_f32_16x16x32_bf16 v[28:31], v[152:155], v[200:203], v[28:31]
	v_mfma_f32_16x16x32_bf16 v[24:27], v[160:163], v[200:203], v[24:27]
	v_mfma_f32_16x16x32_bf16 v[12:15], v[152:155], v[208:211], v[12:15]
	v_mfma_f32_16x16x32_bf16 v[8:11], v[160:163], v[208:211], v[8:11]
	v_mfma_f32_16x16x32_bf16 v[60:63], v[156:159], v[188:191], v[60:63]
	v_mfma_f32_16x16x32_bf16 v[56:59], v[164:167], v[188:191], v[56:59]
	v_mfma_f32_16x16x32_bf16 v[44:47], v[156:159], v[196:199], v[44:47]
	v_mfma_f32_16x16x32_bf16 v[40:43], v[164:167], v[196:199], v[40:43]
	v_mfma_f32_16x16x32_bf16 v[28:31], v[156:159], v[204:207], v[28:31]
	v_mfma_f32_16x16x32_bf16 v[24:27], v[164:167], v[204:207], v[24:27]
	v_mfma_f32_16x16x32_bf16 v[12:15], v[156:159], v[212:215], v[12:15]
	v_mfma_f32_16x16x32_bf16 v[8:11], v[164:167], v[212:215], v[8:11]
	v_mfma_f32_16x16x32_bf16 v[52:55], v[168:171], v[184:187], v[52:55]
	v_mfma_f32_16x16x32_bf16 v[48:51], v[176:179], v[184:187], v[48:51]
	v_mfma_f32_16x16x32_bf16 v[36:39], v[168:171], v[192:195], v[36:39]
	v_mfma_f32_16x16x32_bf16 v[32:35], v[176:179], v[192:195], v[32:35]
	v_mfma_f32_16x16x32_bf16 v[20:23], v[168:171], v[200:203], v[20:23]
	v_mfma_f32_16x16x32_bf16 v[16:19], v[176:179], v[200:203], v[16:19]
	v_mfma_f32_16x16x32_bf16 v[4:7], v[168:171], v[208:211], v[4:7]
	v_mfma_f32_16x16x32_bf16 v[0:3], v[176:179], v[208:211], v[0:3]
	v_mfma_f32_16x16x32_bf16 v[52:55], v[172:175], v[188:191], v[52:55]
	v_mfma_f32_16x16x32_bf16 v[48:51], v[180:183], v[188:191], v[48:51]
	v_mfma_f32_16x16x32_bf16 v[36:39], v[172:175], v[196:199], v[36:39]
	v_mfma_f32_16x16x32_bf16 v[32:35], v[180:183], v[196:199], v[32:35]
	v_mfma_f32_16x16x32_bf16 v[20:23], v[172:175], v[204:207], v[20:23]
	v_mfma_f32_16x16x32_bf16 v[16:19], v[180:183], v[204:207], v[16:19]
	v_mfma_f32_16x16x32_bf16 v[4:7], v[172:175], v[212:215], v[4:7]
	v_mfma_f32_16x16x32_bf16 v[0:3], v[180:183], v[212:215], v[0:3]
	s_setprio 0
	s_barrier
	s_add_i32 s53, 0, 0x18000
	s_add_i32 s54, 0, 0x1c000
	v_add_u32_e32 v164, s53, v147
	v_add_u32_e32 v180, s54, v147
	ds_read_b128 v[152:155], v164
	ds_read_b128 v[156:159], v164 offset:1024
	ds_read_b128 v[160:163], v164 offset:2048
	ds_read_b128 v[164:167], v164 offset:3072
	ds_read_b128 v[168:171], v180
	ds_read_b128 v[172:175], v180 offset:1024
	ds_read_b128 v[176:179], v180 offset:2048
	ds_read_b128 v[180:183], v180 offset:3072
	s_add_u32 s30, s30, 0x40000
	s_addc_u32 s31, s31, 0
	s_mov_b32 m0, s38
	v_lshl_add_u64 v[222:223], s[30:31], 0, v[134:135]
	ds_read_b128 v[184:187], v151 offset:32768
	ds_read_b128 v[188:191], v151 offset:33792
	ds_read_b128 v[192:195], v151 offset:34816
	ds_read_b128 v[196:199], v151 offset:35840
	ds_read_b128 v[200:203], v151 offset:36864
	ds_read_b128 v[204:207], v151 offset:37888
	ds_read_b128 v[208:211], v151 offset:38912
	ds_read_b128 v[212:215], v151 offset:39936
	global_load_lds_dwordx4 v[222:223], off
	v_lshl_add_u64 v[222:223], s[30:31], 0, v[130:131]
	s_mov_b32 m0, s39
	s_nop 0
	global_load_lds_dwordx4 v[222:223], off
	s_waitcnt vmcnt(8)
	s_waitcnt lgkmcnt(0)
	s_barrier
	s_setprio 1
	s_waitcnt lgkmcnt(0)
	v_mfma_f32_16x16x32_bf16 v[124:127], v[152:155], v[184:187], v[124:127]
	v_mfma_f32_16x16x32_bf16 v[120:123], v[160:163], v[184:187], v[120:123]
	v_mfma_f32_16x16x32_bf16 v[108:111], v[152:155], v[192:195], v[108:111]
	v_mfma_f32_16x16x32_bf16 v[104:107], v[160:163], v[192:195], v[104:107]
	v_mfma_f32_16x16x32_bf16 v[92:95], v[152:155], v[200:203], v[92:95]
	v_mfma_f32_16x16x32_bf16 v[88:91], v[160:163], v[200:203], v[88:91]
	v_mfma_f32_16x16x32_bf16 v[76:79], v[152:155], v[208:211], v[76:79]
	v_mfma_f32_16x16x32_bf16 v[72:75], v[160:163], v[208:211], v[72:75]
	v_mfma_f32_16x16x32_bf16 v[124:127], v[156:159], v[188:191], v[124:127]
	v_mfma_f32_16x16x32_bf16 v[120:123], v[164:167], v[188:191], v[120:123]
	v_mfma_f32_16x16x32_bf16 v[108:111], v[156:159], v[196:199], v[108:111]
	v_mfma_f32_16x16x32_bf16 v[104:107], v[164:167], v[196:199], v[104:107]
	v_mfma_f32_16x16x32_bf16 v[92:95], v[156:159], v[204:207], v[92:95]
	v_mfma_f32_16x16x32_bf16 v[88:91], v[164:167], v[204:207], v[88:91]
	v_mfma_f32_16x16x32_bf16 v[76:79], v[156:159], v[212:215], v[76:79]
	v_mfma_f32_16x16x32_bf16 v[72:75], v[164:167], v[212:215], v[72:75]
	v_mfma_f32_16x16x32_bf16 v[116:119], v[168:171], v[184:187], v[116:119]
	v_mfma_f32_16x16x32_bf16 v[112:115], v[176:179], v[184:187], v[112:115]
	v_mfma_f32_16x16x32_bf16 v[100:103], v[168:171], v[192:195], v[100:103]
	v_mfma_f32_16x16x32_bf16 v[96:99], v[176:179], v[192:195], v[96:99]
	v_mfma_f32_16x16x32_bf16 v[84:87], v[168:171], v[200:203], v[84:87]
	v_mfma_f32_16x16x32_bf16 v[80:83], v[176:179], v[200:203], v[80:83]
	v_mfma_f32_16x16x32_bf16 v[68:71], v[168:171], v[208:211], v[68:71]
	v_mfma_f32_16x16x32_bf16 v[64:67], v[176:179], v[208:211], v[64:67]
	v_mfma_f32_16x16x32_bf16 v[116:119], v[172:175], v[188:191], v[116:119]
	v_mfma_f32_16x16x32_bf16 v[112:115], v[180:183], v[188:191], v[112:115]
	v_mfma_f32_16x16x32_bf16 v[100:103], v[172:175], v[196:199], v[100:103]
	v_mfma_f32_16x16x32_bf16 v[96:99], v[180:183], v[196:199], v[96:99]
	v_mfma_f32_16x16x32_bf16 v[84:87], v[172:175], v[204:207], v[84:87]
	v_mfma_f32_16x16x32_bf16 v[80:83], v[180:183], v[204:207], v[80:83]
	v_mfma_f32_16x16x32_bf16 v[68:71], v[172:175], v[212:215], v[68:71]
	v_mfma_f32_16x16x32_bf16 v[64:67], v[180:183], v[212:215], v[64:67]
	s_setprio 0
	s_barrier
; #define PG8_STAGE(bufoff, gbase, voff) do { _Pragma("unroll") for (int _i = 0; _i < 2; ++_i) \
;         __builtin_amdgcn_global_load_lds((const unsigned*)((const char*)(gbase) + (voff)[_i]), (LAS unsigned*)(lds + (bufoff) + ldsw + _i * 8192), 16, 0, 0); } while (0)
; #define PG8_LDA(dst, b, h) do { _Pragma("unroll") for (int m = 0; m < 4; ++m) _Pragma("unroll") for (int k = 0; k < 2; ++k) dst[m][k] = *(const LAS bf16x8*)(lds + PG8_SA(b, h) + aoff + m * 2048 + k * 1024); } while (0)
; #define PG8_MMA(ai, bj, At, Bt) do { __builtin_amdgcn_s_setprio(1); _Pragma("unroll") for (int m = 0; m < 4; ++m) _Pragma("unroll") for (int n = 0; n < 2; ++n) _Pragma("unroll") for (int k = 0; k < 2; ++k) \
;         acc[ai][bj][m][n] = __builtin_amdgcn_mfma_f32_16x16x32_bf16(Bt[n][k], At[m][k], acc[ai][bj][m][n], 0, 0, 0); __builtin_amdgcn_s_setprio(0); } while (0)
; #define PG8_WAIT_V(n) asm volatile("s_waitcnt vmcnt(" #n ")" ::: "memory")
; #define PG8_WAIT_L(n) asm volatile("s_waitcnt lgkmcnt(" #n ")" ::: "memory")
; #define PG8_BAR __builtin_amdgcn_s_barrier()
; #define PG8_SCHED __builtin_amdgcn_sched_barrier(0)
; template <class Epi, bool ALIGN_EPI = true, bool SP2 = true>
; __device__ __forceinline__ void gemm_phase(LAS unsigned char* lds, const Gemm g, const StaticOrder& S, const Epi& E, const int wave_s) {
;     ...
;         for (int t = 0; t < nt; t += 2) {
;             const bool last = (t == nt - 2);
;             const char* a1 = cA + (size_t)(t + 1) * kstep;
;             const char* a2 = last ? nA : cA + (size_t)(t + 2) * kstep; const char* b2 = last ? nB : cB + (size_t)(t + 2) * kstep;
;     ...
;             PG8_LDA(At, 1, 1); PG8_STAGE(PG8_SB(1, 0), b3, voffB); PG8_STAGE(PG8_SB(1, 1), b3 + hstep, voffB); PG8_STAGE(PG8_SA(1, 0), a3, voffA);
;             PG8_WAIT_V(8); PG8_WAIT_L(0); PG8_BAR; PG8_MMA(1, 0, At, B0); PG8_MMA(1, 1, At, B1); PG8_BAR; PG8_SCHED;
	s_add_i32 s30, s53, s61
	v_lshl_add_u64 v[144:145], v[144:145], 0, s[10:11]
	s_mov_b32 m0, s30
	ds_read_b128 v[184:187], v151 offset:49152
	ds_read_b128 v[188:191], v151 offset:50176
	ds_read_b128 v[192:195], v151 offset:51200
	ds_read_b128 v[196:199], v151 offset:52224
	ds_read_b128 v[200:203], v151 offset:53248
	ds_read_b128 v[204:207], v151 offset:54272
	ds_read_b128 v[208:211], v151 offset:55296
	ds_read_b128 v[212:215], v151 offset:56320
	global_load_lds_dwordx4 v[144:145], off
	s_add_i32 m0, s30, 0x2000
	s_add_u32 s28, s28, 0x40080
	v_lshl_add_u64 v[144:145], v[216:217], 0, s[10:11]
	s_addc_u32 s29, s29, 0
	s_add_i32 s30, s54, s61
	global_load_lds_dwordx4 v[144:145], off
	v_lshl_add_u64 v[144:145], s[28:29], 0, v[132:133]
	s_mov_b32 m0, s30
	s_nop 0
	global_load_lds_dwordx4 v[144:145], off
	v_lshl_add_u64 v[144:145], s[28:29], 0, v[128:129]
	s_add_i32 m0, s30, 0x2000
	s_nop 0
	global_load_lds_dwordx4 v[144:145], off
	v_lshl_add_u64 v[144:145], v[218:219], 0, s[10:11]
	s_mov_b32 m0, s40
	s_nop 0
	global_load_lds_dwordx4 v[144:145], off
	v_lshl_add_u64 v[144:145], v[220:221], 0, s[10:11]
	s_mov_b32 m0, s41
	s_nop 0
	global_load_lds_dwordx4 v[144:145], off
	s_waitcnt vmcnt(8)
	s_waitcnt lgkmcnt(0)
	s_barrier
	s_setprio 1
	s_waitcnt lgkmcnt(0)
	v_mfma_f32_16x16x32_bf16 v[60:63], v[152:155], v[184:187], v[60:63]
	v_mfma_f32_16x16x32_bf16 v[56:59], v[160:163], v[184:187], v[56:59]
	v_mfma_f32_16x16x32_bf16 v[44:47], v[152:155], v[192:195], v[44:47]
	v_mfma_f32_16x16x32_bf16 v[40:43], v[160:163], v[192:195], v[40:43]
	v_mfma_f32_16x16x32_bf16 v[28:31], v[152:155], v[200:203], v[28:31]
	v_mfma_f32_16x16x32_bf16 v[24:27], v[160:163], v[200:203], v[24:27]
	v_mfma_f32_16x16x32_bf16 v[12:15], v[152:155], v[208:211], v[12:15]
	v_mfma_f32_16x16x32_bf16 v[8:11], v[160:163], v[208:211], v[8:11]
	v_mfma_f32_16x16x32_bf16 v[60:63], v[156:159], v[188:191], v[60:63]
	v_mfma_f32_16x16x32_bf16 v[56:59], v[164:167], v[188:191], v[56:59]
	v_mfma_f32_16x16x32_bf16 v[44:47], v[156:159], v[196:199], v[44:47]
	v_mfma_f32_16x16x32_bf16 v[40:43], v[164:167], v[196:199], v[40:43]
	v_mfma_f32_16x16x32_bf16 v[28:31], v[156:159], v[204:207], v[28:31]
	v_mfma_f32_16x16x32_bf16 v[24:27], v[164:167], v[204:207], v[24:27]
	v_mfma_f32_16x16x32_bf16 v[12:15], v[156:159], v[212:215], v[12:15]
	v_mfma_f32_16x16x32_bf16 v[8:11], v[164:167], v[212:215], v[8:11]
	v_mfma_f32_16x16x32_bf16 v[52:55], v[168:171], v[184:187], v[52:55]
	v_mfma_f32_16x16x32_bf16 v[48:51], v[176:179], v[184:187], v[48:51]
	v_mfma_f32_16x16x32_bf16 v[36:39], v[168:171], v[192:195], v[36:39]
	v_mfma_f32_16x16x32_bf16 v[32:35], v[176:179], v[192:195], v[32:35]
	v_mfma_f32_16x16x32_bf16 v[20:23], v[168:171], v[200:203], v[20:23]
	v_mfma_f32_16x16x32_bf16 v[16:19], v[176:179], v[200:203], v[16:19]
	v_mfma_f32_16x16x32_bf16 v[4:7], v[168:171], v[208:211], v[4:7]
	v_mfma_f32_16x16x32_bf16 v[0:3], v[176:179], v[208:211], v[0:3]
	v_mfma_f32_16x16x32_bf16 v[52:55], v[172:175], v[188:191], v[52:55]
	v_mfma_f32_16x16x32_bf16 v[48:51], v[180:183], v[188:191], v[48:51]
	v_mfma_f32_16x16x32_bf16 v[36:39], v[172:175], v[196:199], v[36:39]
	v_mfma_f32_16x16x32_bf16 v[32:35], v[180:183], v[196:199], v[32:35]
	v_mfma_f32_16x16x32_bf16 v[20:23], v[172:175], v[204:207], v[20:23]
	v_mfma_f32_16x16x32_bf16 v[16:19], v[180:183], v[204:207], v[16:19]
	v_mfma_f32_16x16x32_bf16 v[4:7], v[172:175], v[212:215], v[4:7]
	v_mfma_f32_16x16x32_bf16 v[0:3], v[180:183], v[212:215], v[0:3]
	s_setprio 0
	s_barrier
	s_add_i32 s52, s52, 2
	s_add_u32 s50, s50, 0x100
	s_addc_u32 s51, s51, 0
	s_add_u32 s26, s26, 0x100
	s_addc_u32 s27, s27, 0
	s_cmp_gt_u32 s52, 13
	s_cbranch_scc0 .LBB0_616
	s_and_b64 vcc, exec, s[14:15]
	s_cbranch_vccz .LBB0_619
	s_barrier

; #define PG8_STAGE(bufoff, gbase, voff) do { _Pragma("unroll") for (int _i = 0; _i < 2; ++_i) \
;         __builtin_amdgcn_global_load_lds((const unsigned*)((const char*)(gbase) + (voff)[_i]), (LAS unsigned*)(lds + (bufoff) + ldsw + _i * 8192), 16, 0, 0); } while (0)
; #define PG8_LDA(dst, b, h) do { _Pragma("unroll") for (int m = 0; m < 4; ++m) _Pragma("unroll") for (int k = 0; k < 2; ++k) dst[m][k] = *(const LAS bf16x8*)(lds + PG8_SA(b, h) + aoff + m * 2048 + k * 1024); } while (0)
; #define PG8_LDB(dst, b, h) do { _Pragma("unroll") for (int n = 0; n < 2; ++n) _Pragma("unroll") for (int k = 0; k < 2; ++k) dst[n][k] = *(const LAS bf16x8*)(lds + PG8_SB(b, h) + boff + n * 2048 + k * 1024); } while (0)
; #define PG8_MMA(ai, bj, At, Bt) do { __builtin_amdgcn_s_setprio(1); _Pragma("unroll") for (int m = 0; m < 4; ++m) _Pragma("unroll") for (int n = 0; n < 2; ++n) _Pragma("unroll") for (int k = 0; k < 2; ++k) \
;         acc[ai][bj][m][n] = __builtin_amdgcn_mfma_f32_16x16x32_bf16(Bt[n][k], At[m][k], acc[ai][bj][m][n], 0, 0, 0); __builtin_amdgcn_s_setprio(0); } while (0)
; #define PG8_WAIT_V(n) asm volatile("s_waitcnt vmcnt(" #n ")" ::: "memory")
; #define PG8_WAIT_L(n) asm volatile("s_waitcnt lgkmcnt(" #n ")" ::: "memory")
; #define PG8_BAR __builtin_amdgcn_s_barrier()
; #define PG8_SCHED __builtin_amdgcn_sched_barrier(0)
; template <class Epi, bool ALIGN_EPI = true, bool SP2 = true>
; __device__ __forceinline__ void gemm_phase(LAS unsigned char* lds, const Gemm g, const StaticOrder& S, const Epi& E, const int wave_s) {
;     ...
;             PG8_LDB(B0, 0, 0); PG8_LDB(B1, 0, 1); PG8_SCHED; PG8_LDA(At, 0, 0); PG8_STAGE(PG8_SA(1, 1), a1 + hstep, voffA);
;             PG8_WAIT_V(8); PG8_WAIT_L(0); PG8_BAR; PG8_MMA(0, 0, At, B0); PG8_MMA(0, 1, At, B1); PG8_BAR; PG8_SCHED;
;             PG8_LDA(At, 0, 1); PG8_STAGE(PG8_SB(0, 0), b2, voffB); PG8_STAGE(PG8_SB(0, 1), b2 + hstep, voffB); PG8_STAGE(PG8_SA(0, 0), a2, voffA);
;             PG8_WAIT_V(8); PG8_WAIT_L(0); PG8_BAR; PG8_MMA(1, 0, At, B0); PG8_MMA(1, 1, At, B1); PG8_BAR; PG8_SCHED;
.LBB0_690:
	ds_read_b128 v[140:143], v185
	ds_read_b128 v[144:147], v185 offset:1024
	ds_read_b128 v[148:151], v185 offset:2048
	ds_read_b128 v[152:155], v185 offset:3072
	ds_read_b128 v[156:159], v186
	ds_read_b128 v[160:163], v186 offset:1024
	ds_read_b128 v[164:167], v186 offset:2048
	ds_read_b128 v[168:171], v186 offset:3072
	s_add_u32 s44, s42, 0x100
	s_addc_u32 s45, s43, 0
	s_cmp_eq_u32 s66, 40
	s_cselect_b32 s49, s7, s45
	s_cselect_b32 s48, s6, s44
	s_cselect_b32 s47, s37, s65
	s_cselect_b32 s46, s36, s64
	v_lshl_add_u64 v[180:181], s[42:43], 0, v[138:139]
	s_add_i32 m0, s39, 0xc000
	ds_read_b128 v[172:175], v187
	ds_read_b128 v[176:179], v187 offset:1024
	ds_read_b128 v[188:191], v187 offset:2048
	ds_read_b128 v[192:195], v187 offset:3072
	ds_read_b128 v[196:199], v187 offset:4096
	ds_read_b128 v[200:203], v187 offset:5120
	ds_read_b128 v[204:207], v187 offset:6144
	ds_read_b128 v[208:211], v187 offset:7168
	global_load_lds_dwordx4 v[180:181], off
	v_lshl_add_u64 v[180:181], s[42:43], 0, v[136:137]
	s_add_i32 m0, s39, 0xe000
	s_nop 0
	global_load_lds_dwordx4 v[180:181], off
	s_waitcnt vmcnt(8)
	s_waitcnt lgkmcnt(0)
	s_barrier
	s_setprio 1
	s_waitcnt lgkmcnt(0)
	v_mfma_f32_16x16x32_bf16 v[124:127], v[140:143], v[172:175], v[124:127]
	v_mfma_f32_16x16x32_bf16 v[120:123], v[148:151], v[172:175], v[120:123]
	v_mfma_f32_16x16x32_bf16 v[116:119], v[140:143], v[188:191], v[116:119]
	v_mfma_f32_16x16x32_bf16 v[112:115], v[148:151], v[188:191], v[112:115]
	v_mfma_f32_16x16x32_bf16 v[108:111], v[140:143], v[196:199], v[108:111]
	v_mfma_f32_16x16x32_bf16 v[104:107], v[148:151], v[196:199], v[104:107]
	v_mfma_f32_16x16x32_bf16 v[100:103], v[140:143], v[204:207], v[100:103]
	v_mfma_f32_16x16x32_bf16 v[96:99], v[148:151], v[204:207], v[96:99]
	v_mfma_f32_16x16x32_bf16 v[124:127], v[144:147], v[176:179], v[124:127]
	v_mfma_f32_16x16x32_bf16 v[120:123], v[152:155], v[176:179], v[120:123]
	v_mfma_f32_16x16x32_bf16 v[116:119], v[144:147], v[192:195], v[116:119]
	v_mfma_f32_16x16x32_bf16 v[112:115], v[152:155], v[192:195], v[112:115]
	v_mfma_f32_16x16x32_bf16 v[108:111], v[144:147], v[200:203], v[108:111]
	v_mfma_f32_16x16x32_bf16 v[104:107], v[152:155], v[200:203], v[104:107]
	v_mfma_f32_16x16x32_bf16 v[100:103], v[144:147], v[208:211], v[100:103]
	v_mfma_f32_16x16x32_bf16 v[96:99], v[152:155], v[208:211], v[96:99]
	v_mfma_f32_16x16x32_bf16 v[60:63], v[156:159], v[172:175], v[60:63]
	v_mfma_f32_16x16x32_bf16 v[56:59], v[164:167], v[172:175], v[56:59]
	v_mfma_f32_16x16x32_bf16 v[52:55], v[156:159], v[188:191], v[52:55]
	v_mfma_f32_16x16x32_bf16 v[48:51], v[164:167], v[188:191], v[48:51]
	v_mfma_f32_16x16x32_bf16 v[44:47], v[156:159], v[196:199], v[44:47]
	v_mfma_f32_16x16x32_bf16 v[40:43], v[164:167], v[196:199], v[40:43]
	v_mfma_f32_16x16x32_bf16 v[36:39], v[156:159], v[204:207], v[36:39]
	v_mfma_f32_16x16x32_bf16 v[32:35], v[164:167], v[204:207], v[32:35]
	v_mfma_f32_16x16x32_bf16 v[60:63], v[160:163], v[176:179], v[60:63]
	v_mfma_f32_16x16x32_bf16 v[56:59], v[168:171], v[176:179], v[56:59]
	v_mfma_f32_16x16x32_bf16 v[52:55], v[160:163], v[192:195], v[52:55]
	v_mfma_f32_16x16x32_bf16 v[48:51], v[168:171], v[192:195], v[48:51]
	v_mfma_f32_16x16x32_bf16 v[44:47], v[160:163], v[200:203], v[44:47]
	v_mfma_f32_16x16x32_bf16 v[40:43], v[168:171], v[200:203], v[40:43]
	v_mfma_f32_16x16x32_bf16 v[36:39], v[160:163], v[208:211], v[36:39]
	v_mfma_f32_16x16x32_bf16 v[32:35], v[168:171], v[208:211], v[32:35]
	s_setprio 0
	s_barrier
	s_add_i32 s42, s57, s61
	v_lshl_add_u64 v[180:181], s[46:47], 0, v[130:131]
	s_mov_b32 m0, s42
	ds_read_b128 v[172:175], v187 offset:16384
	ds_read_b128 v[176:179], v187 offset:17408
	ds_read_b128 v[188:191], v187 offset:18432
	ds_read_b128 v[192:195], v187 offset:19456
	ds_read_b128 v[196:199], v187 offset:20480
	ds_read_b128 v[200:203], v187 offset:21504
	ds_read_b128 v[204:207], v187 offset:22528
	ds_read_b128 v[208:211], v187 offset:23552
	global_load_lds_dwordx4 v[180:181], off
	s_add_i32 m0, s42, 0x2000
	s_add_u32 s42, s46, 0xb0000
	v_lshl_add_u64 v[212:213], s[46:47], 0, v[134:135]
	s_addc_u32 s43, s47, 0
	s_add_i32 s68, s58, s61
	global_load_lds_dwordx4 v[212:213], off
	v_lshl_add_u64 v[214:215], s[42:43], 0, v[130:131]
	s_mov_b32 m0, s68
	v_lshl_add_u64 v[216:217], s[48:49], 0, v[132:133]
	global_load_lds_dwordx4 v[214:215], off
	v_lshl_add_u64 v[214:215], s[42:43], 0, v[134:135]
	s_add_i32 m0, s68, 0x2000
	s_nop 0
	global_load_lds_dwordx4 v[214:215], off
	v_lshl_add_u64 v[214:215], s[48:49], 0, v[128:129]
	s_mov_b32 m0, s39
	s_nop 0
	global_load_lds_dwordx4 v[214:215], off
	s_mov_b32 m0, s40
	s_nop 0
	global_load_lds_dwordx4 v[216:217], off
	s_waitcnt vmcnt(8)
	s_waitcnt lgkmcnt(0)
	s_barrier
; #define PG8_STAGE(bufoff, gbase, voff) do { _Pragma("unroll") for (int _i = 0; _i < 2; ++_i) \
;         __builtin_amdgcn_global_load_lds((const unsigned*)((const char*)(gbase) + (voff)[_i]), (LAS unsigned*)(lds + (bufoff) + ldsw + _i * 8192), 16, 0, 0); } while (0)
; #define PG8_LDA(dst, b, h) do { _Pragma("unroll") for (int m = 0; m < 4; ++m) _Pragma("unroll") for (int k = 0; k < 2; ++k) dst[m][k] = *(const LAS bf16x8*)(lds + PG8_SA(b, h) + aoff + m * 2048 + k * 1024); } while (0)
; #define PG8_LDB(dst, b, h) do { _Pragma("unroll") for (int n = 0; n < 2; ++n) _Pragma("unroll") for (int k = 0; k < 2; ++k) dst[n][k] = *(const LAS bf16x8*)(lds + PG8_SB(b, h) + boff + n * 2048 + k * 1024); } while (0)
; #define PG8_MMA(ai, bj, At, Bt) do { __builtin_amdgcn_s_setprio(1); _Pragma("unroll") for (int m = 0; m < 4; ++m) _Pragma("unroll") for (int n = 0; n < 2; ++n) _Pragma("unroll") for (int k = 0; k < 2; ++k) \
;         acc[ai][bj][m][n] = __builtin_amdgcn_mfma_f32_16x16x32_bf16(Bt[n][k], At[m][k], acc[ai][bj][m][n], 0, 0, 0); __builtin_amdgcn_s_setprio(0); } while (0)
; #define PG8_WAIT_V(n) asm volatile("s_waitcnt vmcnt(" #n ")" ::: "memory")
; #define PG8_WAIT_L(n) asm volatile("s_waitcnt lgkmcnt(" #n ")" ::: "memory")
; #define PG8_BAR __builtin_amdgcn_s_barrier()
; #define PG8_SCHED __builtin_amdgcn_sched_barrier(0)
; template <class Epi, bool ALIGN_EPI = true, bool SP2 = true>
; __device__ __forceinline__ void gemm_phase(LAS unsigned char* lds, const Gemm g, const StaticOrder& S, const Epi& E, const int wave_s) {
;     ...
;             PG8_WAIT_V(8); PG8_WAIT_L(0); PG8_BAR; PG8_MMA(1, 0, At, B0); PG8_MMA(1, 1, At, B1); PG8_BAR; PG8_SCHED;
;             PG8_LDB(B0, 1, 0); PG8_LDB(B1, 1, 1); PG8_SCHED; PG8_LDA(At, 1, 0); PG8_STAGE(PG8_SA(0, 1), a2 + hstep, voffA);
;             PG8_WAIT_V(8); PG8_WAIT_L(0); PG8_BAR; PG8_MMA(0, 0, At, B0); PG8_MMA(0, 1, At, B1); PG8_BAR; PG8_SCHED;
	s_setprio 1
	s_waitcnt lgkmcnt(0)
	v_mfma_f32_16x16x32_bf16 v[92:95], v[140:143], v[172:175], v[92:95]
	v_mfma_f32_16x16x32_bf16 v[88:91], v[148:151], v[172:175], v[88:91]
	v_mfma_f32_16x16x32_bf16 v[84:87], v[140:143], v[188:191], v[84:87]
	v_mfma_f32_16x16x32_bf16 v[80:83], v[148:151], v[188:191], v[80:83]
	v_mfma_f32_16x16x32_bf16 v[76:79], v[140:143], v[196:199], v[76:79]
	v_mfma_f32_16x16x32_bf16 v[72:75], v[148:151], v[196:199], v[72:75]
	v_mfma_f32_16x16x32_bf16 v[68:71], v[140:143], v[204:207], v[68:71]
	v_mfma_f32_16x16x32_bf16 v[64:67], v[148:151], v[204:207], v[64:67]
	v_mfma_f32_16x16x32_bf16 v[92:95], v[144:147], v[176:179], v[92:95]
	v_mfma_f32_16x16x32_bf16 v[88:91], v[152:155], v[176:179], v[88:91]
	v_mfma_f32_16x16x32_bf16 v[84:87], v[144:147], v[192:195], v[84:87]
	v_mfma_f32_16x16x32_bf16 v[80:83], v[152:155], v[192:195], v[80:83]
	v_mfma_f32_16x16x32_bf16 v[76:79], v[144:147], v[200:203], v[76:79]
	v_mfma_f32_16x16x32_bf16 v[72:75], v[152:155], v[200:203], v[72:75]
	v_mfma_f32_16x16x32_bf16 v[68:71], v[144:147], v[208:211], v[68:71]
	v_mfma_f32_16x16x32_bf16 v[64:67], v[152:155], v[208:211], v[64:67]
	v_mfma_f32_16x16x32_bf16 v[28:31], v[156:159], v[172:175], v[28:31]
	v_mfma_f32_16x16x32_bf16 v[24:27], v[164:167], v[172:175], v[24:27]
	v_mfma_f32_16x16x32_bf16 v[20:23], v[156:159], v[188:191], v[20:23]
	v_mfma_f32_16x16x32_bf16 v[16:19], v[164:167], v[188:191], v[16:19]
	v_mfma_f32_16x16x32_bf16 v[12:15], v[156:159], v[196:199], v[12:15]
	v_mfma_f32_16x16x32_bf16 v[8:11], v[164:167], v[196:199], v[8:11]
	v_mfma_f32_16x16x32_bf16 v[4:7], v[156:159], v[204:207], v[4:7]
	v_mfma_f32_16x16x32_bf16 v[0:3], v[164:167], v[204:207], v[0:3]
	v_mfma_f32_16x16x32_bf16 v[28:31], v[160:163], v[176:179], v[28:31]
	v_mfma_f32_16x16x32_bf16 v[24:27], v[168:171], v[176:179], v[24:27]
	v_mfma_f32_16x16x32_bf16 v[20:23], v[160:163], v[192:195], v[20:23]
	v_mfma_f32_16x16x32_bf16 v[16:19], v[168:171], v[192:195], v[16:19]
	v_mfma_f32_16x16x32_bf16 v[12:15], v[160:163], v[200:203], v[12:15]
	v_mfma_f32_16x16x32_bf16 v[8:11], v[168:171], v[200:203], v[8:11]
	v_mfma_f32_16x16x32_bf16 v[4:7], v[160:163], v[208:211], v[4:7]
	v_mfma_f32_16x16x32_bf16 v[0:3], v[168:171], v[208:211], v[0:3]
	s_setprio 0
	s_barrier
	s_add_i32 s68, 0, 0x18000
	s_add_i32 s69, 0, 0x1c000
	v_add_u32_e32 v152, s68, v183
	v_add_u32_e32 v168, s69, v183
	ds_read_b128 v[140:143], v152
	ds_read_b128 v[144:147], v152 offset:1024
	ds_read_b128 v[148:151], v152 offset:2048
	ds_read_b128 v[152:155], v152 offset:3072
	ds_read_b128 v[156:159], v168
	ds_read_b128 v[160:163], v168 offset:1024
	ds_read_b128 v[164:167], v168 offset:2048
	ds_read_b128 v[168:171], v168 offset:3072
	s_add_u32 s42, s48, 0xb0000
	s_addc_u32 s43, s49, 0
	s_mov_b32 m0, s41
	v_lshl_add_u64 v[218:219], s[42:43], 0, v[128:129]
	ds_read_b128 v[172:175], v187 offset:32768
	ds_read_b128 v[176:179], v187 offset:33792
	ds_read_b128 v[188:191], v187 offset:34816
	ds_read_b128 v[192:195], v187 offset:35840
	ds_read_b128 v[196:199], v187 offset:36864
	ds_read_b128 v[200:203], v187 offset:37888
	ds_read_b128 v[204:207], v187 offset:38912
	ds_read_b128 v[208:211], v187 offset:39936
	global_load_lds_dwordx4 v[218:219], off
	v_lshl_add_u64 v[218:219], s[42:43], 0, v[132:133]
	s_mov_b32 m0, s50
	s_nop 0
	global_load_lds_dwordx4 v[218:219], off
	s_waitcnt vmcnt(8)
	s_waitcnt lgkmcnt(0)
	s_barrier
	s_setprio 1
	s_waitcnt lgkmcnt(0)
	v_mfma_f32_16x16x32_bf16 v[124:127], v[140:143], v[172:175], v[124:127]
	v_mfma_f32_16x16x32_bf16 v[120:123], v[148:151], v[172:175], v[120:123]
	v_mfma_f32_16x16x32_bf16 v[116:119], v[140:143], v[188:191], v[116:119]
	v_mfma_f32_16x16x32_bf16 v[112:115], v[148:151], v[188:191], v[112:115]
	v_mfma_f32_16x16x32_bf16 v[108:111], v[140:143], v[196:199], v[108:111]
	v_mfma_f32_16x16x32_bf16 v[104:107], v[148:151], v[196:199], v[104:107]
	v_mfma_f32_16x16x32_bf16 v[100:103], v[140:143], v[204:207], v[100:103]
	v_mfma_f32_16x16x32_bf16 v[96:99], v[148:151], v[204:207], v[96:99]
	v_mfma_f32_16x16x32_bf16 v[124:127], v[144:147], v[176:179], v[124:127]
	v_mfma_f32_16x16x32_bf16 v[120:123], v[152:155], v[176:179], v[120:123]
	v_mfma_f32_16x16x32_bf16 v[116:119], v[144:147], v[192:195], v[116:119]
	v_mfma_f32_16x16x32_bf16 v[112:115], v[152:155], v[192:195], v[112:115]
	v_mfma_f32_16x16x32_bf16 v[108:111], v[144:147], v[200:203], v[108:111]
	v_mfma_f32_16x16x32_bf16 v[104:107], v[152:155], v[200:203], v[104:107]
	v_mfma_f32_16x16x32_bf16 v[100:103], v[144:147], v[208:211], v[100:103]
	v_mfma_f32_16x16x32_bf16 v[96:99], v[152:155], v[208:211], v[96:99]
	v_mfma_f32_16x16x32_bf16 v[60:63], v[156:159], v[172:175], v[60:63]
	v_mfma_f32_16x16x32_bf16 v[56:59], v[164:167], v[172:175], v[56:59]
	v_mfma_f32_16x16x32_bf16 v[52:55], v[156:159], v[188:191], v[52:55]
	v_mfma_f32_16x16x32_bf16 v[48:51], v[164:167], v[188:191], v[48:51]
	v_mfma_f32_16x16x32_bf16 v[44:47], v[156:159], v[196:199], v[44:47]
	v_mfma_f32_16x16x32_bf16 v[40:43], v[164:167], v[196:199], v[40:43]
	v_mfma_f32_16x16x32_bf16 v[36:39], v[156:159], v[204:207], v[36:39]
	v_mfma_f32_16x16x32_bf16 v[32:35], v[164:167], v[204:207], v[32:35]
	v_mfma_f32_16x16x32_bf16 v[60:63], v[160:163], v[176:179], v[60:63]
	v_mfma_f32_16x16x32_bf16 v[56:59], v[168:171], v[176:179], v[56:59]
	v_mfma_f32_16x16x32_bf16 v[52:55], v[160:163], v[192:195], v[52:55]
	v_mfma_f32_16x16x32_bf16 v[48:51], v[168:171], v[192:195], v[48:51]
	v_mfma_f32_16x16x32_bf16 v[44:47], v[160:163], v[200:203], v[44:47]
	v_mfma_f32_16x16x32_bf16 v[40:43], v[168:171], v[200:203], v[40:43]
	v_mfma_f32_16x16x32_bf16 v[36:39], v[160:163], v[208:211], v[36:39]
	v_mfma_f32_16x16x32_bf16 v[32:35], v[168:171], v[208:211], v[32:35]
	s_setprio 0
	s_barrier
; #define PG8_STAGE(bufoff, gbase, voff) do { _Pragma("unroll") for (int _i = 0; _i < 2; ++_i) \
;         __builtin_amdgcn_global_load_lds((const unsigned*)((const char*)(gbase) + (voff)[_i]), (LAS unsigned*)(lds + (bufoff) + ldsw + _i * 8192), 16, 0, 0); } while (0)
; #define PG8_LDA(dst, b, h) do { _Pragma("unroll") for (int m = 0; m < 4; ++m) _Pragma("unroll") for (int k = 0; k < 2; ++k) dst[m][k] = *(const LAS bf16x8*)(lds + PG8_SA(b, h) + aoff + m * 2048 + k * 1024); } while (0)
; #define PG8_MMA(ai, bj, At, Bt) do { __builtin_amdgcn_s_setprio(1); _Pragma("unroll") for (int m = 0; m < 4; ++m) _Pragma("unroll") for (int n = 0; n < 2; ++n) _Pragma("unroll") for (int k = 0; k < 2; ++k) \
;         acc[ai][bj][m][n] = __builtin_amdgcn_mfma_f32_16x16x32_bf16(Bt[n][k], At[m][k], acc[ai][bj][m][n], 0, 0, 0); __builtin_amdgcn_s_setprio(0); } while (0)
; #define PG8_WAIT_V(n) asm volatile("s_waitcnt vmcnt(" #n ")" ::: "memory")
; #define PG8_WAIT_L(n) asm volatile("s_waitcnt lgkmcnt(" #n ")" ::: "memory")
; #define PG8_BAR __builtin_amdgcn_s_barrier()
; #define PG8_SCHED __builtin_amdgcn_sched_barrier(0)
; template <class Epi, bool ALIGN_EPI = true, bool SP2 = true>
; __device__ __forceinline__ void gemm_phase(LAS unsigned char* lds, const Gemm g, const StaticOrder& S, const Epi& E, const int wave_s) {
;     ...
;         for (int t = 0; t < nt; t += 2) {
;             const bool last = (t == nt - 2);
;             const char* a1 = cA + (size_t)(t + 1) * kstep;
;             const char* a2 = last ? nA : cA + (size_t)(t + 2) * kstep; const char* b2 = last ? nB : cB + (size_t)(t + 2) * kstep;
;     ...
;             PG8_LDA(At, 1, 1); PG8_STAGE(PG8_SB(1, 0), b3, voffB); PG8_STAGE(PG8_SB(1, 1), b3 + hstep, voffB); PG8_STAGE(PG8_SA(1, 0), a3, voffA);
;             PG8_WAIT_V(8); PG8_WAIT_L(0); PG8_BAR; PG8_MMA(1, 0, At, B0); PG8_MMA(1, 1, At, B1); PG8_BAR; PG8_SCHED;
	s_add_i32 s42, s68, s61
	v_lshl_add_u64 v[180:181], v[180:181], 0, s[22:23]
	s_mov_b32 m0, s42
	ds_read_b128 v[172:175], v187 offset:49152
	ds_read_b128 v[176:179], v187 offset:50176
	ds_read_b128 v[188:191], v187 offset:51200
	ds_read_b128 v[192:195], v187 offset:52224
	ds_read_b128 v[196:199], v187 offset:53248
	ds_read_b128 v[200:203], v187 offset:54272
	ds_read_b128 v[204:207], v187 offset:55296
	ds_read_b128 v[208:211], v187 offset:56320
	global_load_lds_dwordx4 v[180:181], off
	s_add_i32 m0, s42, 0x2000
	s_add_u32 s42, s46, 0xb0080
	v_lshl_add_u64 v[180:181], v[212:213], 0, s[22:23]
	s_addc_u32 s43, s47, 0
	s_add_i32 s46, s69, s61
	global_load_lds_dwordx4 v[180:181], off
	v_lshl_add_u64 v[180:181], s[42:43], 0, v[130:131]
	s_mov_b32 m0, s46
	s_nop 0
	global_load_lds_dwordx4 v[180:181], off
	v_lshl_add_u64 v[180:181], s[42:43], 0, v[134:135]
	s_add_i32 m0, s46, 0x2000
	s_nop 0
	global_load_lds_dwordx4 v[180:181], off
	v_lshl_add_u64 v[180:181], v[214:215], 0, s[22:23]
	s_mov_b32 m0, s54
	s_nop 0
	global_load_lds_dwordx4 v[180:181], off
	v_lshl_add_u64 v[180:181], v[216:217], 0, s[22:23]
	s_mov_b32 m0, s55
	s_nop 0
	global_load_lds_dwordx4 v[180:181], off
	s_waitcnt vmcnt(8)
	s_waitcnt lgkmcnt(0)
	s_barrier
	s_setprio 1
	s_waitcnt lgkmcnt(0)
	v_mfma_f32_16x16x32_bf16 v[92:95], v[140:143], v[172:175], v[92:95]
	v_mfma_f32_16x16x32_bf16 v[88:91], v[148:151], v[172:175], v[88:91]
	v_mfma_f32_16x16x32_bf16 v[84:87], v[140:143], v[188:191], v[84:87]
	v_mfma_f32_16x16x32_bf16 v[80:83], v[148:151], v[188:191], v[80:83]
	v_mfma_f32_16x16x32_bf16 v[76:79], v[140:143], v[196:199], v[76:79]
	v_mfma_f32_16x16x32_bf16 v[72:75], v[148:151], v[196:199], v[72:75]
	v_mfma_f32_16x16x32_bf16 v[68:71], v[140:143], v[204:207], v[68:71]
	v_mfma_f32_16x16x32_bf16 v[64:67], v[148:151], v[204:207], v[64:67]
	v_mfma_f32_16x16x32_bf16 v[92:95], v[144:147], v[176:179], v[92:95]
	v_mfma_f32_16x16x32_bf16 v[88:91], v[152:155], v[176:179], v[88:91]
	v_mfma_f32_16x16x32_bf16 v[84:87], v[144:147], v[192:195], v[84:87]
	v_mfma_f32_16x16x32_bf16 v[80:83], v[152:155], v[192:195], v[80:83]
	v_mfma_f32_16x16x32_bf16 v[76:79], v[144:147], v[200:203], v[76:79]
	v_mfma_f32_16x16x32_bf16 v[72:75], v[152:155], v[200:203], v[72:75]
	v_mfma_f32_16x16x32_bf16 v[68:71], v[144:147], v[208:211], v[68:71]
	v_mfma_f32_16x16x32_bf16 v[64:67], v[152:155], v[208:211], v[64:67]
	v_mfma_f32_16x16x32_bf16 v[28:31], v[156:159], v[172:175], v[28:31]
	v_mfma_f32_16x16x32_bf16 v[24:27], v[164:167], v[172:175], v[24:27]
	v_mfma_f32_16x16x32_bf16 v[20:23], v[156:159], v[188:191], v[20:23]
	v_mfma_f32_16x16x32_bf16 v[16:19], v[164:167], v[188:191], v[16:19]
	v_mfma_f32_16x16x32_bf16 v[12:15], v[156:159], v[196:199], v[12:15]
	v_mfma_f32_16x16x32_bf16 v[8:11], v[164:167], v[196:199], v[8:11]
	v_mfma_f32_16x16x32_bf16 v[4:7], v[156:159], v[204:207], v[4:7]
	v_mfma_f32_16x16x32_bf16 v[0:3], v[164:167], v[204:207], v[0:3]
	v_mfma_f32_16x16x32_bf16 v[28:31], v[160:163], v[176:179], v[28:31]
	v_mfma_f32_16x16x32_bf16 v[24:27], v[168:171], v[176:179], v[24:27]
	v_mfma_f32_16x16x32_bf16 v[20:23], v[160:163], v[192:195], v[20:23]
	v_mfma_f32_16x16x32_bf16 v[16:19], v[168:171], v[192:195], v[16:19]
	v_mfma_f32_16x16x32_bf16 v[12:15], v[160:163], v[200:203], v[12:15]
	v_mfma_f32_16x16x32_bf16 v[8:11], v[168:171], v[200:203], v[8:11]
	v_mfma_f32_16x16x32_bf16 v[4:7], v[160:163], v[208:211], v[4:7]
	v_mfma_f32_16x16x32_bf16 v[0:3], v[168:171], v[208:211], v[0:3]
	s_setprio 0
	s_barrier
	s_add_i32 s66, s66, 2
	s_add_u32 s64, s64, 0x100
	s_addc_u32 s65, s65, 0
	s_cmp_gt_u32 s66, 41
	s_mov_b64 s[42:43], s[44:45]
	s_cbranch_scc0 .LBB0_690
	s_and_b64 vcc, exec, s[24:25]
	s_cbranch_vccz .LBB0_693
	s_barrier

; #define PG8_STAGE(bufoff, gbase, voff) do { _Pragma("unroll") for (int _i = 0; _i < 2; ++_i) \
;         __builtin_amdgcn_global_load_lds((const unsigned*)((const char*)(gbase) + (voff)[_i]), (LAS unsigned*)(lds + (bufoff) + ldsw + _i * 8192), 16, 0, 0); } while (0)
; #define PG8_LDA(dst, b, h) do { _Pragma("unroll") for (int m = 0; m < 4; ++m) _Pragma("unroll") for (int k = 0; k < 2; ++k) dst[m][k] = *(const LAS bf16x8*)(lds + PG8_SA(b, h) + aoff + m * 2048 + k * 1024); } while (0)
; #define PG8_LDB(dst, b, h) do { _Pragma("unroll") for (int n = 0; n < 2; ++n) _Pragma("unroll") for (int k = 0; k < 2; ++k) dst[n][k] = *(const LAS bf16x8*)(lds + PG8_SB(b, h) + boff + n * 2048 + k * 1024); } while (0)
; #define PG8_MMA(ai, bj, At, Bt) do { __builtin_amdgcn_s_setprio(1); _Pragma("unroll") for (int m = 0; m < 4; ++m) _Pragma("unroll") for (int n = 0; n < 2; ++n) _Pragma("unroll") for (int k = 0; k < 2; ++k) \
;         acc[ai][bj][m][n] = __builtin_amdgcn_mfma_f32_16x16x32_bf16(Bt[n][k], At[m][k], acc[ai][bj][m][n], 0, 0, 0); __builtin_amdgcn_s_setprio(0); } while (0)
; #define PG8_WAIT_V(n) asm volatile("s_waitcnt vmcnt(" #n ")" ::: "memory")
; #define PG8_WAIT_L(n) asm volatile("s_waitcnt lgkmcnt(" #n ")" ::: "memory")
; #define PG8_BAR __builtin_amdgcn_s_barrier()
; #define PG8_SCHED __builtin_amdgcn_sched_barrier(0)
; template <class Epi, bool ALIGN_EPI = true, bool SP2 = true>
; __device__ __forceinline__ void gemm_phase(LAS unsigned char* lds, const Gemm g, const StaticOrder& S, const Epi& E, const int wave_s) {
;     ...
;             PG8_LDB(B0, 0, 0); PG8_LDB(B1, 0, 1); PG8_SCHED; PG8_LDA(At, 0, 0); PG8_STAGE(PG8_SA(1, 1), a1 + hstep, voffA);
;             PG8_WAIT_V(8); PG8_WAIT_L(0); PG8_BAR; PG8_MMA(0, 0, At, B0); PG8_MMA(0, 1, At, B1); PG8_BAR; PG8_SCHED;
;             PG8_LDA(At, 0, 1); PG8_STAGE(PG8_SB(0, 0), b2, voffB); PG8_STAGE(PG8_SB(0, 1), b2 + hstep, voffB); PG8_STAGE(PG8_SA(0, 0), a2, voffA);
;             PG8_WAIT_V(8); PG8_WAIT_L(0); PG8_BAR; PG8_MMA(1, 0, At, B0); PG8_MMA(1, 1, At, B1); PG8_BAR; PG8_SCHED;
.LBB0_829:
	ds_read_b128 v[144:147], v151
	ds_read_b128 v[154:157], v151 offset:1024
	ds_read_b128 v[158:161], v151 offset:2048
	ds_read_b128 v[162:165], v151 offset:3072
	ds_read_b128 v[166:169], v152
	ds_read_b128 v[170:173], v152 offset:1024
	ds_read_b128 v[174:177], v152 offset:2048
	ds_read_b128 v[178:181], v152 offset:3072
	s_add_u32 s28, s26, 0xfffc0080
	s_addc_u32 s29, s27, -1
	s_cmp_eq_u32 s52, 12
	s_cselect_b32 s31, s19, s29
	s_cselect_b32 s30, s48, s28
	s_cselect_b32 s29, s17, s51
	s_cselect_b32 s28, s49, s50
	v_lshl_add_u64 v[214:215], s[26:27], 0, v[138:139]
	s_add_i32 m0, s25, 0xc000
	ds_read_b128 v[182:185], v153
	ds_read_b128 v[186:189], v153 offset:1024
	ds_read_b128 v[190:193], v153 offset:2048
	ds_read_b128 v[194:197], v153 offset:3072
	ds_read_b128 v[198:201], v153 offset:4096
	ds_read_b128 v[202:205], v153 offset:5120
	ds_read_b128 v[206:209], v153 offset:6144
	ds_read_b128 v[210:213], v153 offset:7168
	global_load_lds_dwordx4 v[214:215], off
	v_lshl_add_u64 v[214:215], s[26:27], 0, v[136:137]
	s_add_i32 m0, s25, 0xe000
	s_nop 0
	global_load_lds_dwordx4 v[214:215], off
	s_waitcnt vmcnt(8)
	s_waitcnt lgkmcnt(0)
	s_barrier
	s_setprio 1
	s_waitcnt lgkmcnt(0)
	v_mfma_f32_16x16x32_bf16 v[124:127], v[144:147], v[182:185], v[124:127]
	v_mfma_f32_16x16x32_bf16 v[120:123], v[158:161], v[182:185], v[120:123]
	v_mfma_f32_16x16x32_bf16 v[116:119], v[144:147], v[190:193], v[116:119]
	v_mfma_f32_16x16x32_bf16 v[108:111], v[158:161], v[190:193], v[108:111]
	v_mfma_f32_16x16x32_bf16 v[100:103], v[144:147], v[198:201], v[100:103]
	v_mfma_f32_16x16x32_bf16 v[92:95], v[158:161], v[198:201], v[92:95]
	v_mfma_f32_16x16x32_bf16 v[84:87], v[144:147], v[206:209], v[84:87]
	v_mfma_f32_16x16x32_bf16 v[76:79], v[158:161], v[206:209], v[76:79]
	v_mfma_f32_16x16x32_bf16 v[124:127], v[154:157], v[186:189], v[124:127]
	v_mfma_f32_16x16x32_bf16 v[120:123], v[162:165], v[186:189], v[120:123]
	v_mfma_f32_16x16x32_bf16 v[116:119], v[154:157], v[194:197], v[116:119]
	v_mfma_f32_16x16x32_bf16 v[108:111], v[162:165], v[194:197], v[108:111]
	v_mfma_f32_16x16x32_bf16 v[100:103], v[154:157], v[202:205], v[100:103]
	v_mfma_f32_16x16x32_bf16 v[92:95], v[162:165], v[202:205], v[92:95]
	v_mfma_f32_16x16x32_bf16 v[84:87], v[154:157], v[210:213], v[84:87]
	v_mfma_f32_16x16x32_bf16 v[76:79], v[162:165], v[210:213], v[76:79]
	v_mfma_f32_16x16x32_bf16 v[112:115], v[166:169], v[182:185], v[112:115]
	v_mfma_f32_16x16x32_bf16 v[104:107], v[174:177], v[182:185], v[104:107]
	v_mfma_f32_16x16x32_bf16 v[96:99], v[166:169], v[190:193], v[96:99]
	v_mfma_f32_16x16x32_bf16 v[88:91], v[174:177], v[190:193], v[88:91]
	v_mfma_f32_16x16x32_bf16 v[80:83], v[166:169], v[198:201], v[80:83]
	v_mfma_f32_16x16x32_bf16 v[72:75], v[174:177], v[198:201], v[72:75]
	v_mfma_f32_16x16x32_bf16 v[68:71], v[166:169], v[206:209], v[68:71]
	v_mfma_f32_16x16x32_bf16 v[64:67], v[174:177], v[206:209], v[64:67]
	v_mfma_f32_16x16x32_bf16 v[112:115], v[170:173], v[186:189], v[112:115]
	v_mfma_f32_16x16x32_bf16 v[104:107], v[178:181], v[186:189], v[104:107]
	v_mfma_f32_16x16x32_bf16 v[96:99], v[170:173], v[194:197], v[96:99]
	v_mfma_f32_16x16x32_bf16 v[88:91], v[178:181], v[194:197], v[88:91]
	v_mfma_f32_16x16x32_bf16 v[80:83], v[170:173], v[202:205], v[80:83]
	v_mfma_f32_16x16x32_bf16 v[72:75], v[178:181], v[202:205], v[72:75]
	v_mfma_f32_16x16x32_bf16 v[68:71], v[170:173], v[210:213], v[68:71]
	v_mfma_f32_16x16x32_bf16 v[64:67], v[178:181], v[210:213], v[64:67]
	s_setprio 0
	s_barrier
	s_add_i32 s53, s44, s61
	v_lshl_add_u64 v[214:215], s[28:29], 0, v[132:133]
	s_mov_b32 m0, s53
	ds_read_b128 v[182:185], v153 offset:16384
	ds_read_b128 v[186:189], v153 offset:17408
	ds_read_b128 v[190:193], v153 offset:18432
	ds_read_b128 v[194:197], v153 offset:19456
	ds_read_b128 v[198:201], v153 offset:20480
	ds_read_b128 v[202:205], v153 offset:21504
	ds_read_b128 v[206:209], v153 offset:22528
	ds_read_b128 v[210:213], v153 offset:23552
	global_load_lds_dwordx4 v[214:215], off
	s_add_i32 m0, s53, 0x2000
	s_add_u32 s54, s28, 0x40000
	v_lshl_add_u64 v[216:217], s[28:29], 0, v[128:129]
	s_addc_u32 s55, s29, 0
	s_add_i32 s53, s45, s61
	global_load_lds_dwordx4 v[216:217], off
	v_lshl_add_u64 v[218:219], s[54:55], 0, v[132:133]
	s_mov_b32 m0, s53
	v_lshl_add_u64 v[220:221], s[30:31], 0, v[130:131]
	global_load_lds_dwordx4 v[218:219], off
	v_lshl_add_u64 v[218:219], s[54:55], 0, v[128:129]
	s_add_i32 m0, s53, 0x2000
	s_nop 0
	global_load_lds_dwordx4 v[218:219], off
	v_lshl_add_u64 v[218:219], s[30:31], 0, v[134:135]
	s_mov_b32 m0, s25
	s_nop 0
	global_load_lds_dwordx4 v[218:219], off
	s_mov_b32 m0, s37
	s_nop 0
	global_load_lds_dwordx4 v[220:221], off
	s_waitcnt vmcnt(8)
	s_waitcnt lgkmcnt(0)
	s_barrier
; #define PG8_STAGE(bufoff, gbase, voff) do { _Pragma("unroll") for (int _i = 0; _i < 2; ++_i) \
;         __builtin_amdgcn_global_load_lds((const unsigned*)((const char*)(gbase) + (voff)[_i]), (LAS unsigned*)(lds + (bufoff) + ldsw + _i * 8192), 16, 0, 0); } while (0)
; #define PG8_LDA(dst, b, h) do { _Pragma("unroll") for (int m = 0; m < 4; ++m) _Pragma("unroll") for (int k = 0; k < 2; ++k) dst[m][k] = *(const LAS bf16x8*)(lds + PG8_SA(b, h) + aoff + m * 2048 + k * 1024); } while (0)
; #define PG8_LDB(dst, b, h) do { _Pragma("unroll") for (int n = 0; n < 2; ++n) _Pragma("unroll") for (int k = 0; k < 2; ++k) dst[n][k] = *(const LAS bf16x8*)(lds + PG8_SB(b, h) + boff + n * 2048 + k * 1024); } while (0)
; #define PG8_MMA(ai, bj, At, Bt) do { __builtin_amdgcn_s_setprio(1); _Pragma("unroll") for (int m = 0; m < 4; ++m) _Pragma("unroll") for (int n = 0; n < 2; ++n) _Pragma("unroll") for (int k = 0; k < 2; ++k) \
;         acc[ai][bj][m][n] = __builtin_amdgcn_mfma_f32_16x16x32_bf16(Bt[n][k], At[m][k], acc[ai][bj][m][n], 0, 0, 0); __builtin_amdgcn_s_setprio(0); } while (0)
; #define PG8_WAIT_V(n) asm volatile("s_waitcnt vmcnt(" #n ")" ::: "memory")
; #define PG8_WAIT_L(n) asm volatile("s_waitcnt lgkmcnt(" #n ")" ::: "memory")
; #define PG8_BAR __builtin_amdgcn_s_barrier()
; #define PG8_SCHED __builtin_amdgcn_sched_barrier(0)
; template <class Epi, bool ALIGN_EPI = true, bool SP2 = true>
; __device__ __forceinline__ void gemm_phase(LAS unsigned char* lds, const Gemm g, const StaticOrder& S, const Epi& E, const int wave_s) {
;     ...
;             PG8_WAIT_V(8); PG8_WAIT_L(0); PG8_BAR; PG8_MMA(1, 0, At, B0); PG8_MMA(1, 1, At, B1); PG8_BAR; PG8_SCHED;
;             PG8_LDB(B0, 1, 0); PG8_LDB(B1, 1, 1); PG8_SCHED; PG8_LDA(At, 1, 0); PG8_STAGE(PG8_SA(0, 1), a2 + hstep, voffA);
;             PG8_WAIT_V(8); PG8_WAIT_L(0); PG8_BAR; PG8_MMA(0, 0, At, B0); PG8_MMA(0, 1, At, B1); PG8_BAR; PG8_SCHED;
	s_setprio 1
	s_waitcnt lgkmcnt(0)
	v_mfma_f32_16x16x32_bf16 v[60:63], v[144:147], v[182:185], v[60:63]
	v_mfma_f32_16x16x32_bf16 v[56:59], v[158:161], v[182:185], v[56:59]
	v_mfma_f32_16x16x32_bf16 v[52:55], v[144:147], v[190:193], v[52:55]
	v_mfma_f32_16x16x32_bf16 v[44:47], v[158:161], v[190:193], v[44:47]
	v_mfma_f32_16x16x32_bf16 v[36:39], v[144:147], v[198:201], v[36:39]
	v_mfma_f32_16x16x32_bf16 v[28:31], v[158:161], v[198:201], v[28:31]
	v_mfma_f32_16x16x32_bf16 v[20:23], v[144:147], v[206:209], v[20:23]
	v_mfma_f32_16x16x32_bf16 v[12:15], v[158:161], v[206:209], v[12:15]
	v_mfma_f32_16x16x32_bf16 v[60:63], v[154:157], v[186:189], v[60:63]
	v_mfma_f32_16x16x32_bf16 v[56:59], v[162:165], v[186:189], v[56:59]
	v_mfma_f32_16x16x32_bf16 v[52:55], v[154:157], v[194:197], v[52:55]
	v_mfma_f32_16x16x32_bf16 v[44:47], v[162:165], v[194:197], v[44:47]
	v_mfma_f32_16x16x32_bf16 v[36:39], v[154:157], v[202:205], v[36:39]
	v_mfma_f32_16x16x32_bf16 v[28:31], v[162:165], v[202:205], v[28:31]
	v_mfma_f32_16x16x32_bf16 v[20:23], v[154:157], v[210:213], v[20:23]
	v_mfma_f32_16x16x32_bf16 v[12:15], v[162:165], v[210:213], v[12:15]
	v_mfma_f32_16x16x32_bf16 v[48:51], v[166:169], v[182:185], v[48:51]
	v_mfma_f32_16x16x32_bf16 v[40:43], v[174:177], v[182:185], v[40:43]
	v_mfma_f32_16x16x32_bf16 v[32:35], v[166:169], v[190:193], v[32:35]
	v_mfma_f32_16x16x32_bf16 v[24:27], v[174:177], v[190:193], v[24:27]
	v_mfma_f32_16x16x32_bf16 v[16:19], v[166:169], v[198:201], v[16:19]
	v_mfma_f32_16x16x32_bf16 v[8:11], v[174:177], v[198:201], v[8:11]
	v_mfma_f32_16x16x32_bf16 v[4:7], v[166:169], v[206:209], v[4:7]
	v_mfma_f32_16x16x32_bf16 v[0:3], v[174:177], v[206:209], v[0:3]
	v_mfma_f32_16x16x32_bf16 v[48:51], v[170:173], v[186:189], v[48:51]
	v_mfma_f32_16x16x32_bf16 v[40:43], v[178:181], v[186:189], v[40:43]
	v_mfma_f32_16x16x32_bf16 v[32:35], v[170:173], v[194:197], v[32:35]
	v_mfma_f32_16x16x32_bf16 v[24:27], v[178:181], v[194:197], v[24:27]
	v_mfma_f32_16x16x32_bf16 v[16:19], v[170:173], v[202:205], v[16:19]
	v_mfma_f32_16x16x32_bf16 v[8:11], v[178:181], v[202:205], v[8:11]
	v_mfma_f32_16x16x32_bf16 v[4:7], v[170:173], v[210:213], v[4:7]
	v_mfma_f32_16x16x32_bf16 v[0:3], v[178:181], v[210:213], v[0:3]
	s_setprio 0
	s_barrier
	s_add_i32 s53, 0, 0x18000
	s_add_i32 s54, 0, 0x1c000
	v_add_u32_e32 v162, s53, v149
	v_add_u32_e32 v178, s54, v149
	ds_read_b128 v[144:147], v162
	ds_read_b128 v[154:157], v162 offset:1024
	ds_read_b128 v[158:161], v162 offset:2048
	ds_read_b128 v[162:165], v162 offset:3072
	ds_read_b128 v[166:169], v178
	ds_read_b128 v[170:173], v178 offset:1024
	ds_read_b128 v[174:177], v178 offset:2048
	ds_read_b128 v[178:181], v178 offset:3072
	s_add_u32 s30, s30, 0x40000
	s_addc_u32 s31, s31, 0
	s_mov_b32 m0, s38
	v_lshl_add_u64 v[222:223], s[30:31], 0, v[134:135]
	ds_read_b128 v[182:185], v153 offset:32768
	ds_read_b128 v[186:189], v153 offset:33792
	ds_read_b128 v[190:193], v153 offset:34816
	ds_read_b128 v[194:197], v153 offset:35840
	ds_read_b128 v[198:201], v153 offset:36864
	ds_read_b128 v[202:205], v153 offset:37888
	ds_read_b128 v[206:209], v153 offset:38912
	ds_read_b128 v[210:213], v153 offset:39936
	global_load_lds_dwordx4 v[222:223], off
	v_lshl_add_u64 v[222:223], s[30:31], 0, v[130:131]
	s_mov_b32 m0, s39
	s_nop 0
	global_load_lds_dwordx4 v[222:223], off
	s_waitcnt vmcnt(8)
	s_waitcnt lgkmcnt(0)
	s_barrier
	s_setprio 1
	s_waitcnt lgkmcnt(0)
	v_mfma_f32_16x16x32_bf16 v[124:127], v[144:147], v[182:185], v[124:127]
	v_mfma_f32_16x16x32_bf16 v[120:123], v[158:161], v[182:185], v[120:123]
	v_mfma_f32_16x16x32_bf16 v[116:119], v[144:147], v[190:193], v[116:119]
	v_mfma_f32_16x16x32_bf16 v[108:111], v[158:161], v[190:193], v[108:111]
	v_mfma_f32_16x16x32_bf16 v[100:103], v[144:147], v[198:201], v[100:103]
	v_mfma_f32_16x16x32_bf16 v[92:95], v[158:161], v[198:201], v[92:95]
	v_mfma_f32_16x16x32_bf16 v[84:87], v[144:147], v[206:209], v[84:87]
	v_mfma_f32_16x16x32_bf16 v[76:79], v[158:161], v[206:209], v[76:79]
	v_mfma_f32_16x16x32_bf16 v[124:127], v[154:157], v[186:189], v[124:127]
	v_mfma_f32_16x16x32_bf16 v[120:123], v[162:165], v[186:189], v[120:123]
	v_mfma_f32_16x16x32_bf16 v[116:119], v[154:157], v[194:197], v[116:119]
	v_mfma_f32_16x16x32_bf16 v[108:111], v[162:165], v[194:197], v[108:111]
	v_mfma_f32_16x16x32_bf16 v[100:103], v[154:157], v[202:205], v[100:103]
	v_mfma_f32_16x16x32_bf16 v[92:95], v[162:165], v[202:205], v[92:95]
	v_mfma_f32_16x16x32_bf16 v[84:87], v[154:157], v[210:213], v[84:87]
	v_mfma_f32_16x16x32_bf16 v[76:79], v[162:165], v[210:213], v[76:79]
	v_mfma_f32_16x16x32_bf16 v[112:115], v[166:169], v[182:185], v[112:115]
	v_mfma_f32_16x16x32_bf16 v[104:107], v[174:177], v[182:185], v[104:107]
	v_mfma_f32_16x16x32_bf16 v[96:99], v[166:169], v[190:193], v[96:99]
	v_mfma_f32_16x16x32_bf16 v[88:91], v[174:177], v[190:193], v[88:91]
	v_mfma_f32_16x16x32_bf16 v[80:83], v[166:169], v[198:201], v[80:83]
	v_mfma_f32_16x16x32_bf16 v[72:75], v[174:177], v[198:201], v[72:75]
	v_mfma_f32_16x16x32_bf16 v[68:71], v[166:169], v[206:209], v[68:71]
	v_mfma_f32_16x16x32_bf16 v[64:67], v[174:177], v[206:209], v[64:67]
	v_mfma_f32_16x16x32_bf16 v[112:115], v[170:173], v[186:189], v[112:115]
	v_mfma_f32_16x16x32_bf16 v[104:107], v[178:181], v[186:189], v[104:107]
	v_mfma_f32_16x16x32_bf16 v[96:99], v[170:173], v[194:197], v[96:99]
	v_mfma_f32_16x16x32_bf16 v[88:91], v[178:181], v[194:197], v[88:91]
	v_mfma_f32_16x16x32_bf16 v[80:83], v[170:173], v[202:205], v[80:83]
	v_mfma_f32_16x16x32_bf16 v[72:75], v[178:181], v[202:205], v[72:75]
	v_mfma_f32_16x16x32_bf16 v[68:71], v[170:173], v[210:213], v[68:71]
	v_mfma_f32_16x16x32_bf16 v[64:67], v[178:181], v[210:213], v[64:67]
	s_setprio 0
	s_barrier
; #define PG8_STAGE(bufoff, gbase, voff) do { _Pragma("unroll") for (int _i = 0; _i < 2; ++_i) \
;         __builtin_amdgcn_global_load_lds((const unsigned*)((const char*)(gbase) + (voff)[_i]), (LAS unsigned*)(lds + (bufoff) + ldsw + _i * 8192), 16, 0, 0); } while (0)
; #define PG8_LDA(dst, b, h) do { _Pragma("unroll") for (int m = 0; m < 4; ++m) _Pragma("unroll") for (int k = 0; k < 2; ++k) dst[m][k] = *(const LAS bf16x8*)(lds + PG8_SA(b, h) + aoff + m * 2048 + k * 1024); } while (0)
; #define PG8_MMA(ai, bj, At, Bt) do { __builtin_amdgcn_s_setprio(1); _Pragma("unroll") for (int m = 0; m < 4; ++m) _Pragma("unroll") for (int n = 0; n < 2; ++n) _Pragma("unroll") for (int k = 0; k < 2; ++k) \
;         acc[ai][bj][m][n] = __builtin_amdgcn_mfma_f32_16x16x32_bf16(Bt[n][k], At[m][k], acc[ai][bj][m][n], 0, 0, 0); __builtin_amdgcn_s_setprio(0); } while (0)
; #define PG8_WAIT_V(n) asm volatile("s_waitcnt vmcnt(" #n ")" ::: "memory")
; #define PG8_WAIT_L(n) asm volatile("s_waitcnt lgkmcnt(" #n ")" ::: "memory")
; #define PG8_BAR __builtin_amdgcn_s_barrier()
; #define PG8_SCHED __builtin_amdgcn_sched_barrier(0)
; template <class Epi, bool ALIGN_EPI = true, bool SP2 = true>
; __device__ __forceinline__ void gemm_phase(LAS unsigned char* lds, const Gemm g, const StaticOrder& S, const Epi& E, const int wave_s) {
;     ...
;         for (int t = 0; t < nt; t += 2) {
;             const bool last = (t == nt - 2);
;             const char* a1 = cA + (size_t)(t + 1) * kstep;
;             const char* a2 = last ? nA : cA + (size_t)(t + 2) * kstep; const char* b2 = last ? nB : cB + (size_t)(t + 2) * kstep;
;     ...
;             PG8_LDA(At, 1, 1); PG8_STAGE(PG8_SB(1, 0), b3, voffB); PG8_STAGE(PG8_SB(1, 1), b3 + hstep, voffB); PG8_STAGE(PG8_SA(1, 0), a3, voffA);
;             PG8_WAIT_V(8); PG8_WAIT_L(0); PG8_BAR; PG8_MMA(1, 0, At, B0); PG8_MMA(1, 1, At, B1); PG8_BAR; PG8_SCHED;
	s_add_i32 s30, s53, s61
	v_lshl_add_u64 v[214:215], v[214:215], 0, s[10:11]
	s_mov_b32 m0, s30
	ds_read_b128 v[182:185], v153 offset:49152
	ds_read_b128 v[186:189], v153 offset:50176
	ds_read_b128 v[190:193], v153 offset:51200
	ds_read_b128 v[194:197], v153 offset:52224
	ds_read_b128 v[198:201], v153 offset:53248
	ds_read_b128 v[202:205], v153 offset:54272
	ds_read_b128 v[206:209], v153 offset:55296
	ds_read_b128 v[210:213], v153 offset:56320
	global_load_lds_dwordx4 v[214:215], off
	s_add_i32 m0, s30, 0x2000
	s_add_u32 s28, s28, 0x40080
	v_lshl_add_u64 v[214:215], v[216:217], 0, s[10:11]
	s_addc_u32 s29, s29, 0
	s_add_i32 s30, s54, s61
	global_load_lds_dwordx4 v[214:215], off
	v_lshl_add_u64 v[214:215], s[28:29], 0, v[132:133]
	s_mov_b32 m0, s30
	s_nop 0
	global_load_lds_dwordx4 v[214:215], off
	v_lshl_add_u64 v[214:215], s[28:29], 0, v[128:129]
	s_add_i32 m0, s30, 0x2000
	s_nop 0
	global_load_lds_dwordx4 v[214:215], off
	v_lshl_add_u64 v[214:215], v[218:219], 0, s[10:11]
	s_mov_b32 m0, s40
	s_nop 0
	global_load_lds_dwordx4 v[214:215], off
	v_lshl_add_u64 v[214:215], v[220:221], 0, s[10:11]
	s_mov_b32 m0, s41
	s_nop 0
	global_load_lds_dwordx4 v[214:215], off
	s_waitcnt vmcnt(8)
	s_waitcnt lgkmcnt(0)
	s_barrier
	s_setprio 1
	s_waitcnt lgkmcnt(0)
	v_mfma_f32_16x16x32_bf16 v[60:63], v[144:147], v[182:185], v[60:63]
	v_mfma_f32_16x16x32_bf16 v[56:59], v[158:161], v[182:185], v[56:59]
	v_mfma_f32_16x16x32_bf16 v[52:55], v[144:147], v[190:193], v[52:55]
	v_mfma_f32_16x16x32_bf16 v[44:47], v[158:161], v[190:193], v[44:47]
	v_mfma_f32_16x16x32_bf16 v[36:39], v[144:147], v[198:201], v[36:39]
	v_mfma_f32_16x16x32_bf16 v[28:31], v[158:161], v[198:201], v[28:31]
	v_mfma_f32_16x16x32_bf16 v[20:23], v[144:147], v[206:209], v[20:23]
	v_mfma_f32_16x16x32_bf16 v[12:15], v[158:161], v[206:209], v[12:15]
	v_mfma_f32_16x16x32_bf16 v[60:63], v[154:157], v[186:189], v[60:63]
	v_mfma_f32_16x16x32_bf16 v[56:59], v[162:165], v[186:189], v[56:59]
	v_mfma_f32_16x16x32_bf16 v[52:55], v[154:157], v[194:197], v[52:55]
	v_mfma_f32_16x16x32_bf16 v[44:47], v[162:165], v[194:197], v[44:47]
	v_mfma_f32_16x16x32_bf16 v[36:39], v[154:157], v[202:205], v[36:39]
	v_mfma_f32_16x16x32_bf16 v[28:31], v[162:165], v[202:205], v[28:31]
	v_mfma_f32_16x16x32_bf16 v[20:23], v[154:157], v[210:213], v[20:23]
	v_mfma_f32_16x16x32_bf16 v[12:15], v[162:165], v[210:213], v[12:15]
	v_mfma_f32_16x16x32_bf16 v[48:51], v[166:169], v[182:185], v[48:51]
	v_mfma_f32_16x16x32_bf16 v[40:43], v[174:177], v[182:185], v[40:43]
	v_mfma_f32_16x16x32_bf16 v[32:35], v[166:169], v[190:193], v[32:35]
	v_mfma_f32_16x16x32_bf16 v[24:27], v[174:177], v[190:193], v[24:27]
	v_mfma_f32_16x16x32_bf16 v[16:19], v[166:169], v[198:201], v[16:19]
	v_mfma_f32_16x16x32_bf16 v[8:11], v[174:177], v[198:201], v[8:11]
	v_mfma_f32_16x16x32_bf16 v[4:7], v[166:169], v[206:209], v[4:7]
	v_mfma_f32_16x16x32_bf16 v[0:3], v[174:177], v[206:209], v[0:3]
	v_mfma_f32_16x16x32_bf16 v[48:51], v[170:173], v[186:189], v[48:51]
	v_mfma_f32_16x16x32_bf16 v[40:43], v[178:181], v[186:189], v[40:43]
	v_mfma_f32_16x16x32_bf16 v[32:35], v[170:173], v[194:197], v[32:35]
	v_mfma_f32_16x16x32_bf16 v[24:27], v[178:181], v[194:197], v[24:27]
	v_mfma_f32_16x16x32_bf16 v[16:19], v[170:173], v[202:205], v[16:19]
	v_mfma_f32_16x16x32_bf16 v[8:11], v[178:181], v[202:205], v[8:11]
	v_mfma_f32_16x16x32_bf16 v[4:7], v[170:173], v[210:213], v[4:7]
	v_mfma_f32_16x16x32_bf16 v[0:3], v[178:181], v[210:213], v[0:3]
	s_setprio 0
	s_barrier
	s_add_i32 s52, s52, 2
	s_add_u32 s50, s50, 0x100
	s_addc_u32 s51, s51, 0
	s_add_u32 s26, s26, 0x100
	s_addc_u32 s27, s27, 0
	s_cmp_gt_u32 s52, 13
	s_cbranch_scc0 .LBB0_829
	s_and_b64 vcc, exec, s[14:15]
	s_cbranch_vccz .LBB0_832
	s_barrier

; #define PG8_STAGE(bufoff, gbase, voff) do { _Pragma("unroll") for (int _i = 0; _i < 2; ++_i) \
;         __builtin_amdgcn_global_load_lds((const unsigned*)((const char*)(gbase) + (voff)[_i]), (LAS unsigned*)(lds + (bufoff) + ldsw + _i * 8192), 16, 0, 0); } while (0)
; #define PG8_LDA(dst, b, h) do { _Pragma("unroll") for (int m = 0; m < 4; ++m) _Pragma("unroll") for (int k = 0; k < 2; ++k) dst[m][k] = *(const LAS bf16x8*)(lds + PG8_SA(b, h) + aoff + m * 2048 + k * 1024); } while (0)
; #define PG8_LDB(dst, b, h) do { _Pragma("unroll") for (int n = 0; n < 2; ++n) _Pragma("unroll") for (int k = 0; k < 2; ++k) dst[n][k] = *(const LAS bf16x8*)(lds + PG8_SB(b, h) + boff + n * 2048 + k * 1024); } while (0)
; #define PG8_MMA(ai, bj, At, Bt) do { __builtin_amdgcn_s_setprio(1); _Pragma("unroll") for (int m = 0; m < 4; ++m) _Pragma("unroll") for (int n = 0; n < 2; ++n) _Pragma("unroll") for (int k = 0; k < 2; ++k) \
;         acc[ai][bj][m][n] = __builtin_amdgcn_mfma_f32_16x16x32_bf16(Bt[n][k], At[m][k], acc[ai][bj][m][n], 0, 0, 0); __builtin_amdgcn_s_setprio(0); } while (0)
; #define PG8_WAIT_V(n) asm volatile("s_waitcnt vmcnt(" #n ")" ::: "memory")
; #define PG8_WAIT_L(n) asm volatile("s_waitcnt lgkmcnt(" #n ")" ::: "memory")
; #define PG8_BAR __builtin_amdgcn_s_barrier()
; #define PG8_SCHED __builtin_amdgcn_sched_barrier(0)
; template <class Epi, bool ALIGN_EPI = true, bool SP2 = true>
; __device__ __forceinline__ void gemm_phase(LAS unsigned char* lds, const Gemm g, const StaticOrder& S, const Epi& E, const int wave_s) {
;     ...
;             PG8_LDB(B0, 0, 0); PG8_LDB(B1, 0, 1); PG8_SCHED; PG8_LDA(At, 0, 0); PG8_STAGE(PG8_SA(1, 1), a1 + hstep, voffA);
;             PG8_WAIT_V(8); PG8_WAIT_L(0); PG8_BAR; PG8_MMA(0, 0, At, B0); PG8_MMA(0, 1, At, B1); PG8_BAR; PG8_SCHED;
;             PG8_LDA(At, 0, 1); PG8_STAGE(PG8_SB(0, 0), b2, voffB); PG8_STAGE(PG8_SB(0, 1), b2 + hstep, voffB); PG8_STAGE(PG8_SA(0, 0), a2, voffA);
;             PG8_WAIT_V(8); PG8_WAIT_L(0); PG8_BAR; PG8_MMA(1, 0, At, B0); PG8_MMA(1, 1, At, B1); PG8_BAR; PG8_SCHED;
.LBB0_1190:
	ds_read_b128 v[140:143], v185
	ds_read_b128 v[144:147], v185 offset:1024
	ds_read_b128 v[148:151], v185 offset:2048
	ds_read_b128 v[152:155], v185 offset:3072
	ds_read_b128 v[156:159], v186
	ds_read_b128 v[160:163], v186 offset:1024
	ds_read_b128 v[164:167], v186 offset:2048
	ds_read_b128 v[168:171], v186 offset:3072
	s_add_u32 s50, s48, 0xfffc0080
	s_addc_u32 s51, s49, -1
	s_cmp_eq_u32 s68, 12
	s_cselect_b32 s53, s37, s51
	s_cselect_b32 s52, s64, s50
	s_cselect_b32 s51, s35, s67
	s_cselect_b32 s50, s65, s66
	v_lshl_add_u64 v[180:181], s[48:49], 0, v[138:139]
	s_add_i32 m0, s39, 0xc000
	ds_read_b128 v[172:175], v187
	ds_read_b128 v[176:179], v187 offset:1024
	ds_read_b128 v[188:191], v187 offset:2048
	ds_read_b128 v[192:195], v187 offset:3072
	ds_read_b128 v[196:199], v187 offset:4096
	ds_read_b128 v[200:203], v187 offset:5120
	ds_read_b128 v[204:207], v187 offset:6144
	ds_read_b128 v[208:211], v187 offset:7168
	global_load_lds_dwordx4 v[180:181], off
	v_lshl_add_u64 v[180:181], s[48:49], 0, v[136:137]
	s_add_i32 m0, s39, 0xe000
	s_nop 0
	global_load_lds_dwordx4 v[180:181], off
	s_waitcnt vmcnt(8)
	s_waitcnt lgkmcnt(0)
	s_barrier
	s_setprio 1
	s_waitcnt lgkmcnt(0)
	v_mfma_f32_16x16x32_bf16 v[124:127], v[140:143], v[172:175], v[124:127]
	v_mfma_f32_16x16x32_bf16 v[120:123], v[148:151], v[172:175], v[120:123]
	v_mfma_f32_16x16x32_bf16 v[116:119], v[140:143], v[188:191], v[116:119]
	v_mfma_f32_16x16x32_bf16 v[112:115], v[148:151], v[188:191], v[112:115]
	v_mfma_f32_16x16x32_bf16 v[108:111], v[140:143], v[196:199], v[108:111]
	v_mfma_f32_16x16x32_bf16 v[104:107], v[148:151], v[196:199], v[104:107]
	v_mfma_f32_16x16x32_bf16 v[100:103], v[140:143], v[204:207], v[100:103]
	v_mfma_f32_16x16x32_bf16 v[96:99], v[148:151], v[204:207], v[96:99]
	v_mfma_f32_16x16x32_bf16 v[124:127], v[144:147], v[176:179], v[124:127]
	v_mfma_f32_16x16x32_bf16 v[120:123], v[152:155], v[176:179], v[120:123]
	v_mfma_f32_16x16x32_bf16 v[116:119], v[144:147], v[192:195], v[116:119]
	v_mfma_f32_16x16x32_bf16 v[112:115], v[152:155], v[192:195], v[112:115]
	v_mfma_f32_16x16x32_bf16 v[108:111], v[144:147], v[200:203], v[108:111]
	v_mfma_f32_16x16x32_bf16 v[104:107], v[152:155], v[200:203], v[104:107]
	v_mfma_f32_16x16x32_bf16 v[100:103], v[144:147], v[208:211], v[100:103]
	v_mfma_f32_16x16x32_bf16 v[96:99], v[152:155], v[208:211], v[96:99]
	v_mfma_f32_16x16x32_bf16 v[60:63], v[156:159], v[172:175], v[60:63]
	v_mfma_f32_16x16x32_bf16 v[56:59], v[164:167], v[172:175], v[56:59]
	v_mfma_f32_16x16x32_bf16 v[52:55], v[156:159], v[188:191], v[52:55]
	v_mfma_f32_16x16x32_bf16 v[48:51], v[164:167], v[188:191], v[48:51]
	v_mfma_f32_16x16x32_bf16 v[44:47], v[156:159], v[196:199], v[44:47]
	v_mfma_f32_16x16x32_bf16 v[40:43], v[164:167], v[196:199], v[40:43]
	v_mfma_f32_16x16x32_bf16 v[36:39], v[156:159], v[204:207], v[36:39]
	v_mfma_f32_16x16x32_bf16 v[32:35], v[164:167], v[204:207], v[32:35]
	v_mfma_f32_16x16x32_bf16 v[60:63], v[160:163], v[176:179], v[60:63]
	v_mfma_f32_16x16x32_bf16 v[56:59], v[168:171], v[176:179], v[56:59]
	v_mfma_f32_16x16x32_bf16 v[52:55], v[160:163], v[192:195], v[52:55]
	v_mfma_f32_16x16x32_bf16 v[48:51], v[168:171], v[192:195], v[48:51]
	v_mfma_f32_16x16x32_bf16 v[44:47], v[160:163], v[200:203], v[44:47]
	v_mfma_f32_16x16x32_bf16 v[40:43], v[168:171], v[200:203], v[40:43]
	v_mfma_f32_16x16x32_bf16 v[36:39], v[160:163], v[208:211], v[36:39]
	v_mfma_f32_16x16x32_bf16 v[32:35], v[168:171], v[208:211], v[32:35]
	s_setprio 0
	s_barrier
	s_add_i32 s69, s60, s61
	v_lshl_add_u64 v[180:181], s[50:51], 0, v[130:131]
	s_mov_b32 m0, s69
	ds_read_b128 v[172:175], v187 offset:16384
	ds_read_b128 v[176:179], v187 offset:17408
	ds_read_b128 v[188:191], v187 offset:18432
	ds_read_b128 v[192:195], v187 offset:19456
	ds_read_b128 v[196:199], v187 offset:20480
	ds_read_b128 v[200:203], v187 offset:21504
	ds_read_b128 v[204:207], v187 offset:22528
	ds_read_b128 v[208:211], v187 offset:23552
	global_load_lds_dwordx4 v[180:181], off
	s_add_i32 m0, s69, 0x2000
	s_add_u32 s70, s50, 0x40000
	v_lshl_add_u64 v[212:213], s[50:51], 0, v[134:135]
	s_addc_u32 s71, s51, 0
	s_add_i32 s69, s62, s61
	global_load_lds_dwordx4 v[212:213], off
	v_lshl_add_u64 v[214:215], s[70:71], 0, v[130:131]
	s_mov_b32 m0, s69
	v_lshl_add_u64 v[216:217], s[52:53], 0, v[132:133]
	global_load_lds_dwordx4 v[214:215], off
	v_lshl_add_u64 v[214:215], s[70:71], 0, v[134:135]
	s_add_i32 m0, s69, 0x2000
	s_nop 0
	global_load_lds_dwordx4 v[214:215], off
	v_lshl_add_u64 v[214:215], s[52:53], 0, v[128:129]
	s_mov_b32 m0, s39
	s_nop 0
	global_load_lds_dwordx4 v[214:215], off
	s_mov_b32 m0, s40
	s_nop 0
	global_load_lds_dwordx4 v[216:217], off
	s_waitcnt vmcnt(8)
	s_waitcnt lgkmcnt(0)
	s_barrier
; #define PG8_STAGE(bufoff, gbase, voff) do { _Pragma("unroll") for (int _i = 0; _i < 2; ++_i) \
;         __builtin_amdgcn_global_load_lds((const unsigned*)((const char*)(gbase) + (voff)[_i]), (LAS unsigned*)(lds + (bufoff) + ldsw + _i * 8192), 16, 0, 0); } while (0)
; #define PG8_LDA(dst, b, h) do { _Pragma("unroll") for (int m = 0; m < 4; ++m) _Pragma("unroll") for (int k = 0; k < 2; ++k) dst[m][k] = *(const LAS bf16x8*)(lds + PG8_SA(b, h) + aoff + m * 2048 + k * 1024); } while (0)
; #define PG8_LDB(dst, b, h) do { _Pragma("unroll") for (int n = 0; n < 2; ++n) _Pragma("unroll") for (int k = 0; k < 2; ++k) dst[n][k] = *(const LAS bf16x8*)(lds + PG8_SB(b, h) + boff + n * 2048 + k * 1024); } while (0)
; #define PG8_MMA(ai, bj, At, Bt) do { __builtin_amdgcn_s_setprio(1); _Pragma("unroll") for (int m = 0; m < 4; ++m) _Pragma("unroll") for (int n = 0; n < 2; ++n) _Pragma("unroll") for (int k = 0; k < 2; ++k) \
;         acc[ai][bj][m][n] = __builtin_amdgcn_mfma_f32_16x16x32_bf16(Bt[n][k], At[m][k], acc[ai][bj][m][n], 0, 0, 0); __builtin_amdgcn_s_setprio(0); } while (0)
; #define PG8_WAIT_V(n) asm volatile("s_waitcnt vmcnt(" #n ")" ::: "memory")
; #define PG8_WAIT_L(n) asm volatile("s_waitcnt lgkmcnt(" #n ")" ::: "memory")
; #define PG8_BAR __builtin_amdgcn_s_barrier()
; #define PG8_SCHED __builtin_amdgcn_sched_barrier(0)
; template <class Epi, bool ALIGN_EPI = true, bool SP2 = true>
; __device__ __forceinline__ void gemm_phase(LAS unsigned char* lds, const Gemm g, const StaticOrder& S, const Epi& E, const int wave_s) {
;     ...
;             PG8_WAIT_V(8); PG8_WAIT_L(0); PG8_BAR; PG8_MMA(1, 0, At, B0); PG8_MMA(1, 1, At, B1); PG8_BAR; PG8_SCHED;
;             PG8_LDB(B0, 1, 0); PG8_LDB(B1, 1, 1); PG8_SCHED; PG8_LDA(At, 1, 0); PG8_STAGE(PG8_SA(0, 1), a2 + hstep, voffA);
;             PG8_WAIT_V(8); PG8_WAIT_L(0); PG8_BAR; PG8_MMA(0, 0, At, B0); PG8_MMA(0, 1, At, B1); PG8_BAR; PG8_SCHED;
	s_setprio 1
	s_waitcnt lgkmcnt(0)
	v_mfma_f32_16x16x32_bf16 v[92:95], v[140:143], v[172:175], v[92:95]
	v_mfma_f32_16x16x32_bf16 v[88:91], v[148:151], v[172:175], v[88:91]
	v_mfma_f32_16x16x32_bf16 v[84:87], v[140:143], v[188:191], v[84:87]
	v_mfma_f32_16x16x32_bf16 v[80:83], v[148:151], v[188:191], v[80:83]
	v_mfma_f32_16x16x32_bf16 v[76:79], v[140:143], v[196:199], v[76:79]
	v_mfma_f32_16x16x32_bf16 v[72:75], v[148:151], v[196:199], v[72:75]
	v_mfma_f32_16x16x32_bf16 v[68:71], v[140:143], v[204:207], v[68:71]
	v_mfma_f32_16x16x32_bf16 v[64:67], v[148:151], v[204:207], v[64:67]
	v_mfma_f32_16x16x32_bf16 v[92:95], v[144:147], v[176:179], v[92:95]
	v_mfma_f32_16x16x32_bf16 v[88:91], v[152:155], v[176:179], v[88:91]
	v_mfma_f32_16x16x32_bf16 v[84:87], v[144:147], v[192:195], v[84:87]
	v_mfma_f32_16x16x32_bf16 v[80:83], v[152:155], v[192:195], v[80:83]
	v_mfma_f32_16x16x32_bf16 v[76:79], v[144:147], v[200:203], v[76:79]
	v_mfma_f32_16x16x32_bf16 v[72:75], v[152:155], v[200:203], v[72:75]
	v_mfma_f32_16x16x32_bf16 v[68:71], v[144:147], v[208:211], v[68:71]
	v_mfma_f32_16x16x32_bf16 v[64:67], v[152:155], v[208:211], v[64:67]
	v_mfma_f32_16x16x32_bf16 v[28:31], v[156:159], v[172:175], v[28:31]
	v_mfma_f32_16x16x32_bf16 v[24:27], v[164:167], v[172:175], v[24:27]
	v_mfma_f32_16x16x32_bf16 v[20:23], v[156:159], v[188:191], v[20:23]
	v_mfma_f32_16x16x32_bf16 v[16:19], v[164:167], v[188:191], v[16:19]
	v_mfma_f32_16x16x32_bf16 v[12:15], v[156:159], v[196:199], v[12:15]
	v_mfma_f32_16x16x32_bf16 v[8:11], v[164:167], v[196:199], v[8:11]
	v_mfma_f32_16x16x32_bf16 v[4:7], v[156:159], v[204:207], v[4:7]
	v_mfma_f32_16x16x32_bf16 v[0:3], v[164:167], v[204:207], v[0:3]
	v_mfma_f32_16x16x32_bf16 v[28:31], v[160:163], v[176:179], v[28:31]
	v_mfma_f32_16x16x32_bf16 v[24:27], v[168:171], v[176:179], v[24:27]
	v_mfma_f32_16x16x32_bf16 v[20:23], v[160:163], v[192:195], v[20:23]
	v_mfma_f32_16x16x32_bf16 v[16:19], v[168:171], v[192:195], v[16:19]
	v_mfma_f32_16x16x32_bf16 v[12:15], v[160:163], v[200:203], v[12:15]
	v_mfma_f32_16x16x32_bf16 v[8:11], v[168:171], v[200:203], v[8:11]
	v_mfma_f32_16x16x32_bf16 v[4:7], v[160:163], v[208:211], v[4:7]
	v_mfma_f32_16x16x32_bf16 v[0:3], v[168:171], v[208:211], v[0:3]
	s_setprio 0
	s_barrier
	s_add_i32 s69, 0, 0x18000
	s_add_i32 s70, 0, 0x1c000
	v_add_u32_e32 v152, s69, v183
	v_add_u32_e32 v168, s70, v183
	ds_read_b128 v[140:143], v152
	ds_read_b128 v[144:147], v152 offset:1024
	ds_read_b128 v[148:151], v152 offset:2048
	ds_read_b128 v[152:155], v152 offset:3072
	ds_read_b128 v[156:159], v168
	ds_read_b128 v[160:163], v168 offset:1024
	ds_read_b128 v[164:167], v168 offset:2048
	ds_read_b128 v[168:171], v168 offset:3072
	s_add_u32 s52, s52, 0x40000
	s_addc_u32 s53, s53, 0
	s_mov_b32 m0, s41
	v_lshl_add_u64 v[218:219], s[52:53], 0, v[128:129]
	ds_read_b128 v[172:175], v187 offset:32768
	ds_read_b128 v[176:179], v187 offset:33792
	ds_read_b128 v[188:191], v187 offset:34816
	ds_read_b128 v[192:195], v187 offset:35840
	ds_read_b128 v[196:199], v187 offset:36864
	ds_read_b128 v[200:203], v187 offset:37888
	ds_read_b128 v[204:207], v187 offset:38912
	ds_read_b128 v[208:211], v187 offset:39936
	global_load_lds_dwordx4 v[218:219], off
	v_lshl_add_u64 v[218:219], s[52:53], 0, v[132:133]
	s_mov_b32 m0, s47
	s_nop 0
	global_load_lds_dwordx4 v[218:219], off
	s_waitcnt vmcnt(8)
	s_waitcnt lgkmcnt(0)
	s_barrier
	s_setprio 1
	s_waitcnt lgkmcnt(0)
	v_mfma_f32_16x16x32_bf16 v[124:127], v[140:143], v[172:175], v[124:127]
	v_mfma_f32_16x16x32_bf16 v[120:123], v[148:151], v[172:175], v[120:123]
	v_mfma_f32_16x16x32_bf16 v[116:119], v[140:143], v[188:191], v[116:119]
	v_mfma_f32_16x16x32_bf16 v[112:115], v[148:151], v[188:191], v[112:115]
	v_mfma_f32_16x16x32_bf16 v[108:111], v[140:143], v[196:199], v[108:111]
	v_mfma_f32_16x16x32_bf16 v[104:107], v[148:151], v[196:199], v[104:107]
	v_mfma_f32_16x16x32_bf16 v[100:103], v[140:143], v[204:207], v[100:103]
	v_mfma_f32_16x16x32_bf16 v[96:99], v[148:151], v[204:207], v[96:99]
	v_mfma_f32_16x16x32_bf16 v[124:127], v[144:147], v[176:179], v[124:127]
	v_mfma_f32_16x16x32_bf16 v[120:123], v[152:155], v[176:179], v[120:123]
	v_mfma_f32_16x16x32_bf16 v[116:119], v[144:147], v[192:195], v[116:119]
	v_mfma_f32_16x16x32_bf16 v[112:115], v[152:155], v[192:195], v[112:115]
	v_mfma_f32_16x16x32_bf16 v[108:111], v[144:147], v[200:203], v[108:111]
	v_mfma_f32_16x16x32_bf16 v[104:107], v[152:155], v[200:203], v[104:107]
	v_mfma_f32_16x16x32_bf16 v[100:103], v[144:147], v[208:211], v[100:103]
	v_mfma_f32_16x16x32_bf16 v[96:99], v[152:155], v[208:211], v[96:99]
	v_mfma_f32_16x16x32_bf16 v[60:63], v[156:159], v[172:175], v[60:63]
	v_mfma_f32_16x16x32_bf16 v[56:59], v[164:167], v[172:175], v[56:59]
	v_mfma_f32_16x16x32_bf16 v[52:55], v[156:159], v[188:191], v[52:55]
	v_mfma_f32_16x16x32_bf16 v[48:51], v[164:167], v[188:191], v[48:51]
	v_mfma_f32_16x16x32_bf16 v[44:47], v[156:159], v[196:199], v[44:47]
	v_mfma_f32_16x16x32_bf16 v[40:43], v[164:167], v[196:199], v[40:43]
	v_mfma_f32_16x16x32_bf16 v[36:39], v[156:159], v[204:207], v[36:39]
	v_mfma_f32_16x16x32_bf16 v[32:35], v[164:167], v[204:207], v[32:35]
	v_mfma_f32_16x16x32_bf16 v[60:63], v[160:163], v[176:179], v[60:63]
	v_mfma_f32_16x16x32_bf16 v[56:59], v[168:171], v[176:179], v[56:59]
	v_mfma_f32_16x16x32_bf16 v[52:55], v[160:163], v[192:195], v[52:55]
	v_mfma_f32_16x16x32_bf16 v[48:51], v[168:171], v[192:195], v[48:51]
	v_mfma_f32_16x16x32_bf16 v[44:47], v[160:163], v[200:203], v[44:47]
	v_mfma_f32_16x16x32_bf16 v[40:43], v[168:171], v[200:203], v[40:43]
	v_mfma_f32_16x16x32_bf16 v[36:39], v[160:163], v[208:211], v[36:39]
	v_mfma_f32_16x16x32_bf16 v[32:35], v[168:171], v[208:211], v[32:35]
	s_setprio 0
	s_barrier
; #define PG8_STAGE(bufoff, gbase, voff) do { _Pragma("unroll") for (int _i = 0; _i < 2; ++_i) \
;         __builtin_amdgcn_global_load_lds((const unsigned*)((const char*)(gbase) + (voff)[_i]), (LAS unsigned*)(lds + (bufoff) + ldsw + _i * 8192), 16, 0, 0); } while (0)
; #define PG8_LDA(dst, b, h) do { _Pragma("unroll") for (int m = 0; m < 4; ++m) _Pragma("unroll") for (int k = 0; k < 2; ++k) dst[m][k] = *(const LAS bf16x8*)(lds + PG8_SA(b, h) + aoff + m * 2048 + k * 1024); } while (0)
; #define PG8_MMA(ai, bj, At, Bt) do { __builtin_amdgcn_s_setprio(1); _Pragma("unroll") for (int m = 0; m < 4; ++m) _Pragma("unroll") for (int n = 0; n < 2; ++n) _Pragma("unroll") for (int k = 0; k < 2; ++k) \
;         acc[ai][bj][m][n] = __builtin_amdgcn_mfma_f32_16x16x32_bf16(Bt[n][k], At[m][k], acc[ai][bj][m][n], 0, 0, 0); __builtin_amdgcn_s_setprio(0); } while (0)
; #define PG8_WAIT_V(n) asm volatile("s_waitcnt vmcnt(" #n ")" ::: "memory")
; #define PG8_WAIT_L(n) asm volatile("s_waitcnt lgkmcnt(" #n ")" ::: "memory")
; #define PG8_BAR __builtin_amdgcn_s_barrier()
; #define PG8_SCHED __builtin_amdgcn_sched_barrier(0)
; template <class Epi, bool ALIGN_EPI = true, bool SP2 = true>
; __device__ __forceinline__ void gemm_phase(LAS unsigned char* lds, const Gemm g, const StaticOrder& S, const Epi& E, const int wave_s) {
;     ...
;             PG8_LDA(At, 1, 1); PG8_STAGE(PG8_SB(1, 0), b3, voffB); PG8_STAGE(PG8_SB(1, 1), b3 + hstep, voffB); PG8_STAGE(PG8_SA(1, 0), a3, voffA);
;             PG8_WAIT_V(8); PG8_WAIT_L(0); PG8_BAR; PG8_MMA(1, 0, At, B0); PG8_MMA(1, 1, At, B1); PG8_BAR; PG8_SCHED;
;     ...
;         if constexpr (ALIGN_EPI) { if (wr == 0) PG8_BAR; }
	s_add_i32 s52, s69, s61
	v_lshl_add_u64 v[180:181], v[180:181], 0, s[18:19]
	s_mov_b32 m0, s52
	ds_read_b128 v[172:175], v187 offset:49152
	ds_read_b128 v[176:179], v187 offset:50176
	ds_read_b128 v[188:191], v187 offset:51200
	ds_read_b128 v[192:195], v187 offset:52224
	ds_read_b128 v[196:199], v187 offset:53248
	ds_read_b128 v[200:203], v187 offset:54272
	ds_read_b128 v[204:207], v187 offset:55296
	ds_read_b128 v[208:211], v187 offset:56320
	global_load_lds_dwordx4 v[180:181], off
	s_add_i32 m0, s52, 0x2000
	s_add_u32 s50, s50, 0x40080
	v_lshl_add_u64 v[180:181], v[212:213], 0, s[18:19]
	s_addc_u32 s51, s51, 0
	s_add_i32 s52, s70, s61
	global_load_lds_dwordx4 v[180:181], off
	v_lshl_add_u64 v[180:181], s[50:51], 0, v[130:131]
	s_mov_b32 m0, s52
	s_nop 0
	global_load_lds_dwordx4 v[180:181], off
	v_lshl_add_u64 v[180:181], s[50:51], 0, v[134:135]
	s_add_i32 m0, s52, 0x2000
	s_nop 0
	global_load_lds_dwordx4 v[180:181], off
	v_lshl_add_u64 v[180:181], v[214:215], 0, s[18:19]
	s_mov_b32 m0, s57
	s_nop 0
	global_load_lds_dwordx4 v[180:181], off
	v_lshl_add_u64 v[180:181], v[216:217], 0, s[18:19]
	s_mov_b32 m0, s58
	s_nop 0
	global_load_lds_dwordx4 v[180:181], off
	s_waitcnt vmcnt(8)
	s_waitcnt lgkmcnt(0)
	s_barrier
	s_setprio 1
	s_waitcnt lgkmcnt(0)
	v_mfma_f32_16x16x32_bf16 v[92:95], v[140:143], v[172:175], v[92:95]
	v_mfma_f32_16x16x32_bf16 v[88:91], v[148:151], v[172:175], v[88:91]
	v_mfma_f32_16x16x32_bf16 v[84:87], v[140:143], v[188:191], v[84:87]
	v_mfma_f32_16x16x32_bf16 v[80:83], v[148:151], v[188:191], v[80:83]
	v_mfma_f32_16x16x32_bf16 v[76:79], v[140:143], v[196:199], v[76:79]
	v_mfma_f32_16x16x32_bf16 v[72:75], v[148:151], v[196:199], v[72:75]
	v_mfma_f32_16x16x32_bf16 v[68:71], v[140:143], v[204:207], v[68:71]
	v_mfma_f32_16x16x32_bf16 v[64:67], v[148:151], v[204:207], v[64:67]
	v_mfma_f32_16x16x32_bf16 v[92:95], v[144:147], v[176:179], v[92:95]
	v_mfma_f32_16x16x32_bf16 v[88:91], v[152:155], v[176:179], v[88:91]
	v_mfma_f32_16x16x32_bf16 v[84:87], v[144:147], v[192:195], v[84:87]
	v_mfma_f32_16x16x32_bf16 v[80:83], v[152:155], v[192:195], v[80:83]
	v_mfma_f32_16x16x32_bf16 v[76:79], v[144:147], v[200:203], v[76:79]
	v_mfma_f32_16x16x32_bf16 v[72:75], v[152:155], v[200:203], v[72:75]
	v_mfma_f32_16x16x32_bf16 v[68:71], v[144:147], v[208:211], v[68:71]
	v_mfma_f32_16x16x32_bf16 v[64:67], v[152:155], v[208:211], v[64:67]
	v_mfma_f32_16x16x32_bf16 v[28:31], v[156:159], v[172:175], v[28:31]
	v_mfma_f32_16x16x32_bf16 v[24:27], v[164:167], v[172:175], v[24:27]
	v_mfma_f32_16x16x32_bf16 v[20:23], v[156:159], v[188:191], v[20:23]
	v_mfma_f32_16x16x32_bf16 v[16:19], v[164:167], v[188:191], v[16:19]
	v_mfma_f32_16x16x32_bf16 v[12:15], v[156:159], v[196:199], v[12:15]
	v_mfma_f32_16x16x32_bf16 v[8:11], v[164:167], v[196:199], v[8:11]
	v_mfma_f32_16x16x32_bf16 v[4:7], v[156:159], v[204:207], v[4:7]
	v_mfma_f32_16x16x32_bf16 v[0:3], v[164:167], v[204:207], v[0:3]
	v_mfma_f32_16x16x32_bf16 v[28:31], v[160:163], v[176:179], v[28:31]
	v_mfma_f32_16x16x32_bf16 v[24:27], v[168:171], v[176:179], v[24:27]
	v_mfma_f32_16x16x32_bf16 v[20:23], v[160:163], v[192:195], v[20:23]
	v_mfma_f32_16x16x32_bf16 v[16:19], v[168:171], v[192:195], v[16:19]
	v_mfma_f32_16x16x32_bf16 v[12:15], v[160:163], v[200:203], v[12:15]
	v_mfma_f32_16x16x32_bf16 v[8:11], v[168:171], v[200:203], v[8:11]
	v_mfma_f32_16x16x32_bf16 v[4:7], v[160:163], v[208:211], v[4:7]
	v_mfma_f32_16x16x32_bf16 v[0:3], v[168:171], v[208:211], v[0:3]
	s_setprio 0
	s_barrier
	s_add_i32 s68, s68, 2
	s_add_u32 s66, s66, 0x100
	s_addc_u32 s67, s67, 0
	s_add_u32 s48, s48, 0x100
	s_addc_u32 s49, s49, 0
	s_cmp_gt_u32 s68, 13
	s_cbranch_scc0 .LBB0_1190
	s_and_b64 vcc, exec, s[20:21]
	s_cbranch_vccz .LBB0_1193
	s_barrier

; #define PG8_STAGE(bufoff, gbase, voff) do { _Pragma("unroll") for (int _i = 0; _i < 2; ++_i) \
;         __builtin_amdgcn_global_load_lds((const unsigned*)((const char*)(gbase) + (voff)[_i]), (LAS unsigned*)(lds + (bufoff) + ldsw + _i * 8192), 16, 0, 0); } while (0)
; #define PG8_LDA(dst, b, h) do { _Pragma("unroll") for (int m = 0; m < 4; ++m) _Pragma("unroll") for (int k = 0; k < 2; ++k) dst[m][k] = *(const LAS bf16x8*)(lds + PG8_SA(b, h) + aoff + m * 2048 + k * 1024); } while (0)
; #define PG8_LDB(dst, b, h) do { _Pragma("unroll") for (int n = 0; n < 2; ++n) _Pragma("unroll") for (int k = 0; k < 2; ++k) dst[n][k] = *(const LAS bf16x8*)(lds + PG8_SB(b, h) + boff + n * 2048 + k * 1024); } while (0)
; #define PG8_MMA(ai, bj, At, Bt) do { __builtin_amdgcn_s_setprio(1); _Pragma("unroll") for (int m = 0; m < 4; ++m) _Pragma("unroll") for (int n = 0; n < 2; ++n) _Pragma("unroll") for (int k = 0; k < 2; ++k) \
;         acc[ai][bj][m][n] = __builtin_amdgcn_mfma_f32_16x16x32_bf16(Bt[n][k], At[m][k], acc[ai][bj][m][n], 0, 0, 0); __builtin_amdgcn_s_setprio(0); } while (0)
; #define PG8_WAIT_V(n) asm volatile("s_waitcnt vmcnt(" #n ")" ::: "memory")
; #define PG8_WAIT_L(n) asm volatile("s_waitcnt lgkmcnt(" #n ")" ::: "memory")
; #define PG8_BAR __builtin_amdgcn_s_barrier()
; #define PG8_SCHED __builtin_amdgcn_sched_barrier(0)
; template <class Epi, bool ALIGN_EPI = true, bool SP2 = true>
; __device__ __forceinline__ void gemm_phase(LAS unsigned char* lds, const Gemm g, const StaticOrder& S, const Epi& E, const int wave_s) {
;     ...
;             PG8_LDB(B0, 0, 0); PG8_LDB(B1, 0, 1); PG8_SCHED; PG8_LDA(At, 0, 0); PG8_STAGE(PG8_SA(1, 1), a1 + hstep, voffA);
;             PG8_WAIT_V(8); PG8_WAIT_L(0); PG8_BAR; PG8_MMA(0, 0, At, B0); PG8_MMA(0, 1, At, B1); PG8_BAR; PG8_SCHED;
;             PG8_LDA(At, 0, 1); PG8_STAGE(PG8_SB(0, 0), b2, voffB); PG8_STAGE(PG8_SB(0, 1), b2 + hstep, voffB); PG8_STAGE(PG8_SA(0, 0), a2, voffA);
;             PG8_WAIT_V(8); PG8_WAIT_L(0); PG8_BAR; PG8_MMA(1, 0, At, B0); PG8_MMA(1, 1, At, B1); PG8_BAR; PG8_SCHED;
.LBB0_1404:
	ds_read_b128 v[140:143], v185
	ds_read_b128 v[144:147], v185 offset:1024
	ds_read_b128 v[148:151], v185 offset:2048
	ds_read_b128 v[152:155], v185 offset:3072
	ds_read_b128 v[156:159], v186
	ds_read_b128 v[160:163], v186 offset:1024
	ds_read_b128 v[164:167], v186 offset:2048
	ds_read_b128 v[168:171], v186 offset:3072
	s_add_u32 s42, s40, 0x100
	s_addc_u32 s43, s41, 0
	s_cmp_eq_u32 s66, 40
	s_cselect_b32 s47, s7, s43
	s_cselect_b32 s46, s6, s42
	s_cselect_b32 s45, s37, s65
	s_cselect_b32 s44, s36, s64
	v_lshl_add_u64 v[180:181], s[40:41], 0, v[138:139]
	s_add_i32 m0, s39, 0xc000
	ds_read_b128 v[172:175], v187
	ds_read_b128 v[176:179], v187 offset:1024
	ds_read_b128 v[188:191], v187 offset:2048
	ds_read_b128 v[192:195], v187 offset:3072
	ds_read_b128 v[196:199], v187 offset:4096
	ds_read_b128 v[200:203], v187 offset:5120
	ds_read_b128 v[204:207], v187 offset:6144
	ds_read_b128 v[208:211], v187 offset:7168
	global_load_lds_dwordx4 v[180:181], off
	v_lshl_add_u64 v[180:181], s[40:41], 0, v[136:137]
	s_add_i32 m0, s39, 0xe000
	s_nop 0
	global_load_lds_dwordx4 v[180:181], off
	s_waitcnt vmcnt(8)
	s_waitcnt lgkmcnt(0)
	s_barrier
	s_setprio 1
	s_waitcnt lgkmcnt(0)
	v_mfma_f32_16x16x32_bf16 v[124:127], v[140:143], v[172:175], v[124:127]
	v_mfma_f32_16x16x32_bf16 v[120:123], v[148:151], v[172:175], v[120:123]
	v_mfma_f32_16x16x32_bf16 v[116:119], v[140:143], v[188:191], v[116:119]
	v_mfma_f32_16x16x32_bf16 v[112:115], v[148:151], v[188:191], v[112:115]
	v_mfma_f32_16x16x32_bf16 v[108:111], v[140:143], v[196:199], v[108:111]
	v_mfma_f32_16x16x32_bf16 v[104:107], v[148:151], v[196:199], v[104:107]
	v_mfma_f32_16x16x32_bf16 v[100:103], v[140:143], v[204:207], v[100:103]
	v_mfma_f32_16x16x32_bf16 v[96:99], v[148:151], v[204:207], v[96:99]
	v_mfma_f32_16x16x32_bf16 v[124:127], v[144:147], v[176:179], v[124:127]
	v_mfma_f32_16x16x32_bf16 v[120:123], v[152:155], v[176:179], v[120:123]
	v_mfma_f32_16x16x32_bf16 v[116:119], v[144:147], v[192:195], v[116:119]
	v_mfma_f32_16x16x32_bf16 v[112:115], v[152:155], v[192:195], v[112:115]
	v_mfma_f32_16x16x32_bf16 v[108:111], v[144:147], v[200:203], v[108:111]
	v_mfma_f32_16x16x32_bf16 v[104:107], v[152:155], v[200:203], v[104:107]
	v_mfma_f32_16x16x32_bf16 v[100:103], v[144:147], v[208:211], v[100:103]
	v_mfma_f32_16x16x32_bf16 v[96:99], v[152:155], v[208:211], v[96:99]
	v_mfma_f32_16x16x32_bf16 v[60:63], v[156:159], v[172:175], v[60:63]
	v_mfma_f32_16x16x32_bf16 v[56:59], v[164:167], v[172:175], v[56:59]
	v_mfma_f32_16x16x32_bf16 v[52:55], v[156:159], v[188:191], v[52:55]
	v_mfma_f32_16x16x32_bf16 v[48:51], v[164:167], v[188:191], v[48:51]
	v_mfma_f32_16x16x32_bf16 v[44:47], v[156:159], v[196:199], v[44:47]
	v_mfma_f32_16x16x32_bf16 v[40:43], v[164:167], v[196:199], v[40:43]
	v_mfma_f32_16x16x32_bf16 v[36:39], v[156:159], v[204:207], v[36:39]
	v_mfma_f32_16x16x32_bf16 v[32:35], v[164:167], v[204:207], v[32:35]
	v_mfma_f32_16x16x32_bf16 v[60:63], v[160:163], v[176:179], v[60:63]
	v_mfma_f32_16x16x32_bf16 v[56:59], v[168:171], v[176:179], v[56:59]
	v_mfma_f32_16x16x32_bf16 v[52:55], v[160:163], v[192:195], v[52:55]
	v_mfma_f32_16x16x32_bf16 v[48:51], v[168:171], v[192:195], v[48:51]
	v_mfma_f32_16x16x32_bf16 v[44:47], v[160:163], v[200:203], v[44:47]
	v_mfma_f32_16x16x32_bf16 v[40:43], v[168:171], v[200:203], v[40:43]
	v_mfma_f32_16x16x32_bf16 v[36:39], v[160:163], v[208:211], v[36:39]
	v_mfma_f32_16x16x32_bf16 v[32:35], v[168:171], v[208:211], v[32:35]
	s_setprio 0
	s_barrier
	s_add_i32 s40, s57, s61
	v_lshl_add_u64 v[180:181], s[44:45], 0, v[130:131]
	s_mov_b32 m0, s40
	ds_read_b128 v[172:175], v187 offset:16384
	ds_read_b128 v[176:179], v187 offset:17408
	ds_read_b128 v[188:191], v187 offset:18432
	ds_read_b128 v[192:195], v187 offset:19456
	ds_read_b128 v[196:199], v187 offset:20480
	ds_read_b128 v[200:203], v187 offset:21504
	ds_read_b128 v[204:207], v187 offset:22528
	ds_read_b128 v[208:211], v187 offset:23552
	global_load_lds_dwordx4 v[180:181], off
	s_add_i32 m0, s40, 0x2000
	s_add_u32 s40, s44, 0xb0000
	v_lshl_add_u64 v[212:213], s[44:45], 0, v[134:135]
	s_addc_u32 s41, s45, 0
	s_add_i32 s67, s58, s61
	global_load_lds_dwordx4 v[212:213], off
	v_lshl_add_u64 v[214:215], s[40:41], 0, v[130:131]
	s_mov_b32 m0, s67
	v_lshl_add_u64 v[216:217], s[46:47], 0, v[132:133]
	global_load_lds_dwordx4 v[214:215], off
	v_lshl_add_u64 v[214:215], s[40:41], 0, v[134:135]
	s_add_i32 m0, s67, 0x2000
	s_nop 0
	global_load_lds_dwordx4 v[214:215], off
	v_lshl_add_u64 v[214:215], s[46:47], 0, v[128:129]
	s_mov_b32 m0, s39
	s_nop 0
	global_load_lds_dwordx4 v[214:215], off
	s_mov_b32 m0, s48
	s_nop 0
	global_load_lds_dwordx4 v[216:217], off
	s_waitcnt vmcnt(8)
	s_waitcnt lgkmcnt(0)
	s_barrier
; #define PG8_STAGE(bufoff, gbase, voff) do { _Pragma("unroll") for (int _i = 0; _i < 2; ++_i) \
;         __builtin_amdgcn_global_load_lds((const unsigned*)((const char*)(gbase) + (voff)[_i]), (LAS unsigned*)(lds + (bufoff) + ldsw + _i * 8192), 16, 0, 0); } while (0)
; #define PG8_LDA(dst, b, h) do { _Pragma("unroll") for (int m = 0; m < 4; ++m) _Pragma("unroll") for (int k = 0; k < 2; ++k) dst[m][k] = *(const LAS bf16x8*)(lds + PG8_SA(b, h) + aoff + m * 2048 + k * 1024); } while (0)
; #define PG8_LDB(dst, b, h) do { _Pragma("unroll") for (int n = 0; n < 2; ++n) _Pragma("unroll") for (int k = 0; k < 2; ++k) dst[n][k] = *(const LAS bf16x8*)(lds + PG8_SB(b, h) + boff + n * 2048 + k * 1024); } while (0)
; #define PG8_MMA(ai, bj, At, Bt) do { __builtin_amdgcn_s_setprio(1); _Pragma("unroll") for (int m = 0; m < 4; ++m) _Pragma("unroll") for (int n = 0; n < 2; ++n) _Pragma("unroll") for (int k = 0; k < 2; ++k) \
;         acc[ai][bj][m][n] = __builtin_amdgcn_mfma_f32_16x16x32_bf16(Bt[n][k], At[m][k], acc[ai][bj][m][n], 0, 0, 0); __builtin_amdgcn_s_setprio(0); } while (0)
; #define PG8_WAIT_V(n) asm volatile("s_waitcnt vmcnt(" #n ")" ::: "memory")
; #define PG8_WAIT_L(n) asm volatile("s_waitcnt lgkmcnt(" #n ")" ::: "memory")
; #define PG8_BAR __builtin_amdgcn_s_barrier()
; #define PG8_SCHED __builtin_amdgcn_sched_barrier(0)
; template <class Epi, bool ALIGN_EPI = true, bool SP2 = true>
; __device__ __forceinline__ void gemm_phase(LAS unsigned char* lds, const Gemm g, const StaticOrder& S, const Epi& E, const int wave_s) {
;     ...
;             PG8_WAIT_V(8); PG8_WAIT_L(0); PG8_BAR; PG8_MMA(1, 0, At, B0); PG8_MMA(1, 1, At, B1); PG8_BAR; PG8_SCHED;
;             PG8_LDB(B0, 1, 0); PG8_LDB(B1, 1, 1); PG8_SCHED; PG8_LDA(At, 1, 0); PG8_STAGE(PG8_SA(0, 1), a2 + hstep, voffA);
;             PG8_WAIT_V(8); PG8_WAIT_L(0); PG8_BAR; PG8_MMA(0, 0, At, B0); PG8_MMA(0, 1, At, B1); PG8_BAR; PG8_SCHED;
	s_setprio 1
	s_waitcnt lgkmcnt(0)
	v_mfma_f32_16x16x32_bf16 v[92:95], v[140:143], v[172:175], v[92:95]
	v_mfma_f32_16x16x32_bf16 v[88:91], v[148:151], v[172:175], v[88:91]
	v_mfma_f32_16x16x32_bf16 v[84:87], v[140:143], v[188:191], v[84:87]
	v_mfma_f32_16x16x32_bf16 v[80:83], v[148:151], v[188:191], v[80:83]
	v_mfma_f32_16x16x32_bf16 v[76:79], v[140:143], v[196:199], v[76:79]
	v_mfma_f32_16x16x32_bf16 v[72:75], v[148:151], v[196:199], v[72:75]
	v_mfma_f32_16x16x32_bf16 v[68:71], v[140:143], v[204:207], v[68:71]
	v_mfma_f32_16x16x32_bf16 v[64:67], v[148:151], v[204:207], v[64:67]
	v_mfma_f32_16x16x32_bf16 v[92:95], v[144:147], v[176:179], v[92:95]
	v_mfma_f32_16x16x32_bf16 v[88:91], v[152:155], v[176:179], v[88:91]
	v_mfma_f32_16x16x32_bf16 v[84:87], v[144:147], v[192:195], v[84:87]
	v_mfma_f32_16x16x32_bf16 v[80:83], v[152:155], v[192:195], v[80:83]
	v_mfma_f32_16x16x32_bf16 v[76:79], v[144:147], v[200:203], v[76:79]
	v_mfma_f32_16x16x32_bf16 v[72:75], v[152:155], v[200:203], v[72:75]
	v_mfma_f32_16x16x32_bf16 v[68:71], v[144:147], v[208:211], v[68:71]
	v_mfma_f32_16x16x32_bf16 v[64:67], v[152:155], v[208:211], v[64:67]
	v_mfma_f32_16x16x32_bf16 v[28:31], v[156:159], v[172:175], v[28:31]
	v_mfma_f32_16x16x32_bf16 v[24:27], v[164:167], v[172:175], v[24:27]
	v_mfma_f32_16x16x32_bf16 v[20:23], v[156:159], v[188:191], v[20:23]
	v_mfma_f32_16x16x32_bf16 v[16:19], v[164:167], v[188:191], v[16:19]
	v_mfma_f32_16x16x32_bf16 v[12:15], v[156:159], v[196:199], v[12:15]
	v_mfma_f32_16x16x32_bf16 v[8:11], v[164:167], v[196:199], v[8:11]
	v_mfma_f32_16x16x32_bf16 v[4:7], v[156:159], v[204:207], v[4:7]
	v_mfma_f32_16x16x32_bf16 v[0:3], v[164:167], v[204:207], v[0:3]
	v_mfma_f32_16x16x32_bf16 v[28:31], v[160:163], v[176:179], v[28:31]
	v_mfma_f32_16x16x32_bf16 v[24:27], v[168:171], v[176:179], v[24:27]
	v_mfma_f32_16x16x32_bf16 v[20:23], v[160:163], v[192:195], v[20:23]
	v_mfma_f32_16x16x32_bf16 v[16:19], v[168:171], v[192:195], v[16:19]
	v_mfma_f32_16x16x32_bf16 v[12:15], v[160:163], v[200:203], v[12:15]
	v_mfma_f32_16x16x32_bf16 v[8:11], v[168:171], v[200:203], v[8:11]
	v_mfma_f32_16x16x32_bf16 v[4:7], v[160:163], v[208:211], v[4:7]
	v_mfma_f32_16x16x32_bf16 v[0:3], v[168:171], v[208:211], v[0:3]
	s_setprio 0
	s_barrier
	s_add_i32 s67, 0, 0x18000
	s_add_i32 s68, 0, 0x1c000
	v_add_u32_e32 v152, s67, v183
	v_add_u32_e32 v168, s68, v183
	ds_read_b128 v[140:143], v152
	ds_read_b128 v[144:147], v152 offset:1024
	ds_read_b128 v[148:151], v152 offset:2048
	ds_read_b128 v[152:155], v152 offset:3072
	ds_read_b128 v[156:159], v168
	ds_read_b128 v[160:163], v168 offset:1024
	ds_read_b128 v[164:167], v168 offset:2048
	ds_read_b128 v[168:171], v168 offset:3072
	s_add_u32 s40, s46, 0xb0000
	s_addc_u32 s41, s47, 0
	s_mov_b32 m0, s49
	v_lshl_add_u64 v[218:219], s[40:41], 0, v[128:129]
	ds_read_b128 v[172:175], v187 offset:32768
	ds_read_b128 v[176:179], v187 offset:33792
	ds_read_b128 v[188:191], v187 offset:34816
	ds_read_b128 v[192:195], v187 offset:35840
	ds_read_b128 v[196:199], v187 offset:36864
	ds_read_b128 v[200:203], v187 offset:37888
	ds_read_b128 v[204:207], v187 offset:38912
	ds_read_b128 v[208:211], v187 offset:39936
	global_load_lds_dwordx4 v[218:219], off
	v_lshl_add_u64 v[218:219], s[40:41], 0, v[132:133]
	s_mov_b32 m0, s50
	s_nop 0
	global_load_lds_dwordx4 v[218:219], off
	s_waitcnt vmcnt(8)
	s_waitcnt lgkmcnt(0)
	s_barrier
	s_setprio 1
	s_waitcnt lgkmcnt(0)
	v_mfma_f32_16x16x32_bf16 v[124:127], v[140:143], v[172:175], v[124:127]
	v_mfma_f32_16x16x32_bf16 v[120:123], v[148:151], v[172:175], v[120:123]
	v_mfma_f32_16x16x32_bf16 v[116:119], v[140:143], v[188:191], v[116:119]
	v_mfma_f32_16x16x32_bf16 v[112:115], v[148:151], v[188:191], v[112:115]
	v_mfma_f32_16x16x32_bf16 v[108:111], v[140:143], v[196:199], v[108:111]
	v_mfma_f32_16x16x32_bf16 v[104:107], v[148:151], v[196:199], v[104:107]
	v_mfma_f32_16x16x32_bf16 v[100:103], v[140:143], v[204:207], v[100:103]
	v_mfma_f32_16x16x32_bf16 v[96:99], v[148:151], v[204:207], v[96:99]
	v_mfma_f32_16x16x32_bf16 v[124:127], v[144:147], v[176:179], v[124:127]
	v_mfma_f32_16x16x32_bf16 v[120:123], v[152:155], v[176:179], v[120:123]
	v_mfma_f32_16x16x32_bf16 v[116:119], v[144:147], v[192:195], v[116:119]
	v_mfma_f32_16x16x32_bf16 v[112:115], v[152:155], v[192:195], v[112:115]
	v_mfma_f32_16x16x32_bf16 v[108:111], v[144:147], v[200:203], v[108:111]
	v_mfma_f32_16x16x32_bf16 v[104:107], v[152:155], v[200:203], v[104:107]
	v_mfma_f32_16x16x32_bf16 v[100:103], v[144:147], v[208:211], v[100:103]
	v_mfma_f32_16x16x32_bf16 v[96:99], v[152:155], v[208:211], v[96:99]
	v_mfma_f32_16x16x32_bf16 v[60:63], v[156:159], v[172:175], v[60:63]
	v_mfma_f32_16x16x32_bf16 v[56:59], v[164:167], v[172:175], v[56:59]
	v_mfma_f32_16x16x32_bf16 v[52:55], v[156:159], v[188:191], v[52:55]
	v_mfma_f32_16x16x32_bf16 v[48:51], v[164:167], v[188:191], v[48:51]
	v_mfma_f32_16x16x32_bf16 v[44:47], v[156:159], v[196:199], v[44:47]
	v_mfma_f32_16x16x32_bf16 v[40:43], v[164:167], v[196:199], v[40:43]
	v_mfma_f32_16x16x32_bf16 v[36:39], v[156:159], v[204:207], v[36:39]
	v_mfma_f32_16x16x32_bf16 v[32:35], v[164:167], v[204:207], v[32:35]
	v_mfma_f32_16x16x32_bf16 v[60:63], v[160:163], v[176:179], v[60:63]
	v_mfma_f32_16x16x32_bf16 v[56:59], v[168:171], v[176:179], v[56:59]
	v_mfma_f32_16x16x32_bf16 v[52:55], v[160:163], v[192:195], v[52:55]
	v_mfma_f32_16x16x32_bf16 v[48:51], v[168:171], v[192:195], v[48:51]
	v_mfma_f32_16x16x32_bf16 v[44:47], v[160:163], v[200:203], v[44:47]
	v_mfma_f32_16x16x32_bf16 v[40:43], v[168:171], v[200:203], v[40:43]
	v_mfma_f32_16x16x32_bf16 v[36:39], v[160:163], v[208:211], v[36:39]
	v_mfma_f32_16x16x32_bf16 v[32:35], v[168:171], v[208:211], v[32:35]
	s_setprio 0
	s_barrier
; #define PG8_STAGE(bufoff, gbase, voff) do { _Pragma("unroll") for (int _i = 0; _i < 2; ++_i) \
;         __builtin_amdgcn_global_load_lds((const unsigned*)((const char*)(gbase) + (voff)[_i]), (LAS unsigned*)(lds + (bufoff) + ldsw + _i * 8192), 16, 0, 0); } while (0)
; #define PG8_LDA(dst, b, h) do { _Pragma("unroll") for (int m = 0; m < 4; ++m) _Pragma("unroll") for (int k = 0; k < 2; ++k) dst[m][k] = *(const LAS bf16x8*)(lds + PG8_SA(b, h) + aoff + m * 2048 + k * 1024); } while (0)
; #define PG8_MMA(ai, bj, At, Bt) do { __builtin_amdgcn_s_setprio(1); _Pragma("unroll") for (int m = 0; m < 4; ++m) _Pragma("unroll") for (int n = 0; n < 2; ++n) _Pragma("unroll") for (int k = 0; k < 2; ++k) \
;         acc[ai][bj][m][n] = __builtin_amdgcn_mfma_f32_16x16x32_bf16(Bt[n][k], At[m][k], acc[ai][bj][m][n], 0, 0, 0); __builtin_amdgcn_s_setprio(0); } while (0)
; #define PG8_WAIT_V(n) asm volatile("s_waitcnt vmcnt(" #n ")" ::: "memory")
; #define PG8_WAIT_L(n) asm volatile("s_waitcnt lgkmcnt(" #n ")" ::: "memory")
; #define PG8_BAR __builtin_amdgcn_s_barrier()
; #define PG8_SCHED __builtin_amdgcn_sched_barrier(0)
; template <class Epi, bool ALIGN_EPI = true, bool SP2 = true>
; __device__ __forceinline__ void gemm_phase(LAS unsigned char* lds, const Gemm g, const StaticOrder& S, const Epi& E, const int wave_s) {
;     ...
;             PG8_LDA(At, 1, 1); PG8_STAGE(PG8_SB(1, 0), b3, voffB); PG8_STAGE(PG8_SB(1, 1), b3 + hstep, voffB); PG8_STAGE(PG8_SA(1, 0), a3, voffA);
;             PG8_WAIT_V(8); PG8_WAIT_L(0); PG8_BAR; PG8_MMA(1, 0, At, B0); PG8_MMA(1, 1, At, B1); PG8_BAR; PG8_SCHED;
;     ...
;         if constexpr (ALIGN_EPI) { if (wr == 0) PG8_BAR; }
	s_add_i32 s40, s67, s61
	v_lshl_add_u64 v[180:181], v[180:181], 0, s[22:23]
	s_mov_b32 m0, s40
	ds_read_b128 v[172:175], v187 offset:49152
	ds_read_b128 v[176:179], v187 offset:50176
	ds_read_b128 v[188:191], v187 offset:51200
	ds_read_b128 v[192:195], v187 offset:52224
	ds_read_b128 v[196:199], v187 offset:53248
	ds_read_b128 v[200:203], v187 offset:54272
	ds_read_b128 v[204:207], v187 offset:55296
	ds_read_b128 v[208:211], v187 offset:56320
	global_load_lds_dwordx4 v[180:181], off
	s_add_i32 m0, s40, 0x2000
	s_add_u32 s40, s44, 0xb0080
	v_lshl_add_u64 v[180:181], v[212:213], 0, s[22:23]
	s_addc_u32 s41, s45, 0
	s_add_i32 s44, s68, s61
	global_load_lds_dwordx4 v[180:181], off
	v_lshl_add_u64 v[180:181], s[40:41], 0, v[130:131]
	s_mov_b32 m0, s44
	s_nop 0
	global_load_lds_dwordx4 v[180:181], off
	v_lshl_add_u64 v[180:181], s[40:41], 0, v[134:135]
	s_add_i32 m0, s44, 0x2000
	s_nop 0
	global_load_lds_dwordx4 v[180:181], off
	v_lshl_add_u64 v[180:181], v[214:215], 0, s[22:23]
	s_mov_b32 m0, s54
	s_nop 0
	global_load_lds_dwordx4 v[180:181], off
	v_lshl_add_u64 v[180:181], v[216:217], 0, s[22:23]
	s_mov_b32 m0, s55
	s_nop 0
	global_load_lds_dwordx4 v[180:181], off
	s_waitcnt vmcnt(8)
	s_waitcnt lgkmcnt(0)
	s_barrier
	s_setprio 1
	s_waitcnt lgkmcnt(0)
	v_mfma_f32_16x16x32_bf16 v[92:95], v[140:143], v[172:175], v[92:95]
	v_mfma_f32_16x16x32_bf16 v[88:91], v[148:151], v[172:175], v[88:91]
	v_mfma_f32_16x16x32_bf16 v[84:87], v[140:143], v[188:191], v[84:87]
	v_mfma_f32_16x16x32_bf16 v[80:83], v[148:151], v[188:191], v[80:83]
	v_mfma_f32_16x16x32_bf16 v[76:79], v[140:143], v[196:199], v[76:79]
	v_mfma_f32_16x16x32_bf16 v[72:75], v[148:151], v[196:199], v[72:75]
	v_mfma_f32_16x16x32_bf16 v[68:71], v[140:143], v[204:207], v[68:71]
	v_mfma_f32_16x16x32_bf16 v[64:67], v[148:151], v[204:207], v[64:67]
	v_mfma_f32_16x16x32_bf16 v[92:95], v[144:147], v[176:179], v[92:95]
	v_mfma_f32_16x16x32_bf16 v[88:91], v[152:155], v[176:179], v[88:91]
	v_mfma_f32_16x16x32_bf16 v[84:87], v[144:147], v[192:195], v[84:87]
	v_mfma_f32_16x16x32_bf16 v[80:83], v[152:155], v[192:195], v[80:83]
	v_mfma_f32_16x16x32_bf16 v[76:79], v[144:147], v[200:203], v[76:79]
	v_mfma_f32_16x16x32_bf16 v[72:75], v[152:155], v[200:203], v[72:75]
	v_mfma_f32_16x16x32_bf16 v[68:71], v[144:147], v[208:211], v[68:71]
	v_mfma_f32_16x16x32_bf16 v[64:67], v[152:155], v[208:211], v[64:67]
	v_mfma_f32_16x16x32_bf16 v[28:31], v[156:159], v[172:175], v[28:31]
	v_mfma_f32_16x16x32_bf16 v[24:27], v[164:167], v[172:175], v[24:27]
	v_mfma_f32_16x16x32_bf16 v[20:23], v[156:159], v[188:191], v[20:23]
	v_mfma_f32_16x16x32_bf16 v[16:19], v[164:167], v[188:191], v[16:19]
	v_mfma_f32_16x16x32_bf16 v[12:15], v[156:159], v[196:199], v[12:15]
	v_mfma_f32_16x16x32_bf16 v[8:11], v[164:167], v[196:199], v[8:11]
	v_mfma_f32_16x16x32_bf16 v[4:7], v[156:159], v[204:207], v[4:7]
	v_mfma_f32_16x16x32_bf16 v[0:3], v[164:167], v[204:207], v[0:3]
	v_mfma_f32_16x16x32_bf16 v[28:31], v[160:163], v[176:179], v[28:31]
	v_mfma_f32_16x16x32_bf16 v[24:27], v[168:171], v[176:179], v[24:27]
	v_mfma_f32_16x16x32_bf16 v[20:23], v[160:163], v[192:195], v[20:23]
	v_mfma_f32_16x16x32_bf16 v[16:19], v[168:171], v[192:195], v[16:19]
	v_mfma_f32_16x16x32_bf16 v[12:15], v[160:163], v[200:203], v[12:15]
	v_mfma_f32_16x16x32_bf16 v[8:11], v[168:171], v[200:203], v[8:11]
	v_mfma_f32_16x16x32_bf16 v[4:7], v[160:163], v[208:211], v[4:7]
	v_mfma_f32_16x16x32_bf16 v[0:3], v[168:171], v[208:211], v[0:3]
	s_setprio 0
	s_barrier
	s_add_i32 s66, s66, 2
	s_add_u32 s64, s64, 0x100
	s_addc_u32 s65, s65, 0
	s_cmp_gt_u32 s66, 41
	s_mov_b64 s[40:41], s[42:43]
	s_cbranch_scc0 .LBB0_1404
	s_and_b64 vcc, exec, s[24:25]
	s_cbranch_vccz .LBB0_1407
	s_barrier
